# GEMM units: first K-iteration peeled with srcC=0 for each accumulator chain start; the 128 accumulator-zeroing v_movs per unit removed (11 loop copies)
# speedup vs baseline: 1.0215x; 1.0069x over previous
;     __device__ bool next(int i, Unit& u) const { if (r0 + i >= r1) return false; return base.next(r0 + i, u); }
;     __device__ bool next(int i, Unit& u) const { const int L = i * G + c; if (L >= 256) return false; u.pm = L; u.pn = L >> 3; return true; }
; #define PG8_STAGE(bufoff, gbase, voff) do { _Pragma("unroll") for (int _i = 0; _i < 2; ++_i) \
;         __builtin_amdgcn_global_load_lds((const unsigned*)((const char*)(gbase) + (voff)[_i]), (LAS unsigned*)(lds + (bufoff) + ldsw + _i * 8192), 16, 0, 0); } while (0)
; #define PG8_LDA(dst, b, h) do { _Pragma("unroll") for (int m = 0; m < 4; ++m) _Pragma("unroll") for (int k = 0; k < 2; ++k) dst[m][k] = *(const LAS bf16x8*)(lds + PG8_SA(b, h) + aoff + m * 2048 + k * 1024); } while (0)
; #define PG8_WAIT_V(n) asm volatile("s_waitcnt vmcnt(" #n ")" ::: "memory")
; template <class Epi, class Sched>
; __device__ __forceinline__ void gemm_phase(LAS unsigned char* lds, const Gemm g, const Sched& S, const Epi& E, int wave_id) {
;     ...
;         const bool has_next = S.next(ui + 1, nxt);
;         const char* nA = has_next ? (const char*)g.A + (size_t)nxt.pm * tstepA : cA; const char* nB = has_next ? (const char*)g.Bt + (size_t)nxt.pn * tstepB : cB;
;         for (int t = 0; t < nt; t += 2) {
;             const bool last = (t == nt - 2);
;             const char* a1 = cA + (size_t)(t + 1) * kstep;
;             const char* a2 = last ? nA : cA + (size_t)(t + 2) * kstep; const char* b2 = last ? nB : cB + (size_t)(t + 2) * kstep;
;             const char* a3 = a2 + kstep; const char* b3 = b2 + kstep;
;             PG8_LDB(B0, 0, 0); PG8_LDB(B1, 0, 1); PG8_SCHED; PG8_LDA(At, 0, 0); PG8_STAGE(PG8_SA(1, 1), a1 + hstepA, voffA);
;             PG8_WAIT_V(8); PG8_WAIT_L(0); PG8_BAR; PG8_MMA(0, 0, At, B0); PG8_MMA(0, 1, At, B1); PG8_BAR; PG8_SCHED;
;             PG8_LDA(At, 0, 1); PG8_STAGE(PG8_SB(0, 0), b2, voffB); PG8_STAGE(PG8_SB(0, 1), b2 + hstepB, voffB); PG8_STAGE(PG8_SA(0, 0), a2, voffA);
;             PG8_WAIT_V(8); PG8_WAIT_L(0); PG8_BAR; PG8_MMA(1, 0, At, B0); PG8_MMA(1, 1, At, B1); PG8_BAR; PG8_SCHED;
;     ...
; #pragma unroll
;         for (int a = 0; a < 2; ++a)
; #pragma unroll
;             for (int b = 0; b < 2; ++b)
; #pragma unroll
;                 for (int m = 0; m < 4; ++m)
; #pragma unroll
;                     for (int n = 0; n < 2; ++n) acc[a][b][m][n] = (f32x4){0.f, 0.f, 0.f, 0.f};
.LBB0_251:
	s_ashr_i32 s45, s44, 31
	s_lshl_b64 s[14:15], s[44:45], 19
	s_add_u32 s46, s52, s14
	s_addc_u32 s47, s53, s15
	s_and_b64 s[14:15], s[4:5], exec
	s_cselect_b32 s2, s47, s11
	s_cselect_b32 s7, s46, s10
	s_ashr_i32 s39, s38, 31
	s_lshl_b64 s[14:15], s[38:39], 19
	s_add_u32 s48, s92, s14
	s_addc_u32 s49, s93, s15
	s_and_b64 s[14:15], s[4:5], exec
	s_cselect_b32 s9, s49, s13
	s_cselect_b32 s18, s48, s12
	s_add_u32 s10, s10, 0x40080
	s_addc_u32 s11, s11, 0
	s_add_u32 s33, s12, 0x100
	s_addc_u32 s39, s13, 0
	s_mov_b32 s45, -2
	ds_read_b128 v[16:19], v183
	ds_read_b128 v[20:23], v183 offset:1024
	ds_read_b128 v[32:35], v183 offset:2048
	ds_read_b128 v[36:39], v183 offset:3072
	ds_read_b128 v[184:187], v190
	ds_read_b128 v[194:197], v190 offset:1024
	ds_read_b128 v[198:201], v190 offset:2048
	ds_read_b128 v[202:205], v190 offset:3072
	s_add_u32 s12, s10, 0xfffc0080
	s_addc_u32 s13, s11, -1
	s_cmp_eq_u32 s45, 12
	s_cselect_b32 s15, s2, s13
	s_cselect_b32 s14, s7, s12
	s_cselect_b32 s13, s9, s39
	s_cselect_b32 s12, s18, s33
	v_lshl_add_u64 v[168:169], s[10:11], 0, v[158:159]
	s_add_i32 m0, s55, 0xc000
	ds_read_b128 v[206:209], v191
	ds_read_b128 v[210:213], v191 offset:1024
	ds_read_b128 v[214:217], v191 offset:2048
	ds_read_b128 v[218:221], v191 offset:3072
	ds_read_b128 v[222:225], v191 offset:4096
	ds_read_b128 v[226:229], v191 offset:5120
	ds_read_b128 v[230:233], v191 offset:6144
	ds_read_b128 v[234:237], v191 offset:7168
	global_load_lds_dwordx4 v[168:169], off
	v_lshl_add_u64 v[168:169], s[10:11], 0, v[160:161]
	s_add_i32 m0, s55, 0xe000
	s_nop 0
	global_load_lds_dwordx4 v[168:169], off
	s_waitcnt vmcnt(8)
	s_waitcnt lgkmcnt(0)
	s_barrier
	s_setprio 1
	s_waitcnt lgkmcnt(0)
	v_mfma_f32_16x16x32_bf16 v[140:143], v[16:19], v[206:209], 0
	v_mfma_f32_16x16x32_bf16 v[136:139], v[32:35], v[206:209], 0
	v_mfma_f32_16x16x32_bf16 v[124:127], v[16:19], v[214:217], 0
	v_mfma_f32_16x16x32_bf16 v[120:123], v[32:35], v[214:217], 0
	v_mfma_f32_16x16x32_bf16 v[108:111], v[16:19], v[222:225], 0
	v_mfma_f32_16x16x32_bf16 v[104:107], v[32:35], v[222:225], 0
	v_mfma_f32_16x16x32_bf16 v[92:95], v[16:19], v[230:233], 0
	v_mfma_f32_16x16x32_bf16 v[88:91], v[32:35], v[230:233], 0
	v_mfma_f32_16x16x32_bf16 v[140:143], v[20:23], v[210:213], v[140:143]
	v_mfma_f32_16x16x32_bf16 v[136:139], v[36:39], v[210:213], v[136:139]
	v_mfma_f32_16x16x32_bf16 v[124:127], v[20:23], v[218:221], v[124:127]
	v_mfma_f32_16x16x32_bf16 v[120:123], v[36:39], v[218:221], v[120:123]
	v_mfma_f32_16x16x32_bf16 v[108:111], v[20:23], v[226:229], v[108:111]
	v_mfma_f32_16x16x32_bf16 v[104:107], v[36:39], v[226:229], v[104:107]
	v_mfma_f32_16x16x32_bf16 v[92:95], v[20:23], v[234:237], v[92:95]
	v_mfma_f32_16x16x32_bf16 v[88:91], v[36:39], v[234:237], v[88:91]
	s_setprio 0
	s_setprio 1
	v_mfma_f32_16x16x32_bf16 v[132:135], v[184:187], v[206:209], 0
	v_mfma_f32_16x16x32_bf16 v[128:131], v[198:201], v[206:209], 0
	v_mfma_f32_16x16x32_bf16 v[116:119], v[184:187], v[214:217], 0
	v_mfma_f32_16x16x32_bf16 v[112:115], v[198:201], v[214:217], 0
	v_mfma_f32_16x16x32_bf16 v[100:103], v[184:187], v[222:225], 0
	v_mfma_f32_16x16x32_bf16 v[96:99], v[198:201], v[222:225], 0
	v_mfma_f32_16x16x32_bf16 v[84:87], v[184:187], v[230:233], 0
	v_mfma_f32_16x16x32_bf16 v[80:83], v[198:201], v[230:233], 0
	v_mfma_f32_16x16x32_bf16 v[132:135], v[194:197], v[210:213], v[132:135]
	v_mfma_f32_16x16x32_bf16 v[128:131], v[202:205], v[210:213], v[128:131]
	v_mfma_f32_16x16x32_bf16 v[116:119], v[194:197], v[218:221], v[116:119]
	v_mfma_f32_16x16x32_bf16 v[112:115], v[202:205], v[218:221], v[112:115]
	v_mfma_f32_16x16x32_bf16 v[100:103], v[194:197], v[226:229], v[100:103]
	v_mfma_f32_16x16x32_bf16 v[96:99], v[202:205], v[226:229], v[96:99]
	v_mfma_f32_16x16x32_bf16 v[84:87], v[194:197], v[234:237], v[84:87]
	v_mfma_f32_16x16x32_bf16 v[80:83], v[202:205], v[234:237], v[80:83]
	s_setprio 0
	s_barrier
	s_add_i32 s50, s67, s54
	v_lshl_add_u64 v[168:169], s[12:13], 0, v[146:147]
	s_mov_b32 m0, s50
	ds_read_b128 v[206:209], v191 offset:16384
	ds_read_b128 v[210:213], v191 offset:17408
	ds_read_b128 v[214:217], v191 offset:18432
	ds_read_b128 v[218:221], v191 offset:19456
	ds_read_b128 v[222:225], v191 offset:20480
	ds_read_b128 v[226:229], v191 offset:21504
	ds_read_b128 v[230:233], v191 offset:22528
	ds_read_b128 v[234:237], v191 offset:23552
	global_load_lds_dwordx4 v[168:169], off
	s_add_i32 m0, s50, 0x2000
	s_add_u32 s50, s12, 0x40000
	v_lshl_add_u64 v[188:189], s[12:13], 0, v[150:151]
	s_addc_u32 s51, s13, 0
	s_add_i32 s78, s72, s54
	global_load_lds_dwordx4 v[188:189], off
	v_lshl_add_u64 v[238:239], s[50:51], 0, v[146:147]
	s_mov_b32 m0, s78
	v_lshl_add_u64 v[240:241], s[14:15], 0, v[148:149]
	global_load_lds_dwordx4 v[238:239], off
	v_lshl_add_u64 v[238:239], s[50:51], 0, v[150:151]
	s_add_i32 m0, s78, 0x2000
	s_nop 0
	global_load_lds_dwordx4 v[238:239], off
	v_lshl_add_u64 v[238:239], s[14:15], 0, v[144:145]
	s_mov_b32 m0, s55
	s_nop 0
	global_load_lds_dwordx4 v[238:239], off
	s_mov_b32 m0, s58
	s_nop 0
	global_load_lds_dwordx4 v[240:241], off
	s_waitcnt vmcnt(8)
	s_waitcnt lgkmcnt(0)
	s_barrier
; #define PG8_STAGE(bufoff, gbase, voff) do { _Pragma("unroll") for (int _i = 0; _i < 2; ++_i) \
;         __builtin_amdgcn_global_load_lds((const unsigned*)((const char*)(gbase) + (voff)[_i]), (LAS unsigned*)(lds + (bufoff) + ldsw + _i * 8192), 16, 0, 0); } while (0)
; #define PG8_LDA(dst, b, h) do { _Pragma("unroll") for (int m = 0; m < 4; ++m) _Pragma("unroll") for (int k = 0; k < 2; ++k) dst[m][k] = *(const LAS bf16x8*)(lds + PG8_SA(b, h) + aoff + m * 2048 + k * 1024); } while (0)
; #define PG8_LDB(dst, b, h) do { _Pragma("unroll") for (int n = 0; n < 2; ++n) _Pragma("unroll") for (int k = 0; k < 2; ++k) dst[n][k] = *(const LAS bf16x8*)(lds + PG8_SB(b, h) + boff + n * 2048 + k * 1024); } while (0)
; #define PG8_MMA(ai, bj, At, Bt) do { __builtin_amdgcn_s_setprio(1); _Pragma("unroll") for (int m = 0; m < 4; ++m) _Pragma("unroll") for (int n = 0; n < 2; ++n) _Pragma("unroll") for (int k = 0; k < 2; ++k) \
;         acc[ai][bj][m][n] = __builtin_amdgcn_mfma_f32_16x16x32_bf16(Bt[n][k], At[m][k], acc[ai][bj][m][n], 0, 0, 0); __builtin_amdgcn_s_setprio(0); } while (0)
; #define PG8_WAIT_V(n) asm volatile("s_waitcnt vmcnt(" #n ")" ::: "memory")
; #define PG8_WAIT_L(n) asm volatile("s_waitcnt lgkmcnt(" #n ")" ::: "memory")
; #define PG8_BAR __builtin_amdgcn_s_barrier()
; #define PG8_SCHED __builtin_amdgcn_sched_barrier(0)
; template <class Epi, class Sched>
; __device__ __forceinline__ void gemm_phase(LAS unsigned char* lds, const Gemm g, const Sched& S, const Epi& E, int wave_id) {
;     ...
;             PG8_WAIT_V(8); PG8_WAIT_L(0); PG8_BAR; PG8_MMA(1, 0, At, B0); PG8_MMA(1, 1, At, B1); PG8_BAR; PG8_SCHED;
;             PG8_LDB(B0, 1, 0); PG8_LDB(B1, 1, 1); PG8_SCHED; PG8_LDA(At, 1, 0); PG8_STAGE(PG8_SA(0, 1), a2 + hstepA, voffA);
;             PG8_WAIT_V(8); PG8_WAIT_L(0); PG8_BAR; PG8_MMA(0, 0, At, B0); PG8_MMA(0, 1, At, B1); PG8_BAR; PG8_SCHED;
	s_setprio 1
	s_waitcnt lgkmcnt(0)
	v_mfma_f32_16x16x32_bf16 v[76:79], v[16:19], v[206:209], 0
	v_mfma_f32_16x16x32_bf16 v[72:75], v[32:35], v[206:209], 0
	v_mfma_f32_16x16x32_bf16 v[60:63], v[16:19], v[214:217], 0
	v_mfma_f32_16x16x32_bf16 v[56:59], v[32:35], v[214:217], 0
	v_mfma_f32_16x16x32_bf16 v[44:47], v[16:19], v[222:225], 0
	v_mfma_f32_16x16x32_bf16 v[40:43], v[32:35], v[222:225], 0
	v_mfma_f32_16x16x32_bf16 v[12:15], v[16:19], v[230:233], 0
	v_mfma_f32_16x16x32_bf16 v[8:11], v[32:35], v[230:233], 0
	v_mfma_f32_16x16x32_bf16 v[76:79], v[20:23], v[210:213], v[76:79]
	v_mfma_f32_16x16x32_bf16 v[72:75], v[36:39], v[210:213], v[72:75]
	v_mfma_f32_16x16x32_bf16 v[60:63], v[20:23], v[218:221], v[60:63]
	v_mfma_f32_16x16x32_bf16 v[56:59], v[36:39], v[218:221], v[56:59]
	v_mfma_f32_16x16x32_bf16 v[44:47], v[20:23], v[226:229], v[44:47]
	v_mfma_f32_16x16x32_bf16 v[40:43], v[36:39], v[226:229], v[40:43]
	v_mfma_f32_16x16x32_bf16 v[12:15], v[20:23], v[234:237], v[12:15]
	v_mfma_f32_16x16x32_bf16 v[8:11], v[36:39], v[234:237], v[8:11]
	s_setprio 0
	s_setprio 1
	v_mfma_f32_16x16x32_bf16 v[28:31], v[184:187], v[222:225], 0
	v_mfma_f32_16x16x32_bf16 v[24:27], v[198:201], v[222:225], 0
	v_mfma_f32_16x16x32_bf16 v[4:7], v[184:187], v[230:233], 0
	v_mfma_f32_16x16x32_bf16 v[0:3], v[198:201], v[230:233], 0
	v_mfma_f32_16x16x32_bf16 v[16:19], v[184:187], v[206:209], 0
	v_mfma_f32_16x16x32_bf16 v[20:23], v[198:201], v[206:209], 0
	v_mfma_f32_16x16x32_bf16 v[32:35], v[184:187], v[214:217], 0
	v_mfma_f32_16x16x32_bf16 v[36:39], v[198:201], v[214:217], 0
	v_mfma_f32_16x16x32_bf16 v[28:31], v[194:197], v[226:229], v[28:31]
	v_mfma_f32_16x16x32_bf16 v[24:27], v[202:205], v[226:229], v[24:27]
	v_mfma_f32_16x16x32_bf16 v[4:7], v[194:197], v[234:237], v[4:7]
	v_mfma_f32_16x16x32_bf16 v[0:3], v[202:205], v[234:237], v[0:3]
	v_mfma_f32_16x16x32_bf16 v[16:19], v[194:197], v[210:213], v[16:19]
	v_mfma_f32_16x16x32_bf16 v[20:23], v[202:205], v[210:213], v[20:23]
	v_mfma_f32_16x16x32_bf16 v[32:35], v[194:197], v[218:221], v[32:35]
	v_mfma_f32_16x16x32_bf16 v[36:39], v[202:205], v[218:221], v[36:39]
	s_setprio 0
	s_barrier
	s_add_i32 s50, 0, 0x18000
	s_add_i32 s51, 0, 0x1c000
	v_add_u32_e32 v68, s50, v171
	v_add_u32_e32 v152, s51, v171
	ds_read_b128 v[48:51], v68
	ds_read_b128 v[52:55], v68 offset:1024
	ds_read_b128 v[64:67], v68 offset:2048
	ds_read_b128 v[68:71], v68 offset:3072
	ds_read_b128 v[184:187], v152
	ds_read_b128 v[194:197], v152 offset:1024
	ds_read_b128 v[198:201], v152 offset:2048
	ds_read_b128 v[202:205], v152 offset:3072
	s_add_u32 s14, s14, 0x40000
	s_addc_u32 s15, s15, 0
	s_mov_b32 m0, s59
	v_lshl_add_u64 v[242:243], s[14:15], 0, v[144:145]
	ds_read_b128 v[206:209], v191 offset:32768
	ds_read_b128 v[210:213], v191 offset:33792
	ds_read_b128 v[214:217], v191 offset:34816
	ds_read_b128 v[218:221], v191 offset:35840
	ds_read_b128 v[222:225], v191 offset:36864
	ds_read_b128 v[226:229], v191 offset:37888
	ds_read_b128 v[230:233], v191 offset:38912
	ds_read_b128 v[234:237], v191 offset:39936
	global_load_lds_dwordx4 v[242:243], off
	v_lshl_add_u64 v[242:243], s[14:15], 0, v[148:149]
	s_mov_b32 m0, s60
	s_nop 0
	global_load_lds_dwordx4 v[242:243], off
	s_waitcnt vmcnt(8)
	s_waitcnt lgkmcnt(0)
	s_barrier
	s_setprio 1
	s_waitcnt lgkmcnt(0)
	v_mfma_f32_16x16x32_bf16 v[140:143], v[48:51], v[206:209], v[140:143]
	v_mfma_f32_16x16x32_bf16 v[136:139], v[64:67], v[206:209], v[136:139]
	v_mfma_f32_16x16x32_bf16 v[124:127], v[48:51], v[214:217], v[124:127]
	v_mfma_f32_16x16x32_bf16 v[120:123], v[64:67], v[214:217], v[120:123]
	v_mfma_f32_16x16x32_bf16 v[108:111], v[48:51], v[222:225], v[108:111]
	v_mfma_f32_16x16x32_bf16 v[104:107], v[64:67], v[222:225], v[104:107]
	v_mfma_f32_16x16x32_bf16 v[92:95], v[48:51], v[230:233], v[92:95]
	v_mfma_f32_16x16x32_bf16 v[88:91], v[64:67], v[230:233], v[88:91]
	v_mfma_f32_16x16x32_bf16 v[140:143], v[52:55], v[210:213], v[140:143]
	v_mfma_f32_16x16x32_bf16 v[136:139], v[68:71], v[210:213], v[136:139]
	v_mfma_f32_16x16x32_bf16 v[124:127], v[52:55], v[218:221], v[124:127]
	v_mfma_f32_16x16x32_bf16 v[120:123], v[68:71], v[218:221], v[120:123]
	v_mfma_f32_16x16x32_bf16 v[108:111], v[52:55], v[226:229], v[108:111]
	v_mfma_f32_16x16x32_bf16 v[104:107], v[68:71], v[226:229], v[104:107]
	v_mfma_f32_16x16x32_bf16 v[92:95], v[52:55], v[234:237], v[92:95]
	v_mfma_f32_16x16x32_bf16 v[88:91], v[68:71], v[234:237], v[88:91]
	s_setprio 0
	s_setprio 1
	v_mfma_f32_16x16x32_bf16 v[132:135], v[184:187], v[206:209], v[132:135]
	v_mfma_f32_16x16x32_bf16 v[128:131], v[198:201], v[206:209], v[128:131]
	v_mfma_f32_16x16x32_bf16 v[116:119], v[184:187], v[214:217], v[116:119]
	v_mfma_f32_16x16x32_bf16 v[112:115], v[198:201], v[214:217], v[112:115]
	v_mfma_f32_16x16x32_bf16 v[100:103], v[184:187], v[222:225], v[100:103]
	v_mfma_f32_16x16x32_bf16 v[96:99], v[198:201], v[222:225], v[96:99]
	v_mfma_f32_16x16x32_bf16 v[84:87], v[184:187], v[230:233], v[84:87]
	v_mfma_f32_16x16x32_bf16 v[80:83], v[198:201], v[230:233], v[80:83]
	v_mfma_f32_16x16x32_bf16 v[132:135], v[194:197], v[210:213], v[132:135]
	v_mfma_f32_16x16x32_bf16 v[128:131], v[202:205], v[210:213], v[128:131]
	v_mfma_f32_16x16x32_bf16 v[116:119], v[194:197], v[218:221], v[116:119]
	v_mfma_f32_16x16x32_bf16 v[112:115], v[202:205], v[218:221], v[112:115]
	v_mfma_f32_16x16x32_bf16 v[100:103], v[194:197], v[226:229], v[100:103]
	v_mfma_f32_16x16x32_bf16 v[96:99], v[202:205], v[226:229], v[96:99]
	v_mfma_f32_16x16x32_bf16 v[84:87], v[194:197], v[234:237], v[84:87]
	v_mfma_f32_16x16x32_bf16 v[80:83], v[202:205], v[234:237], v[80:83]
	s_setprio 0
	s_barrier
; #define PG8_STAGE(bufoff, gbase, voff) do { _Pragma("unroll") for (int _i = 0; _i < 2; ++_i) \
;         __builtin_amdgcn_global_load_lds((const unsigned*)((const char*)(gbase) + (voff)[_i]), (LAS unsigned*)(lds + (bufoff) + ldsw + _i * 8192), 16, 0, 0); } while (0)
; #define PG8_LDA(dst, b, h) do { _Pragma("unroll") for (int m = 0; m < 4; ++m) _Pragma("unroll") for (int k = 0; k < 2; ++k) dst[m][k] = *(const LAS bf16x8*)(lds + PG8_SA(b, h) + aoff + m * 2048 + k * 1024); } while (0)
; #define PG8_MMA(ai, bj, At, Bt) do { __builtin_amdgcn_s_setprio(1); _Pragma("unroll") for (int m = 0; m < 4; ++m) _Pragma("unroll") for (int n = 0; n < 2; ++n) _Pragma("unroll") for (int k = 0; k < 2; ++k) \
;         acc[ai][bj][m][n] = __builtin_amdgcn_mfma_f32_16x16x32_bf16(Bt[n][k], At[m][k], acc[ai][bj][m][n], 0, 0, 0); __builtin_amdgcn_s_setprio(0); } while (0)
; #define PG8_WAIT_V(n) asm volatile("s_waitcnt vmcnt(" #n ")" ::: "memory")
; #define PG8_WAIT_L(n) asm volatile("s_waitcnt lgkmcnt(" #n ")" ::: "memory")
; #define PG8_BAR __builtin_amdgcn_s_barrier()
; #define PG8_SCHED __builtin_amdgcn_sched_barrier(0)
; template <class Epi, class Sched>
; __device__ __forceinline__ void gemm_phase(LAS unsigned char* lds, const Gemm g, const Sched& S, const Epi& E, int wave_id) {
;     ...
;             PG8_LDA(At, 1, 1); PG8_STAGE(PG8_SB(1, 0), b3, voffB); PG8_STAGE(PG8_SB(1, 1), b3 + hstepB, voffB); PG8_STAGE(PG8_SA(1, 0), a3, voffA);
;             PG8_WAIT_V(8); PG8_WAIT_L(0); PG8_BAR; PG8_MMA(1, 0, At, B0); PG8_MMA(1, 1, At, B1); PG8_BAR; PG8_SCHED;
;         }
	s_add_i32 s14, s50, s54
	v_lshl_add_u64 v[168:169], v[168:169], 0, s[22:23]
	s_mov_b32 m0, s14
	ds_read_b128 v[206:209], v191 offset:49152
	ds_read_b128 v[210:213], v191 offset:50176
	ds_read_b128 v[214:217], v191 offset:51200
	ds_read_b128 v[218:221], v191 offset:52224
	ds_read_b128 v[222:225], v191 offset:53248
	ds_read_b128 v[226:229], v191 offset:54272
	ds_read_b128 v[230:233], v191 offset:55296
	ds_read_b128 v[234:237], v191 offset:56320
	global_load_lds_dwordx4 v[168:169], off
	s_add_i32 m0, s14, 0x2000
	s_add_u32 s12, s12, 0x40080
	v_lshl_add_u64 v[168:169], v[188:189], 0, s[22:23]
	s_addc_u32 s13, s13, 0
	s_add_i32 s14, s51, s54
	global_load_lds_dwordx4 v[168:169], off
	v_lshl_add_u64 v[168:169], s[12:13], 0, v[146:147]
	s_mov_b32 m0, s14
	s_nop 0
	global_load_lds_dwordx4 v[168:169], off
	v_lshl_add_u64 v[168:169], s[12:13], 0, v[150:151]
	s_add_i32 m0, s14, 0x2000
	s_nop 0
	global_load_lds_dwordx4 v[168:169], off
	v_lshl_add_u64 v[168:169], v[238:239], 0, s[22:23]
	s_mov_b32 m0, s62
	s_nop 0
	global_load_lds_dwordx4 v[168:169], off
	v_lshl_add_u64 v[168:169], v[240:241], 0, s[22:23]
	s_mov_b32 m0, s63
	s_nop 0
	global_load_lds_dwordx4 v[168:169], off
	s_waitcnt vmcnt(8)
	s_waitcnt lgkmcnt(0)
	s_barrier
	s_setprio 1
	s_waitcnt lgkmcnt(0)
	v_mfma_f32_16x16x32_bf16 v[76:79], v[48:51], v[206:209], v[76:79]
	v_mfma_f32_16x16x32_bf16 v[72:75], v[64:67], v[206:209], v[72:75]
	v_mfma_f32_16x16x32_bf16 v[60:63], v[48:51], v[214:217], v[60:63]
	v_mfma_f32_16x16x32_bf16 v[56:59], v[64:67], v[214:217], v[56:59]
	v_mfma_f32_16x16x32_bf16 v[44:47], v[48:51], v[222:225], v[44:47]
	v_mfma_f32_16x16x32_bf16 v[40:43], v[64:67], v[222:225], v[40:43]
	v_mfma_f32_16x16x32_bf16 v[12:15], v[48:51], v[230:233], v[12:15]
	v_mfma_f32_16x16x32_bf16 v[8:11], v[64:67], v[230:233], v[8:11]
	v_mfma_f32_16x16x32_bf16 v[76:79], v[52:55], v[210:213], v[76:79]
	v_mfma_f32_16x16x32_bf16 v[72:75], v[68:71], v[210:213], v[72:75]
	v_mfma_f32_16x16x32_bf16 v[60:63], v[52:55], v[218:221], v[60:63]
	v_mfma_f32_16x16x32_bf16 v[56:59], v[68:71], v[218:221], v[56:59]
	v_mfma_f32_16x16x32_bf16 v[44:47], v[52:55], v[226:229], v[44:47]
	v_mfma_f32_16x16x32_bf16 v[40:43], v[68:71], v[226:229], v[40:43]
	v_mfma_f32_16x16x32_bf16 v[12:15], v[52:55], v[234:237], v[12:15]
	v_mfma_f32_16x16x32_bf16 v[8:11], v[68:71], v[234:237], v[8:11]
	s_setprio 0
	s_setprio 1
	v_mfma_f32_16x16x32_bf16 v[16:19], v[184:187], v[206:209], v[16:19]
	v_mfma_f32_16x16x32_bf16 v[68:71], v[194:197], v[210:213], v[16:19]
	v_mfma_f32_16x16x32_bf16 v[16:19], v[198:201], v[206:209], v[20:23]
	v_mfma_f32_16x16x32_bf16 v[64:67], v[202:205], v[210:213], v[16:19]
	v_mfma_f32_16x16x32_bf16 v[16:19], v[184:187], v[214:217], v[32:35]
	v_mfma_f32_16x16x32_bf16 v[52:55], v[194:197], v[218:221], v[16:19]
	v_mfma_f32_16x16x32_bf16 v[16:19], v[198:201], v[214:217], v[36:39]
	v_mfma_f32_16x16x32_bf16 v[48:51], v[202:205], v[218:221], v[16:19]
	v_mfma_f32_16x16x32_bf16 v[16:19], v[184:187], v[222:225], v[28:31]
	v_mfma_f32_16x16x32_bf16 v[28:31], v[194:197], v[226:229], v[16:19]
	v_mfma_f32_16x16x32_bf16 v[16:19], v[198:201], v[222:225], v[24:27]
	v_mfma_f32_16x16x32_bf16 v[4:7], v[184:187], v[230:233], v[4:7]
	v_mfma_f32_16x16x32_bf16 v[0:3], v[198:201], v[230:233], v[0:3]
	v_mfma_f32_16x16x32_bf16 v[24:27], v[202:205], v[226:229], v[16:19]
	v_mfma_f32_16x16x32_bf16 v[4:7], v[194:197], v[234:237], v[4:7]
	v_mfma_f32_16x16x32_bf16 v[0:3], v[202:205], v[234:237], v[0:3]
	s_setprio 0
	s_barrier
	s_add_i32 s45, s45, 2
	s_add_u32 s10, s10, 0x100
	s_addc_u32 s11, s11, 0
	s_add_u32 s33, s33, 0x100
	s_addc_u32 s39, s39, 0
	s_cmp_gt_u32 s45, 13

;     __device__ bool next(int i, Unit& u) const { if (r0 + i >= r1) return false; return base.next(r0 + i, u); }
;     __device__ bool next(int i, Unit& u) const { const int L = i * G + c; if (L >= 256) return false; u.pm = L; u.pn = L >> 3; return true; }
; #define PG8_STAGE(bufoff, gbase, voff) do { _Pragma("unroll") for (int _i = 0; _i < 2; ++_i) \
;         __builtin_amdgcn_global_load_lds((const unsigned*)((const char*)(gbase) + (voff)[_i]), (LAS unsigned*)(lds + (bufoff) + ldsw + _i * 8192), 16, 0, 0); } while (0)
; #define PG8_LDA(dst, b, h) do { _Pragma("unroll") for (int m = 0; m < 4; ++m) _Pragma("unroll") for (int k = 0; k < 2; ++k) dst[m][k] = *(const LAS bf16x8*)(lds + PG8_SA(b, h) + aoff + m * 2048 + k * 1024); } while (0)
; #define PG8_LDB(dst, b, h) do { _Pragma("unroll") for (int n = 0; n < 2; ++n) _Pragma("unroll") for (int k = 0; k < 2; ++k) dst[n][k] = *(const LAS bf16x8*)(lds + PG8_SB(b, h) + boff + n * 2048 + k * 1024); } while (0)
; template <class Epi, class Sched>
; __device__ __forceinline__ void gemm_phase(LAS unsigned char* lds, const Gemm g, const Sched& S, const Epi& E, int wave_id) {
;     ...
;         const bool has_next = S.next(ui + 1, nxt);
;         const char* nA = has_next ? (const char*)g.A + (size_t)nxt.pm * tstepA : cA; const char* nB = has_next ? (const char*)g.Bt + (size_t)nxt.pn * tstepB : cB;
;         for (int t = 0; t < nt; t += 2) {
;             const bool last = (t == nt - 2);
;             const char* a1 = cA + (size_t)(t + 1) * kstep;
;             const char* a2 = last ? nA : cA + (size_t)(t + 2) * kstep; const char* b2 = last ? nB : cB + (size_t)(t + 2) * kstep;
;             const char* a3 = a2 + kstep; const char* b3 = b2 + kstep;
;             PG8_LDB(B0, 0, 0); PG8_LDB(B1, 0, 1); PG8_SCHED; PG8_LDA(At, 0, 0); PG8_STAGE(PG8_SA(1, 1), a1 + hstepA, voffA);
;             PG8_WAIT_V(8); PG8_WAIT_L(0); PG8_BAR; PG8_MMA(0, 0, At, B0); PG8_MMA(0, 1, At, B1); PG8_BAR; PG8_SCHED;
;             PG8_LDA(At, 0, 1); PG8_STAGE(PG8_SB(0, 0), b2, voffB); PG8_STAGE(PG8_SB(0, 1), b2 + hstepB, voffB); PG8_STAGE(PG8_SA(0, 0), a2, voffA);
;     ...
;         for (int a = 0; a < 2; ++a)
; #pragma unroll
;             for (int b = 0; b < 2; ++b)
; #pragma unroll
;                 for (int m = 0; m < 4; ++m)
; #pragma unroll
;                     for (int n = 0; n < 2; ++n) acc[a][b][m][n] = (f32x4){0.f, 0.f, 0.f, 0.f};
.LBB0_672:
	s_ashr_i32 s23, s22, 31
	s_lshl_b64 s[26:27], s[22:23], 19
	s_add_u32 s26, s15, s26
	s_addc_u32 s27, s33, s27
	s_and_b64 s[28:29], s[24:25], exec
	s_cselect_b32 s23, s27, s35
	s_cselect_b32 s61, s26, s34
	s_ashr_i32 s17, s16, 31
	s_lshl_b64 s[28:29], s[16:17], 19
	s_add_u32 s28, s44, s28
	s_addc_u32 s29, s45, s29
	s_and_b64 s[38:39], s[24:25], exec
	s_cselect_b32 s17, s29, s37
	s_cselect_b32 s62, s28, s36
	s_add_u32 s34, s34, 0x40080
	s_addc_u32 s35, s35, 0
	s_add_u32 s63, s36, 0x100
	s_addc_u32 s64, s37, 0
	s_mov_b32 s65, -2
	ds_read_b128 v[142:145], v161
	ds_read_b128 v[146:149], v161 offset:1024
	ds_read_b128 v[150:153], v161 offset:2048
	ds_read_b128 v[154:157], v161 offset:3072
	ds_read_b128 v[164:167], v162
	ds_read_b128 v[168:171], v162 offset:1024
	ds_read_b128 v[172:175], v162 offset:2048
	ds_read_b128 v[176:179], v162 offset:3072
	s_add_u32 s36, s34, 0xfffc0080
	s_addc_u32 s37, s35, -1
	s_cmp_eq_u32 s65, 12
	s_cselect_b32 s39, s23, s37
	s_cselect_b32 s38, s61, s36
	s_cselect_b32 s37, s17, s64
	s_cselect_b32 s36, s62, s63
	v_lshl_add_u64 v[212:213], s[34:35], 0, v[136:137]
	s_add_i32 m0, s31, 0xc000
	ds_read_b128 v[180:183], v163
	ds_read_b128 v[184:187], v163 offset:1024
	ds_read_b128 v[188:191], v163 offset:2048
	ds_read_b128 v[192:195], v163 offset:3072
	ds_read_b128 v[196:199], v163 offset:4096
	ds_read_b128 v[200:203], v163 offset:5120
	ds_read_b128 v[204:207], v163 offset:6144
	ds_read_b128 v[208:211], v163 offset:7168
	global_load_lds_dwordx4 v[212:213], off
	v_lshl_add_u64 v[212:213], s[34:35], 0, v[138:139]
	s_add_i32 m0, s31, 0xe000
	s_nop 0
	global_load_lds_dwordx4 v[212:213], off
	s_waitcnt vmcnt(8)
	s_waitcnt lgkmcnt(0)
	s_barrier
	s_setprio 1
	s_waitcnt lgkmcnt(0)
	v_mfma_f32_16x16x32_bf16 v[124:127], v[142:145], v[180:183], 0
	v_mfma_f32_16x16x32_bf16 v[120:123], v[150:153], v[180:183], 0
	v_mfma_f32_16x16x32_bf16 v[108:111], v[142:145], v[188:191], 0
	v_mfma_f32_16x16x32_bf16 v[104:107], v[150:153], v[188:191], 0
	v_mfma_f32_16x16x32_bf16 v[92:95], v[142:145], v[196:199], 0
	v_mfma_f32_16x16x32_bf16 v[88:91], v[150:153], v[196:199], 0
	v_mfma_f32_16x16x32_bf16 v[76:79], v[142:145], v[204:207], 0
	v_mfma_f32_16x16x32_bf16 v[72:75], v[150:153], v[204:207], 0
	v_mfma_f32_16x16x32_bf16 v[124:127], v[146:149], v[184:187], v[124:127]
	v_mfma_f32_16x16x32_bf16 v[120:123], v[154:157], v[184:187], v[120:123]
	v_mfma_f32_16x16x32_bf16 v[108:111], v[146:149], v[192:195], v[108:111]
	v_mfma_f32_16x16x32_bf16 v[104:107], v[154:157], v[192:195], v[104:107]
	v_mfma_f32_16x16x32_bf16 v[92:95], v[146:149], v[200:203], v[92:95]
	v_mfma_f32_16x16x32_bf16 v[88:91], v[154:157], v[200:203], v[88:91]
	v_mfma_f32_16x16x32_bf16 v[76:79], v[146:149], v[208:211], v[76:79]
	v_mfma_f32_16x16x32_bf16 v[72:75], v[154:157], v[208:211], v[72:75]
	s_setprio 0
	s_setprio 1
	v_mfma_f32_16x16x32_bf16 v[116:119], v[164:167], v[180:183], 0
	v_mfma_f32_16x16x32_bf16 v[112:115], v[172:175], v[180:183], 0
	v_mfma_f32_16x16x32_bf16 v[100:103], v[164:167], v[188:191], 0
	v_mfma_f32_16x16x32_bf16 v[96:99], v[172:175], v[188:191], 0
	v_mfma_f32_16x16x32_bf16 v[84:87], v[164:167], v[196:199], 0
	v_mfma_f32_16x16x32_bf16 v[80:83], v[172:175], v[196:199], 0
	v_mfma_f32_16x16x32_bf16 v[68:71], v[164:167], v[204:207], 0
	v_mfma_f32_16x16x32_bf16 v[64:67], v[172:175], v[204:207], 0
	v_mfma_f32_16x16x32_bf16 v[116:119], v[168:171], v[184:187], v[116:119]
	v_mfma_f32_16x16x32_bf16 v[112:115], v[176:179], v[184:187], v[112:115]
	v_mfma_f32_16x16x32_bf16 v[100:103], v[168:171], v[192:195], v[100:103]
	v_mfma_f32_16x16x32_bf16 v[96:99], v[176:179], v[192:195], v[96:99]
	v_mfma_f32_16x16x32_bf16 v[84:87], v[168:171], v[200:203], v[84:87]
	v_mfma_f32_16x16x32_bf16 v[80:83], v[176:179], v[200:203], v[80:83]
	v_mfma_f32_16x16x32_bf16 v[68:71], v[168:171], v[208:211], v[68:71]
	v_mfma_f32_16x16x32_bf16 v[64:67], v[176:179], v[208:211], v[64:67]
	s_setprio 0
	s_barrier
	s_add_i32 s66, s55, s46
	v_lshl_add_u64 v[212:213], s[36:37], 0, v[130:131]
	s_mov_b32 m0, s66
	ds_read_b128 v[180:183], v163 offset:16384
	ds_read_b128 v[184:187], v163 offset:17408
	ds_read_b128 v[188:191], v163 offset:18432
	ds_read_b128 v[192:195], v163 offset:19456
	ds_read_b128 v[196:199], v163 offset:20480
	ds_read_b128 v[200:203], v163 offset:21504
	ds_read_b128 v[204:207], v163 offset:22528
	ds_read_b128 v[208:211], v163 offset:23552
	global_load_lds_dwordx4 v[212:213], off
	s_add_i32 m0, s66, 0x2000
	s_add_u32 s66, s36, 0x40000
	v_lshl_add_u64 v[214:215], s[36:37], 0, v[134:135]
	s_addc_u32 s67, s37, 0
	s_add_i32 s72, s58, s46
	global_load_lds_dwordx4 v[214:215], off
	v_lshl_add_u64 v[216:217], s[66:67], 0, v[130:131]
	s_mov_b32 m0, s72
	v_lshl_add_u64 v[218:219], s[38:39], 0, v[132:133]
	global_load_lds_dwordx4 v[216:217], off
	v_lshl_add_u64 v[216:217], s[66:67], 0, v[134:135]
	s_add_i32 m0, s72, 0x2000
	s_nop 0
	global_load_lds_dwordx4 v[216:217], off
	v_lshl_add_u64 v[216:217], s[38:39], 0, v[128:129]
	s_mov_b32 m0, s31
	s_nop 0
	global_load_lds_dwordx4 v[216:217], off
	s_mov_b32 m0, s47
	s_nop 0
	global_load_lds_dwordx4 v[218:219], off
	s_waitcnt vmcnt(8)
	s_waitcnt lgkmcnt(0)
	s_barrier
; #define PG8_STAGE(bufoff, gbase, voff) do { _Pragma("unroll") for (int _i = 0; _i < 2; ++_i) \
;         __builtin_amdgcn_global_load_lds((const unsigned*)((const char*)(gbase) + (voff)[_i]), (LAS unsigned*)(lds + (bufoff) + ldsw + _i * 8192), 16, 0, 0); } while (0)
; #define PG8_LDA(dst, b, h) do { _Pragma("unroll") for (int m = 0; m < 4; ++m) _Pragma("unroll") for (int k = 0; k < 2; ++k) dst[m][k] = *(const LAS bf16x8*)(lds + PG8_SA(b, h) + aoff + m * 2048 + k * 1024); } while (0)
; #define PG8_LDB(dst, b, h) do { _Pragma("unroll") for (int n = 0; n < 2; ++n) _Pragma("unroll") for (int k = 0; k < 2; ++k) dst[n][k] = *(const LAS bf16x8*)(lds + PG8_SB(b, h) + boff + n * 2048 + k * 1024); } while (0)
; #define PG8_MMA(ai, bj, At, Bt) do { __builtin_amdgcn_s_setprio(1); _Pragma("unroll") for (int m = 0; m < 4; ++m) _Pragma("unroll") for (int n = 0; n < 2; ++n) _Pragma("unroll") for (int k = 0; k < 2; ++k) \
;         acc[ai][bj][m][n] = __builtin_amdgcn_mfma_f32_16x16x32_bf16(Bt[n][k], At[m][k], acc[ai][bj][m][n], 0, 0, 0); __builtin_amdgcn_s_setprio(0); } while (0)
; #define PG8_WAIT_V(n) asm volatile("s_waitcnt vmcnt(" #n ")" ::: "memory")
; #define PG8_WAIT_L(n) asm volatile("s_waitcnt lgkmcnt(" #n ")" ::: "memory")
; #define PG8_BAR __builtin_amdgcn_s_barrier()
; #define PG8_SCHED __builtin_amdgcn_sched_barrier(0)
; template <class Epi, class Sched>
; __device__ __forceinline__ void gemm_phase(LAS unsigned char* lds, const Gemm g, const Sched& S, const Epi& E, int wave_id) {
;     ...
;             PG8_WAIT_V(8); PG8_WAIT_L(0); PG8_BAR; PG8_MMA(1, 0, At, B0); PG8_MMA(1, 1, At, B1); PG8_BAR; PG8_SCHED;
;             PG8_LDB(B0, 1, 0); PG8_LDB(B1, 1, 1); PG8_SCHED; PG8_LDA(At, 1, 0); PG8_STAGE(PG8_SA(0, 1), a2 + hstepA, voffA);
;             PG8_WAIT_V(8); PG8_WAIT_L(0); PG8_BAR; PG8_MMA(0, 0, At, B0); PG8_MMA(0, 1, At, B1); PG8_BAR; PG8_SCHED;
	s_setprio 1
	s_waitcnt lgkmcnt(0)
	v_mfma_f32_16x16x32_bf16 v[60:63], v[142:145], v[180:183], 0
	v_mfma_f32_16x16x32_bf16 v[56:59], v[150:153], v[180:183], 0
	v_mfma_f32_16x16x32_bf16 v[44:47], v[142:145], v[188:191], 0
	v_mfma_f32_16x16x32_bf16 v[40:43], v[150:153], v[188:191], 0
	v_mfma_f32_16x16x32_bf16 v[28:31], v[142:145], v[196:199], 0
	v_mfma_f32_16x16x32_bf16 v[24:27], v[150:153], v[196:199], 0
	v_mfma_f32_16x16x32_bf16 v[12:15], v[142:145], v[204:207], 0
	v_mfma_f32_16x16x32_bf16 v[8:11], v[150:153], v[204:207], 0
	v_mfma_f32_16x16x32_bf16 v[60:63], v[146:149], v[184:187], v[60:63]
	v_mfma_f32_16x16x32_bf16 v[56:59], v[154:157], v[184:187], v[56:59]
	v_mfma_f32_16x16x32_bf16 v[44:47], v[146:149], v[192:195], v[44:47]
	v_mfma_f32_16x16x32_bf16 v[40:43], v[154:157], v[192:195], v[40:43]
	v_mfma_f32_16x16x32_bf16 v[28:31], v[146:149], v[200:203], v[28:31]
	v_mfma_f32_16x16x32_bf16 v[24:27], v[154:157], v[200:203], v[24:27]
	v_mfma_f32_16x16x32_bf16 v[12:15], v[146:149], v[208:211], v[12:15]
	v_mfma_f32_16x16x32_bf16 v[8:11], v[154:157], v[208:211], v[8:11]
	s_setprio 0
	s_setprio 1
	v_mfma_f32_16x16x32_bf16 v[52:55], v[164:167], v[180:183], 0
	v_mfma_f32_16x16x32_bf16 v[48:51], v[172:175], v[180:183], 0
	v_mfma_f32_16x16x32_bf16 v[36:39], v[164:167], v[188:191], 0
	v_mfma_f32_16x16x32_bf16 v[32:35], v[172:175], v[188:191], 0
	v_mfma_f32_16x16x32_bf16 v[20:23], v[164:167], v[196:199], 0
	v_mfma_f32_16x16x32_bf16 v[16:19], v[172:175], v[196:199], 0
	v_mfma_f32_16x16x32_bf16 v[4:7], v[164:167], v[204:207], 0
	v_mfma_f32_16x16x32_bf16 v[0:3], v[172:175], v[204:207], 0
	v_mfma_f32_16x16x32_bf16 v[52:55], v[168:171], v[184:187], v[52:55]
	v_mfma_f32_16x16x32_bf16 v[48:51], v[176:179], v[184:187], v[48:51]
	v_mfma_f32_16x16x32_bf16 v[36:39], v[168:171], v[192:195], v[36:39]
	v_mfma_f32_16x16x32_bf16 v[32:35], v[176:179], v[192:195], v[32:35]
	v_mfma_f32_16x16x32_bf16 v[20:23], v[168:171], v[200:203], v[20:23]
	v_mfma_f32_16x16x32_bf16 v[16:19], v[176:179], v[200:203], v[16:19]
	v_mfma_f32_16x16x32_bf16 v[4:7], v[168:171], v[208:211], v[4:7]
	v_mfma_f32_16x16x32_bf16 v[0:3], v[176:179], v[208:211], v[0:3]
	s_setprio 0
	s_barrier
	s_add_i32 s66, 0, 0x18000
	s_add_i32 s67, 0, 0x1c000
	v_add_u32_e32 v154, s66, v159
	v_add_u32_e32 v176, s67, v159
	ds_read_b128 v[142:145], v154
	ds_read_b128 v[146:149], v154 offset:1024
	ds_read_b128 v[150:153], v154 offset:2048
	ds_read_b128 v[154:157], v154 offset:3072
	ds_read_b128 v[164:167], v176
	ds_read_b128 v[168:171], v176 offset:1024
	ds_read_b128 v[172:175], v176 offset:2048
	ds_read_b128 v[176:179], v176 offset:3072
	s_add_u32 s38, s38, 0x40000
	s_addc_u32 s39, s39, 0
	s_mov_b32 m0, s48
	v_lshl_add_u64 v[220:221], s[38:39], 0, v[128:129]
	ds_read_b128 v[180:183], v163 offset:32768
	ds_read_b128 v[184:187], v163 offset:33792
	ds_read_b128 v[188:191], v163 offset:34816
	ds_read_b128 v[192:195], v163 offset:35840
	ds_read_b128 v[196:199], v163 offset:36864
	ds_read_b128 v[200:203], v163 offset:37888
	ds_read_b128 v[204:207], v163 offset:38912
	ds_read_b128 v[208:211], v163 offset:39936
	global_load_lds_dwordx4 v[220:221], off
	v_lshl_add_u64 v[220:221], s[38:39], 0, v[132:133]
	s_mov_b32 m0, s49
	s_nop 0
	global_load_lds_dwordx4 v[220:221], off
	s_waitcnt vmcnt(8)
	s_waitcnt lgkmcnt(0)
	s_barrier
	s_setprio 1
	s_waitcnt lgkmcnt(0)
	v_mfma_f32_16x16x32_bf16 v[124:127], v[142:145], v[180:183], v[124:127]
	v_mfma_f32_16x16x32_bf16 v[120:123], v[150:153], v[180:183], v[120:123]
	v_mfma_f32_16x16x32_bf16 v[108:111], v[142:145], v[188:191], v[108:111]
	v_mfma_f32_16x16x32_bf16 v[104:107], v[150:153], v[188:191], v[104:107]
	v_mfma_f32_16x16x32_bf16 v[92:95], v[142:145], v[196:199], v[92:95]
	v_mfma_f32_16x16x32_bf16 v[88:91], v[150:153], v[196:199], v[88:91]
	v_mfma_f32_16x16x32_bf16 v[76:79], v[142:145], v[204:207], v[76:79]
	v_mfma_f32_16x16x32_bf16 v[72:75], v[150:153], v[204:207], v[72:75]
	v_mfma_f32_16x16x32_bf16 v[124:127], v[146:149], v[184:187], v[124:127]
	v_mfma_f32_16x16x32_bf16 v[120:123], v[154:157], v[184:187], v[120:123]
	v_mfma_f32_16x16x32_bf16 v[108:111], v[146:149], v[192:195], v[108:111]
	v_mfma_f32_16x16x32_bf16 v[104:107], v[154:157], v[192:195], v[104:107]
	v_mfma_f32_16x16x32_bf16 v[92:95], v[146:149], v[200:203], v[92:95]
	v_mfma_f32_16x16x32_bf16 v[88:91], v[154:157], v[200:203], v[88:91]
	v_mfma_f32_16x16x32_bf16 v[76:79], v[146:149], v[208:211], v[76:79]
	v_mfma_f32_16x16x32_bf16 v[72:75], v[154:157], v[208:211], v[72:75]
	s_setprio 0
	s_setprio 1
	v_mfma_f32_16x16x32_bf16 v[116:119], v[164:167], v[180:183], v[116:119]
	v_mfma_f32_16x16x32_bf16 v[112:115], v[172:175], v[180:183], v[112:115]
	v_mfma_f32_16x16x32_bf16 v[100:103], v[164:167], v[188:191], v[100:103]
	v_mfma_f32_16x16x32_bf16 v[96:99], v[172:175], v[188:191], v[96:99]
	v_mfma_f32_16x16x32_bf16 v[84:87], v[164:167], v[196:199], v[84:87]
	v_mfma_f32_16x16x32_bf16 v[80:83], v[172:175], v[196:199], v[80:83]
	v_mfma_f32_16x16x32_bf16 v[68:71], v[164:167], v[204:207], v[68:71]
	v_mfma_f32_16x16x32_bf16 v[64:67], v[172:175], v[204:207], v[64:67]
	v_mfma_f32_16x16x32_bf16 v[116:119], v[168:171], v[184:187], v[116:119]
	v_mfma_f32_16x16x32_bf16 v[112:115], v[176:179], v[184:187], v[112:115]
	v_mfma_f32_16x16x32_bf16 v[100:103], v[168:171], v[192:195], v[100:103]
	v_mfma_f32_16x16x32_bf16 v[96:99], v[176:179], v[192:195], v[96:99]
	v_mfma_f32_16x16x32_bf16 v[84:87], v[168:171], v[200:203], v[84:87]
	v_mfma_f32_16x16x32_bf16 v[80:83], v[176:179], v[200:203], v[80:83]
	v_mfma_f32_16x16x32_bf16 v[68:71], v[168:171], v[208:211], v[68:71]
	v_mfma_f32_16x16x32_bf16 v[64:67], v[176:179], v[208:211], v[64:67]
	s_setprio 0
	s_barrier
; #define PG8_STAGE(bufoff, gbase, voff) do { _Pragma("unroll") for (int _i = 0; _i < 2; ++_i) \
;         __builtin_amdgcn_global_load_lds((const unsigned*)((const char*)(gbase) + (voff)[_i]), (LAS unsigned*)(lds + (bufoff) + ldsw + _i * 8192), 16, 0, 0); } while (0)
; #define PG8_LDA(dst, b, h) do { _Pragma("unroll") for (int m = 0; m < 4; ++m) _Pragma("unroll") for (int k = 0; k < 2; ++k) dst[m][k] = *(const LAS bf16x8*)(lds + PG8_SA(b, h) + aoff + m * 2048 + k * 1024); } while (0)
; #define PG8_MMA(ai, bj, At, Bt) do { __builtin_amdgcn_s_setprio(1); _Pragma("unroll") for (int m = 0; m < 4; ++m) _Pragma("unroll") for (int n = 0; n < 2; ++n) _Pragma("unroll") for (int k = 0; k < 2; ++k) \
;         acc[ai][bj][m][n] = __builtin_amdgcn_mfma_f32_16x16x32_bf16(Bt[n][k], At[m][k], acc[ai][bj][m][n], 0, 0, 0); __builtin_amdgcn_s_setprio(0); } while (0)
; #define PG8_WAIT_V(n) asm volatile("s_waitcnt vmcnt(" #n ")" ::: "memory")
; #define PG8_WAIT_L(n) asm volatile("s_waitcnt lgkmcnt(" #n ")" ::: "memory")
; #define PG8_BAR __builtin_amdgcn_s_barrier()
; #define PG8_SCHED __builtin_amdgcn_sched_barrier(0)
; template <class Epi, class Sched>
; __device__ __forceinline__ void gemm_phase(LAS unsigned char* lds, const Gemm g, const Sched& S, const Epi& E, int wave_id) {
;     ...
;             PG8_LDA(At, 1, 1); PG8_STAGE(PG8_SB(1, 0), b3, voffB); PG8_STAGE(PG8_SB(1, 1), b3 + hstepB, voffB); PG8_STAGE(PG8_SA(1, 0), a3, voffA);
;             PG8_WAIT_V(8); PG8_WAIT_L(0); PG8_BAR; PG8_MMA(1, 0, At, B0); PG8_MMA(1, 1, At, B1); PG8_BAR; PG8_SCHED;
;         }
	s_add_i32 s38, s66, s46
	v_lshl_add_u64 v[212:213], v[212:213], 0, s[6:7]
	s_mov_b32 m0, s38
	ds_read_b128 v[180:183], v163 offset:49152
	ds_read_b128 v[184:187], v163 offset:50176
	ds_read_b128 v[188:191], v163 offset:51200
	ds_read_b128 v[192:195], v163 offset:52224
	ds_read_b128 v[196:199], v163 offset:53248
	ds_read_b128 v[200:203], v163 offset:54272
	ds_read_b128 v[204:207], v163 offset:55296
	ds_read_b128 v[208:211], v163 offset:56320
	global_load_lds_dwordx4 v[212:213], off
	s_add_i32 m0, s38, 0x2000
	s_add_u32 s36, s36, 0x40080
	v_lshl_add_u64 v[212:213], v[214:215], 0, s[6:7]
	s_addc_u32 s37, s37, 0
	s_add_i32 s38, s67, s46
	global_load_lds_dwordx4 v[212:213], off
	v_lshl_add_u64 v[212:213], s[36:37], 0, v[130:131]
	s_mov_b32 m0, s38
	s_nop 0
	global_load_lds_dwordx4 v[212:213], off
	v_lshl_add_u64 v[212:213], s[36:37], 0, v[134:135]
	s_add_i32 m0, s38, 0x2000
	s_nop 0
	global_load_lds_dwordx4 v[212:213], off
	v_lshl_add_u64 v[212:213], v[216:217], 0, s[6:7]
	s_mov_b32 m0, s52
	s_nop 0
	global_load_lds_dwordx4 v[212:213], off
	v_lshl_add_u64 v[212:213], v[218:219], 0, s[6:7]
	s_mov_b32 m0, s53
	s_nop 0
	global_load_lds_dwordx4 v[212:213], off
	s_waitcnt vmcnt(8)
	s_waitcnt lgkmcnt(0)
	s_barrier
	s_setprio 1
	s_waitcnt lgkmcnt(0)
	v_mfma_f32_16x16x32_bf16 v[60:63], v[142:145], v[180:183], v[60:63]
	v_mfma_f32_16x16x32_bf16 v[56:59], v[150:153], v[180:183], v[56:59]
	v_mfma_f32_16x16x32_bf16 v[44:47], v[142:145], v[188:191], v[44:47]
	v_mfma_f32_16x16x32_bf16 v[40:43], v[150:153], v[188:191], v[40:43]
	v_mfma_f32_16x16x32_bf16 v[28:31], v[142:145], v[196:199], v[28:31]
	v_mfma_f32_16x16x32_bf16 v[24:27], v[150:153], v[196:199], v[24:27]
	v_mfma_f32_16x16x32_bf16 v[12:15], v[142:145], v[204:207], v[12:15]
	v_mfma_f32_16x16x32_bf16 v[8:11], v[150:153], v[204:207], v[8:11]
	v_mfma_f32_16x16x32_bf16 v[60:63], v[146:149], v[184:187], v[60:63]
	v_mfma_f32_16x16x32_bf16 v[56:59], v[154:157], v[184:187], v[56:59]
	v_mfma_f32_16x16x32_bf16 v[44:47], v[146:149], v[192:195], v[44:47]
	v_mfma_f32_16x16x32_bf16 v[40:43], v[154:157], v[192:195], v[40:43]
	v_mfma_f32_16x16x32_bf16 v[28:31], v[146:149], v[200:203], v[28:31]
	v_mfma_f32_16x16x32_bf16 v[24:27], v[154:157], v[200:203], v[24:27]
	v_mfma_f32_16x16x32_bf16 v[12:15], v[146:149], v[208:211], v[12:15]
	v_mfma_f32_16x16x32_bf16 v[8:11], v[154:157], v[208:211], v[8:11]
	s_setprio 0
	s_setprio 1
	v_mfma_f32_16x16x32_bf16 v[52:55], v[164:167], v[180:183], v[52:55]
	v_mfma_f32_16x16x32_bf16 v[48:51], v[172:175], v[180:183], v[48:51]
	v_mfma_f32_16x16x32_bf16 v[36:39], v[164:167], v[188:191], v[36:39]
	v_mfma_f32_16x16x32_bf16 v[32:35], v[172:175], v[188:191], v[32:35]
	v_mfma_f32_16x16x32_bf16 v[20:23], v[164:167], v[196:199], v[20:23]
	v_mfma_f32_16x16x32_bf16 v[16:19], v[172:175], v[196:199], v[16:19]
	v_mfma_f32_16x16x32_bf16 v[4:7], v[164:167], v[204:207], v[4:7]
	v_mfma_f32_16x16x32_bf16 v[0:3], v[172:175], v[204:207], v[0:3]
	v_mfma_f32_16x16x32_bf16 v[52:55], v[168:171], v[184:187], v[52:55]
	v_mfma_f32_16x16x32_bf16 v[48:51], v[176:179], v[184:187], v[48:51]
	v_mfma_f32_16x16x32_bf16 v[36:39], v[168:171], v[192:195], v[36:39]
	v_mfma_f32_16x16x32_bf16 v[32:35], v[176:179], v[192:195], v[32:35]
	v_mfma_f32_16x16x32_bf16 v[20:23], v[168:171], v[200:203], v[20:23]
	v_mfma_f32_16x16x32_bf16 v[16:19], v[176:179], v[200:203], v[16:19]
	v_mfma_f32_16x16x32_bf16 v[4:7], v[168:171], v[208:211], v[4:7]
	v_mfma_f32_16x16x32_bf16 v[0:3], v[176:179], v[208:211], v[0:3]
	s_setprio 0
	s_barrier
	s_add_i32 s65, s65, 2
	s_add_u32 s34, s34, 0x100
	s_addc_u32 s35, s35, 0
	s_add_u32 s63, s63, 0x100
	s_addc_u32 s64, s64, 0
	s_cmp_gt_u32 s65, 13

;     __device__ bool next(int i, Unit& u) const { if (r0 + i >= r1) return false; return base.next(r0 + i, u); }
;     __device__ bool next(int i, Unit& u) const { const int L = i * G + c; if (L >= 256) return false; u.pm = L; u.pn = L >> 3; return true; }
; #define PG8_STAGE(bufoff, gbase, voff) do { _Pragma("unroll") for (int _i = 0; _i < 2; ++_i) \
;         __builtin_amdgcn_global_load_lds((const unsigned*)((const char*)(gbase) + (voff)[_i]), (LAS unsigned*)(lds + (bufoff) + ldsw + _i * 8192), 16, 0, 0); } while (0)
; #define PG8_LDA(dst, b, h) do { _Pragma("unroll") for (int m = 0; m < 4; ++m) _Pragma("unroll") for (int k = 0; k < 2; ++k) dst[m][k] = *(const LAS bf16x8*)(lds + PG8_SA(b, h) + aoff + m * 2048 + k * 1024); } while (0)
; #define PG8_LDB(dst, b, h) do { _Pragma("unroll") for (int n = 0; n < 2; ++n) _Pragma("unroll") for (int k = 0; k < 2; ++k) dst[n][k] = *(const LAS bf16x8*)(lds + PG8_SB(b, h) + boff + n * 2048 + k * 1024); } while (0)
; template <class Epi, class Sched>
; __device__ __forceinline__ void gemm_phase(LAS unsigned char* lds, const Gemm g, const Sched& S, const Epi& E, int wave_id) {
;     ...
;         const bool has_next = S.next(ui + 1, nxt);
;         const char* nA = has_next ? (const char*)g.A + (size_t)nxt.pm * tstepA : cA; const char* nB = has_next ? (const char*)g.Bt + (size_t)nxt.pn * tstepB : cB;
;         for (int t = 0; t < nt; t += 2) {
;             const bool last = (t == nt - 2);
;             const char* a1 = cA + (size_t)(t + 1) * kstep;
;             const char* a2 = last ? nA : cA + (size_t)(t + 2) * kstep; const char* b2 = last ? nB : cB + (size_t)(t + 2) * kstep;
;             const char* a3 = a2 + kstep; const char* b3 = b2 + kstep;
;             PG8_LDB(B0, 0, 0); PG8_LDB(B1, 0, 1); PG8_SCHED; PG8_LDA(At, 0, 0); PG8_STAGE(PG8_SA(1, 1), a1 + hstepA, voffA);
;             PG8_WAIT_V(8); PG8_WAIT_L(0); PG8_BAR; PG8_MMA(0, 0, At, B0); PG8_MMA(0, 1, At, B1); PG8_BAR; PG8_SCHED;
;             PG8_LDA(At, 0, 1); PG8_STAGE(PG8_SB(0, 0), b2, voffB); PG8_STAGE(PG8_SB(0, 1), b2 + hstepB, voffB); PG8_STAGE(PG8_SA(0, 0), a2, voffA);
;     ...
;         for (int a = 0; a < 2; ++a)
; #pragma unroll
;             for (int b = 0; b < 2; ++b)
; #pragma unroll
;                 for (int m = 0; m < 4; ++m)
; #pragma unroll
;                     for (int n = 0; n < 2; ++n) acc[a][b][m][n] = (f32x4){0.f, 0.f, 0.f, 0.f};
.LBB0_727:
	s_ashr_i32 s21, s20, 31
	s_lshl_b64 s[24:25], s[20:21], 19
	s_add_u32 s24, s15, s24
	s_addc_u32 s25, s33, s25
	s_and_b64 s[26:27], s[22:23], exec
	s_cselect_b32 s21, s25, s31
	s_cselect_b32 s59, s24, s30
	s_ashr_i32 s17, s16, 31
	s_lshl_b64 s[26:27], s[16:17], 19
	s_add_u32 s26, s38, s26
	s_addc_u32 s27, s39, s27
	s_and_b64 s[36:37], s[22:23], exec
	s_cselect_b32 s17, s27, s35
	s_cselect_b32 s60, s26, s34
	s_add_u32 s30, s30, 0x40080
	s_addc_u32 s31, s31, 0
	s_add_u32 s61, s34, 0x100
	s_addc_u32 s62, s35, 0
	s_mov_b32 s63, -2
	s_waitcnt vmcnt(0)
	ds_read_b128 v[142:145], v161
	ds_read_b128 v[146:149], v161 offset:1024
	ds_read_b128 v[150:153], v161 offset:2048
	ds_read_b128 v[154:157], v161 offset:3072
	ds_read_b128 v[164:167], v162
	ds_read_b128 v[168:171], v162 offset:1024
	ds_read_b128 v[172:175], v162 offset:2048
	ds_read_b128 v[176:179], v162 offset:3072
	s_add_u32 s34, s30, 0xfffc0080
	s_addc_u32 s35, s31, -1
	s_cmp_eq_u32 s63, 12
	s_cselect_b32 s37, s21, s35
	s_cselect_b32 s36, s59, s34
	s_cselect_b32 s35, s17, s62
	s_cselect_b32 s34, s60, s61
	v_lshl_add_u64 v[212:213], s[30:31], 0, v[136:137]
	s_add_i32 m0, s29, 0xc000
	ds_read_b128 v[180:183], v163
	ds_read_b128 v[184:187], v163 offset:1024
	ds_read_b128 v[188:191], v163 offset:2048
	ds_read_b128 v[192:195], v163 offset:3072
	ds_read_b128 v[196:199], v163 offset:4096
	ds_read_b128 v[200:203], v163 offset:5120
	ds_read_b128 v[204:207], v163 offset:6144
	ds_read_b128 v[208:211], v163 offset:7168
	global_load_lds_dwordx4 v[212:213], off
	v_lshl_add_u64 v[212:213], s[30:31], 0, v[138:139]
	s_add_i32 m0, s29, 0xe000
	s_nop 0
	global_load_lds_dwordx4 v[212:213], off
	s_waitcnt vmcnt(8)
	s_waitcnt lgkmcnt(0)
	s_barrier
	s_setprio 1
	s_waitcnt lgkmcnt(0)
	v_mfma_f32_16x16x32_bf16 v[124:127], v[142:145], v[180:183], 0
	v_mfma_f32_16x16x32_bf16 v[120:123], v[150:153], v[180:183], 0
	v_mfma_f32_16x16x32_bf16 v[108:111], v[142:145], v[188:191], 0
	v_mfma_f32_16x16x32_bf16 v[104:107], v[150:153], v[188:191], 0
	v_mfma_f32_16x16x32_bf16 v[92:95], v[142:145], v[196:199], 0
	v_mfma_f32_16x16x32_bf16 v[88:91], v[150:153], v[196:199], 0
	v_mfma_f32_16x16x32_bf16 v[76:79], v[142:145], v[204:207], 0
	v_mfma_f32_16x16x32_bf16 v[72:75], v[150:153], v[204:207], 0
	v_mfma_f32_16x16x32_bf16 v[124:127], v[146:149], v[184:187], v[124:127]
	v_mfma_f32_16x16x32_bf16 v[120:123], v[154:157], v[184:187], v[120:123]
	v_mfma_f32_16x16x32_bf16 v[108:111], v[146:149], v[192:195], v[108:111]
	v_mfma_f32_16x16x32_bf16 v[104:107], v[154:157], v[192:195], v[104:107]
	v_mfma_f32_16x16x32_bf16 v[92:95], v[146:149], v[200:203], v[92:95]
	v_mfma_f32_16x16x32_bf16 v[88:91], v[154:157], v[200:203], v[88:91]
	v_mfma_f32_16x16x32_bf16 v[76:79], v[146:149], v[208:211], v[76:79]
	v_mfma_f32_16x16x32_bf16 v[72:75], v[154:157], v[208:211], v[72:75]
	s_setprio 0
	s_setprio 1
	v_mfma_f32_16x16x32_bf16 v[116:119], v[164:167], v[180:183], 0
	v_mfma_f32_16x16x32_bf16 v[112:115], v[172:175], v[180:183], 0
	v_mfma_f32_16x16x32_bf16 v[100:103], v[164:167], v[188:191], 0
	v_mfma_f32_16x16x32_bf16 v[96:99], v[172:175], v[188:191], 0
	v_mfma_f32_16x16x32_bf16 v[84:87], v[164:167], v[196:199], 0
	v_mfma_f32_16x16x32_bf16 v[80:83], v[172:175], v[196:199], 0
	v_mfma_f32_16x16x32_bf16 v[68:71], v[164:167], v[204:207], 0
	v_mfma_f32_16x16x32_bf16 v[64:67], v[172:175], v[204:207], 0
	v_mfma_f32_16x16x32_bf16 v[116:119], v[168:171], v[184:187], v[116:119]
	v_mfma_f32_16x16x32_bf16 v[112:115], v[176:179], v[184:187], v[112:115]
	v_mfma_f32_16x16x32_bf16 v[100:103], v[168:171], v[192:195], v[100:103]
	v_mfma_f32_16x16x32_bf16 v[96:99], v[176:179], v[192:195], v[96:99]
	v_mfma_f32_16x16x32_bf16 v[84:87], v[168:171], v[200:203], v[84:87]
	v_mfma_f32_16x16x32_bf16 v[80:83], v[176:179], v[200:203], v[80:83]
	v_mfma_f32_16x16x32_bf16 v[68:71], v[168:171], v[208:211], v[68:71]
	v_mfma_f32_16x16x32_bf16 v[64:67], v[176:179], v[208:211], v[64:67]
	s_setprio 0
	s_barrier
	s_add_i32 s64, s53, s44
	v_lshl_add_u64 v[212:213], s[34:35], 0, v[130:131]
	s_mov_b32 m0, s64
	ds_read_b128 v[180:183], v163 offset:16384
	ds_read_b128 v[184:187], v163 offset:17408
	ds_read_b128 v[188:191], v163 offset:18432
	ds_read_b128 v[192:195], v163 offset:19456
	ds_read_b128 v[196:199], v163 offset:20480
	ds_read_b128 v[200:203], v163 offset:21504
	ds_read_b128 v[204:207], v163 offset:22528
	ds_read_b128 v[208:211], v163 offset:23552
	global_load_lds_dwordx4 v[212:213], off
	s_add_i32 m0, s64, 0x2000
	s_add_u32 s64, s34, 0x40000
	v_lshl_add_u64 v[214:215], s[34:35], 0, v[134:135]
	s_addc_u32 s65, s35, 0
	s_add_i32 s66, s54, s44
	global_load_lds_dwordx4 v[214:215], off
	v_lshl_add_u64 v[216:217], s[64:65], 0, v[130:131]
	s_mov_b32 m0, s66
	v_lshl_add_u64 v[218:219], s[36:37], 0, v[132:133]
	global_load_lds_dwordx4 v[216:217], off
	v_lshl_add_u64 v[216:217], s[64:65], 0, v[134:135]
	s_add_i32 m0, s66, 0x2000
	s_nop 0
	global_load_lds_dwordx4 v[216:217], off
	v_lshl_add_u64 v[216:217], s[36:37], 0, v[128:129]
	s_mov_b32 m0, s29
	s_nop 0
	global_load_lds_dwordx4 v[216:217], off
	s_mov_b32 m0, s45
	s_nop 0
	global_load_lds_dwordx4 v[218:219], off
	s_waitcnt vmcnt(8)
	s_waitcnt lgkmcnt(0)
	s_barrier
; #define PG8_STAGE(bufoff, gbase, voff) do { _Pragma("unroll") for (int _i = 0; _i < 2; ++_i) \
;         __builtin_amdgcn_global_load_lds((const unsigned*)((const char*)(gbase) + (voff)[_i]), (LAS unsigned*)(lds + (bufoff) + ldsw + _i * 8192), 16, 0, 0); } while (0)
; #define PG8_LDA(dst, b, h) do { _Pragma("unroll") for (int m = 0; m < 4; ++m) _Pragma("unroll") for (int k = 0; k < 2; ++k) dst[m][k] = *(const LAS bf16x8*)(lds + PG8_SA(b, h) + aoff + m * 2048 + k * 1024); } while (0)
; #define PG8_LDB(dst, b, h) do { _Pragma("unroll") for (int n = 0; n < 2; ++n) _Pragma("unroll") for (int k = 0; k < 2; ++k) dst[n][k] = *(const LAS bf16x8*)(lds + PG8_SB(b, h) + boff + n * 2048 + k * 1024); } while (0)
; #define PG8_MMA(ai, bj, At, Bt) do { __builtin_amdgcn_s_setprio(1); _Pragma("unroll") for (int m = 0; m < 4; ++m) _Pragma("unroll") for (int n = 0; n < 2; ++n) _Pragma("unroll") for (int k = 0; k < 2; ++k) \
;         acc[ai][bj][m][n] = __builtin_amdgcn_mfma_f32_16x16x32_bf16(Bt[n][k], At[m][k], acc[ai][bj][m][n], 0, 0, 0); __builtin_amdgcn_s_setprio(0); } while (0)
; #define PG8_WAIT_V(n) asm volatile("s_waitcnt vmcnt(" #n ")" ::: "memory")
; #define PG8_WAIT_L(n) asm volatile("s_waitcnt lgkmcnt(" #n ")" ::: "memory")
; #define PG8_BAR __builtin_amdgcn_s_barrier()
; #define PG8_SCHED __builtin_amdgcn_sched_barrier(0)
; template <class Epi, class Sched>
; __device__ __forceinline__ void gemm_phase(LAS unsigned char* lds, const Gemm g, const Sched& S, const Epi& E, int wave_id) {
;     ...
;             PG8_WAIT_V(8); PG8_WAIT_L(0); PG8_BAR; PG8_MMA(1, 0, At, B0); PG8_MMA(1, 1, At, B1); PG8_BAR; PG8_SCHED;
;             PG8_LDB(B0, 1, 0); PG8_LDB(B1, 1, 1); PG8_SCHED; PG8_LDA(At, 1, 0); PG8_STAGE(PG8_SA(0, 1), a2 + hstepA, voffA);
;             PG8_WAIT_V(8); PG8_WAIT_L(0); PG8_BAR; PG8_MMA(0, 0, At, B0); PG8_MMA(0, 1, At, B1); PG8_BAR; PG8_SCHED;
	s_setprio 1
	s_waitcnt lgkmcnt(0)
	v_mfma_f32_16x16x32_bf16 v[60:63], v[142:145], v[180:183], 0
	v_mfma_f32_16x16x32_bf16 v[56:59], v[150:153], v[180:183], 0
	v_mfma_f32_16x16x32_bf16 v[44:47], v[142:145], v[188:191], 0
	v_mfma_f32_16x16x32_bf16 v[40:43], v[150:153], v[188:191], 0
	v_mfma_f32_16x16x32_bf16 v[28:31], v[142:145], v[196:199], 0
	v_mfma_f32_16x16x32_bf16 v[24:27], v[150:153], v[196:199], 0
	v_mfma_f32_16x16x32_bf16 v[12:15], v[142:145], v[204:207], 0
	v_mfma_f32_16x16x32_bf16 v[8:11], v[150:153], v[204:207], 0
	v_mfma_f32_16x16x32_bf16 v[60:63], v[146:149], v[184:187], v[60:63]
	v_mfma_f32_16x16x32_bf16 v[56:59], v[154:157], v[184:187], v[56:59]
	v_mfma_f32_16x16x32_bf16 v[44:47], v[146:149], v[192:195], v[44:47]
	v_mfma_f32_16x16x32_bf16 v[40:43], v[154:157], v[192:195], v[40:43]
	v_mfma_f32_16x16x32_bf16 v[28:31], v[146:149], v[200:203], v[28:31]
	v_mfma_f32_16x16x32_bf16 v[24:27], v[154:157], v[200:203], v[24:27]
	v_mfma_f32_16x16x32_bf16 v[12:15], v[146:149], v[208:211], v[12:15]
	v_mfma_f32_16x16x32_bf16 v[8:11], v[154:157], v[208:211], v[8:11]
	s_setprio 0
	s_setprio 1
	v_mfma_f32_16x16x32_bf16 v[52:55], v[164:167], v[180:183], 0
	v_mfma_f32_16x16x32_bf16 v[48:51], v[172:175], v[180:183], 0
	v_mfma_f32_16x16x32_bf16 v[36:39], v[164:167], v[188:191], 0
	v_mfma_f32_16x16x32_bf16 v[32:35], v[172:175], v[188:191], 0
	v_mfma_f32_16x16x32_bf16 v[20:23], v[164:167], v[196:199], 0
	v_mfma_f32_16x16x32_bf16 v[16:19], v[172:175], v[196:199], 0
	v_mfma_f32_16x16x32_bf16 v[4:7], v[164:167], v[204:207], 0
	v_mfma_f32_16x16x32_bf16 v[0:3], v[172:175], v[204:207], 0
	v_mfma_f32_16x16x32_bf16 v[52:55], v[168:171], v[184:187], v[52:55]
	v_mfma_f32_16x16x32_bf16 v[48:51], v[176:179], v[184:187], v[48:51]
	v_mfma_f32_16x16x32_bf16 v[36:39], v[168:171], v[192:195], v[36:39]
	v_mfma_f32_16x16x32_bf16 v[32:35], v[176:179], v[192:195], v[32:35]
	v_mfma_f32_16x16x32_bf16 v[20:23], v[168:171], v[200:203], v[20:23]
	v_mfma_f32_16x16x32_bf16 v[16:19], v[176:179], v[200:203], v[16:19]
	v_mfma_f32_16x16x32_bf16 v[4:7], v[168:171], v[208:211], v[4:7]
	v_mfma_f32_16x16x32_bf16 v[0:3], v[176:179], v[208:211], v[0:3]
	s_setprio 0
	s_barrier
	s_add_i32 s64, 0, 0x18000
	s_add_i32 s65, 0, 0x1c000
	v_add_u32_e32 v154, s64, v159
	v_add_u32_e32 v176, s65, v159
	ds_read_b128 v[142:145], v154
	ds_read_b128 v[146:149], v154 offset:1024
	ds_read_b128 v[150:153], v154 offset:2048
	ds_read_b128 v[154:157], v154 offset:3072
	ds_read_b128 v[164:167], v176
	ds_read_b128 v[168:171], v176 offset:1024
	ds_read_b128 v[172:175], v176 offset:2048
	ds_read_b128 v[176:179], v176 offset:3072
	s_add_u32 s36, s36, 0x40000
	s_addc_u32 s37, s37, 0
	s_mov_b32 m0, s46
	v_lshl_add_u64 v[220:221], s[36:37], 0, v[128:129]
	ds_read_b128 v[180:183], v163 offset:32768
	ds_read_b128 v[184:187], v163 offset:33792
	ds_read_b128 v[188:191], v163 offset:34816
	ds_read_b128 v[192:195], v163 offset:35840
	ds_read_b128 v[196:199], v163 offset:36864
	ds_read_b128 v[200:203], v163 offset:37888
	ds_read_b128 v[204:207], v163 offset:38912
	ds_read_b128 v[208:211], v163 offset:39936
	global_load_lds_dwordx4 v[220:221], off
	v_lshl_add_u64 v[220:221], s[36:37], 0, v[132:133]
	s_mov_b32 m0, s47
	s_nop 0
	global_load_lds_dwordx4 v[220:221], off
	s_waitcnt vmcnt(8)
	s_waitcnt lgkmcnt(0)
	s_barrier
	s_setprio 1
	s_waitcnt lgkmcnt(0)
	v_mfma_f32_16x16x32_bf16 v[124:127], v[142:145], v[180:183], v[124:127]
	v_mfma_f32_16x16x32_bf16 v[120:123], v[150:153], v[180:183], v[120:123]
	v_mfma_f32_16x16x32_bf16 v[108:111], v[142:145], v[188:191], v[108:111]
	v_mfma_f32_16x16x32_bf16 v[104:107], v[150:153], v[188:191], v[104:107]
	v_mfma_f32_16x16x32_bf16 v[92:95], v[142:145], v[196:199], v[92:95]
	v_mfma_f32_16x16x32_bf16 v[88:91], v[150:153], v[196:199], v[88:91]
	v_mfma_f32_16x16x32_bf16 v[76:79], v[142:145], v[204:207], v[76:79]
	v_mfma_f32_16x16x32_bf16 v[72:75], v[150:153], v[204:207], v[72:75]
	v_mfma_f32_16x16x32_bf16 v[124:127], v[146:149], v[184:187], v[124:127]
	v_mfma_f32_16x16x32_bf16 v[120:123], v[154:157], v[184:187], v[120:123]
	v_mfma_f32_16x16x32_bf16 v[108:111], v[146:149], v[192:195], v[108:111]
	v_mfma_f32_16x16x32_bf16 v[104:107], v[154:157], v[192:195], v[104:107]
	v_mfma_f32_16x16x32_bf16 v[92:95], v[146:149], v[200:203], v[92:95]
	v_mfma_f32_16x16x32_bf16 v[88:91], v[154:157], v[200:203], v[88:91]
	v_mfma_f32_16x16x32_bf16 v[76:79], v[146:149], v[208:211], v[76:79]
	v_mfma_f32_16x16x32_bf16 v[72:75], v[154:157], v[208:211], v[72:75]
	s_setprio 0
	s_setprio 1
	v_mfma_f32_16x16x32_bf16 v[116:119], v[164:167], v[180:183], v[116:119]
	v_mfma_f32_16x16x32_bf16 v[112:115], v[172:175], v[180:183], v[112:115]
	v_mfma_f32_16x16x32_bf16 v[100:103], v[164:167], v[188:191], v[100:103]
	v_mfma_f32_16x16x32_bf16 v[96:99], v[172:175], v[188:191], v[96:99]
	v_mfma_f32_16x16x32_bf16 v[84:87], v[164:167], v[196:199], v[84:87]
	v_mfma_f32_16x16x32_bf16 v[80:83], v[172:175], v[196:199], v[80:83]
	v_mfma_f32_16x16x32_bf16 v[68:71], v[164:167], v[204:207], v[68:71]
	v_mfma_f32_16x16x32_bf16 v[64:67], v[172:175], v[204:207], v[64:67]
	v_mfma_f32_16x16x32_bf16 v[116:119], v[168:171], v[184:187], v[116:119]
	v_mfma_f32_16x16x32_bf16 v[112:115], v[176:179], v[184:187], v[112:115]
	v_mfma_f32_16x16x32_bf16 v[100:103], v[168:171], v[192:195], v[100:103]
	v_mfma_f32_16x16x32_bf16 v[96:99], v[176:179], v[192:195], v[96:99]
	v_mfma_f32_16x16x32_bf16 v[84:87], v[168:171], v[200:203], v[84:87]
	v_mfma_f32_16x16x32_bf16 v[80:83], v[176:179], v[200:203], v[80:83]
	v_mfma_f32_16x16x32_bf16 v[68:71], v[168:171], v[208:211], v[68:71]
	v_mfma_f32_16x16x32_bf16 v[64:67], v[176:179], v[208:211], v[64:67]
	s_setprio 0
	s_barrier
; #define PG8_STAGE(bufoff, gbase, voff) do { _Pragma("unroll") for (int _i = 0; _i < 2; ++_i) \
;         __builtin_amdgcn_global_load_lds((const unsigned*)((const char*)(gbase) + (voff)[_i]), (LAS unsigned*)(lds + (bufoff) + ldsw + _i * 8192), 16, 0, 0); } while (0)
; #define PG8_LDA(dst, b, h) do { _Pragma("unroll") for (int m = 0; m < 4; ++m) _Pragma("unroll") for (int k = 0; k < 2; ++k) dst[m][k] = *(const LAS bf16x8*)(lds + PG8_SA(b, h) + aoff + m * 2048 + k * 1024); } while (0)
; #define PG8_MMA(ai, bj, At, Bt) do { __builtin_amdgcn_s_setprio(1); _Pragma("unroll") for (int m = 0; m < 4; ++m) _Pragma("unroll") for (int n = 0; n < 2; ++n) _Pragma("unroll") for (int k = 0; k < 2; ++k) \
;         acc[ai][bj][m][n] = __builtin_amdgcn_mfma_f32_16x16x32_bf16(Bt[n][k], At[m][k], acc[ai][bj][m][n], 0, 0, 0); __builtin_amdgcn_s_setprio(0); } while (0)
; #define PG8_WAIT_V(n) asm volatile("s_waitcnt vmcnt(" #n ")" ::: "memory")
; #define PG8_WAIT_L(n) asm volatile("s_waitcnt lgkmcnt(" #n ")" ::: "memory")
; #define PG8_BAR __builtin_amdgcn_s_barrier()
; #define PG8_SCHED __builtin_amdgcn_sched_barrier(0)
; template <class Epi, class Sched>
; __device__ __forceinline__ void gemm_phase(LAS unsigned char* lds, const Gemm g, const Sched& S, const Epi& E, int wave_id) {
;     ...
;             PG8_LDA(At, 1, 1); PG8_STAGE(PG8_SB(1, 0), b3, voffB); PG8_STAGE(PG8_SB(1, 1), b3 + hstepB, voffB); PG8_STAGE(PG8_SA(1, 0), a3, voffA);
;             PG8_WAIT_V(8); PG8_WAIT_L(0); PG8_BAR; PG8_MMA(1, 0, At, B0); PG8_MMA(1, 1, At, B1); PG8_BAR; PG8_SCHED;
;         }
	s_add_i32 s36, s64, s44
	v_lshl_add_u64 v[212:213], v[212:213], 0, s[6:7]
	s_mov_b32 m0, s36
	ds_read_b128 v[180:183], v163 offset:49152
	ds_read_b128 v[184:187], v163 offset:50176
	ds_read_b128 v[188:191], v163 offset:51200
	ds_read_b128 v[192:195], v163 offset:52224
	ds_read_b128 v[196:199], v163 offset:53248
	ds_read_b128 v[200:203], v163 offset:54272
	ds_read_b128 v[204:207], v163 offset:55296
	ds_read_b128 v[208:211], v163 offset:56320
	global_load_lds_dwordx4 v[212:213], off
	s_add_i32 m0, s36, 0x2000
	s_add_u32 s34, s34, 0x40080
	v_lshl_add_u64 v[212:213], v[214:215], 0, s[6:7]
	s_addc_u32 s35, s35, 0
	s_add_i32 s36, s65, s44
	global_load_lds_dwordx4 v[212:213], off
	v_lshl_add_u64 v[212:213], s[34:35], 0, v[130:131]
	s_mov_b32 m0, s36
	s_nop 0
	global_load_lds_dwordx4 v[212:213], off
	v_lshl_add_u64 v[212:213], s[34:35], 0, v[134:135]
	s_add_i32 m0, s36, 0x2000
	s_nop 0
	global_load_lds_dwordx4 v[212:213], off
	v_lshl_add_u64 v[212:213], v[216:217], 0, s[6:7]
	s_mov_b32 m0, s50
	s_nop 0
	global_load_lds_dwordx4 v[212:213], off
	v_lshl_add_u64 v[212:213], v[218:219], 0, s[6:7]
	s_mov_b32 m0, s51
	s_nop 0
	global_load_lds_dwordx4 v[212:213], off
	s_waitcnt vmcnt(8)
	s_waitcnt lgkmcnt(0)
	s_barrier
	s_setprio 1
	s_waitcnt lgkmcnt(0)
	v_mfma_f32_16x16x32_bf16 v[60:63], v[142:145], v[180:183], v[60:63]
	v_mfma_f32_16x16x32_bf16 v[56:59], v[150:153], v[180:183], v[56:59]
	v_mfma_f32_16x16x32_bf16 v[44:47], v[142:145], v[188:191], v[44:47]
	v_mfma_f32_16x16x32_bf16 v[40:43], v[150:153], v[188:191], v[40:43]
	v_mfma_f32_16x16x32_bf16 v[28:31], v[142:145], v[196:199], v[28:31]
	v_mfma_f32_16x16x32_bf16 v[24:27], v[150:153], v[196:199], v[24:27]
	v_mfma_f32_16x16x32_bf16 v[12:15], v[142:145], v[204:207], v[12:15]
	v_mfma_f32_16x16x32_bf16 v[8:11], v[150:153], v[204:207], v[8:11]
	v_mfma_f32_16x16x32_bf16 v[60:63], v[146:149], v[184:187], v[60:63]
	v_mfma_f32_16x16x32_bf16 v[56:59], v[154:157], v[184:187], v[56:59]
	v_mfma_f32_16x16x32_bf16 v[44:47], v[146:149], v[192:195], v[44:47]
	v_mfma_f32_16x16x32_bf16 v[40:43], v[154:157], v[192:195], v[40:43]
	v_mfma_f32_16x16x32_bf16 v[28:31], v[146:149], v[200:203], v[28:31]
	v_mfma_f32_16x16x32_bf16 v[24:27], v[154:157], v[200:203], v[24:27]
	v_mfma_f32_16x16x32_bf16 v[12:15], v[146:149], v[208:211], v[12:15]
	v_mfma_f32_16x16x32_bf16 v[8:11], v[154:157], v[208:211], v[8:11]
	s_setprio 0
	s_setprio 1
	v_mfma_f32_16x16x32_bf16 v[52:55], v[164:167], v[180:183], v[52:55]
	v_mfma_f32_16x16x32_bf16 v[48:51], v[172:175], v[180:183], v[48:51]
	v_mfma_f32_16x16x32_bf16 v[36:39], v[164:167], v[188:191], v[36:39]
	v_mfma_f32_16x16x32_bf16 v[32:35], v[172:175], v[188:191], v[32:35]
	v_mfma_f32_16x16x32_bf16 v[20:23], v[164:167], v[196:199], v[20:23]
	v_mfma_f32_16x16x32_bf16 v[16:19], v[172:175], v[196:199], v[16:19]
	v_mfma_f32_16x16x32_bf16 v[4:7], v[164:167], v[204:207], v[4:7]
	v_mfma_f32_16x16x32_bf16 v[0:3], v[172:175], v[204:207], v[0:3]
	v_mfma_f32_16x16x32_bf16 v[52:55], v[168:171], v[184:187], v[52:55]
	v_mfma_f32_16x16x32_bf16 v[48:51], v[176:179], v[184:187], v[48:51]
	v_mfma_f32_16x16x32_bf16 v[36:39], v[168:171], v[192:195], v[36:39]
	v_mfma_f32_16x16x32_bf16 v[32:35], v[176:179], v[192:195], v[32:35]
	v_mfma_f32_16x16x32_bf16 v[20:23], v[168:171], v[200:203], v[20:23]
	v_mfma_f32_16x16x32_bf16 v[16:19], v[176:179], v[200:203], v[16:19]
	v_mfma_f32_16x16x32_bf16 v[4:7], v[168:171], v[208:211], v[4:7]
	v_mfma_f32_16x16x32_bf16 v[0:3], v[176:179], v[208:211], v[0:3]
	s_setprio 0
	s_barrier
	s_add_i32 s63, s63, 2
	s_add_u32 s30, s30, 0x100
	s_addc_u32 s31, s31, 0
	s_add_u32 s61, s61, 0x100
	s_addc_u32 s62, s62, 0
	s_cmp_gt_u32 s63, 13

;     __device__ bool next(int i, Unit& u) const { if (r0 + i >= r1) return false; return base.next(r0 + i, u); }
;     __device__ bool next(int i, Unit& u) const { const int L = i * G + c; if (L >= 256) return false; u.pm = L; u.pn = L >> 3; return true; }
; #define PG8_STAGE(bufoff, gbase, voff) do { _Pragma("unroll") for (int _i = 0; _i < 2; ++_i) \
;         __builtin_amdgcn_global_load_lds((const unsigned*)((const char*)(gbase) + (voff)[_i]), (LAS unsigned*)(lds + (bufoff) + ldsw + _i * 8192), 16, 0, 0); } while (0)
; #define PG8_LDA(dst, b, h) do { _Pragma("unroll") for (int m = 0; m < 4; ++m) _Pragma("unroll") for (int k = 0; k < 2; ++k) dst[m][k] = *(const LAS bf16x8*)(lds + PG8_SA(b, h) + aoff + m * 2048 + k * 1024); } while (0)
; #define PG8_LDB(dst, b, h) do { _Pragma("unroll") for (int n = 0; n < 2; ++n) _Pragma("unroll") for (int k = 0; k < 2; ++k) dst[n][k] = *(const LAS bf16x8*)(lds + PG8_SB(b, h) + boff + n * 2048 + k * 1024); } while (0)
; template <class Epi, class Sched>
; __device__ __forceinline__ void gemm_phase(LAS unsigned char* lds, const Gemm g, const Sched& S, const Epi& E, int wave_id) {
;     ...
;         const bool has_next = S.next(ui + 1, nxt);
;         const char* nA = has_next ? (const char*)g.A + (size_t)nxt.pm * tstepA : cA; const char* nB = has_next ? (const char*)g.Bt + (size_t)nxt.pn * tstepB : cB;
;         for (int t = 0; t < nt; t += 2) {
;             const bool last = (t == nt - 2);
;             const char* a1 = cA + (size_t)(t + 1) * kstep;
;             const char* a2 = last ? nA : cA + (size_t)(t + 2) * kstep; const char* b2 = last ? nB : cB + (size_t)(t + 2) * kstep;
;             const char* a3 = a2 + kstep; const char* b3 = b2 + kstep;
;             PG8_LDB(B0, 0, 0); PG8_LDB(B1, 0, 1); PG8_SCHED; PG8_LDA(At, 0, 0); PG8_STAGE(PG8_SA(1, 1), a1 + hstepA, voffA);
;             PG8_WAIT_V(8); PG8_WAIT_L(0); PG8_BAR; PG8_MMA(0, 0, At, B0); PG8_MMA(0, 1, At, B1); PG8_BAR; PG8_SCHED;
;             PG8_LDA(At, 0, 1); PG8_STAGE(PG8_SB(0, 0), b2, voffB); PG8_STAGE(PG8_SB(0, 1), b2 + hstepB, voffB); PG8_STAGE(PG8_SA(0, 0), a2, voffA);
;     ...
;         for (int a = 0; a < 2; ++a)
; #pragma unroll
;             for (int b = 0; b < 2; ++b)
; #pragma unroll
;                 for (int m = 0; m < 4; ++m)
; #pragma unroll
;                     for (int n = 0; n < 2; ++n) acc[a][b][m][n] = (f32x4){0.f, 0.f, 0.f, 0.f};
.LBB0_803:
	s_ashr_i32 s19, s18, 31
	s_andn2_b64 vcc, exec, s[36:37]
	s_lshl_b64 s[22:23], s[18:19], 19
	s_add_u32 s22, s2, s22
	s_addc_u32 s23, s21, s23
	s_and_b64 s[24:25], s[36:37], exec
	s_cselect_b32 s19, s23, s31
	s_cselect_b32 s51, s22, s30
	s_ashr_i32 s17, s16, 31
	s_lshl_b64 s[24:25], s[16:17], 19
	s_add_u32 s24, s33, s24
	s_addc_u32 s25, s38, s25
	v_cndmask_b32_e64 v0, 0, 1, s[36:37]
	s_and_b64 s[36:37], s[36:37], exec
	s_cselect_b32 s17, s25, s35
	s_cselect_b32 s52, s24, s34
	s_add_u32 s30, s30, 0x40080
	s_addc_u32 s31, s31, 0
	v_cmp_ne_u32_e64 s[4:5], 1, v0
	s_add_u32 s53, s34, 0x100
	s_addc_u32 s54, s35, 0
	s_mov_b32 s55, -2
	s_waitcnt vmcnt(0)
	ds_read_b128 v[140:143], v159
	ds_read_b128 v[144:147], v159 offset:1024
	ds_read_b128 v[148:151], v159 offset:2048
	ds_read_b128 v[152:155], v159 offset:3072
	ds_read_b128 v[162:165], v160
	ds_read_b128 v[166:169], v160 offset:1024
	ds_read_b128 v[170:173], v160 offset:2048
	ds_read_b128 v[174:177], v160 offset:3072
	s_add_u32 s34, s30, 0xfffc0080
	s_addc_u32 s35, s31, -1
	s_cmp_eq_u32 s55, 12
	s_cselect_b32 s37, s19, s35
	s_cselect_b32 s36, s51, s34
	s_cselect_b32 s35, s17, s54
	s_cselect_b32 s34, s52, s53
	v_lshl_add_u64 v[210:211], s[30:31], 0, v[136:137]
	s_add_i32 m0, s27, 0xc000
	ds_read_b128 v[178:181], v161
	ds_read_b128 v[182:185], v161 offset:1024
	ds_read_b128 v[186:189], v161 offset:2048
	ds_read_b128 v[190:193], v161 offset:3072
	ds_read_b128 v[194:197], v161 offset:4096
	ds_read_b128 v[198:201], v161 offset:5120
	ds_read_b128 v[202:205], v161 offset:6144
	ds_read_b128 v[206:209], v161 offset:7168
	global_load_lds_dwordx4 v[210:211], off
	v_lshl_add_u64 v[210:211], s[30:31], 0, v[138:139]
	s_add_i32 m0, s27, 0xe000
	s_nop 0
	global_load_lds_dwordx4 v[210:211], off
	s_waitcnt vmcnt(8)
	s_waitcnt lgkmcnt(0)
	s_barrier
	s_setprio 1
	s_waitcnt lgkmcnt(0)
	v_mfma_f32_16x16x32_bf16 v[124:127], v[140:143], v[178:181], 0
	v_mfma_f32_16x16x32_bf16 v[120:123], v[148:151], v[178:181], 0
	v_mfma_f32_16x16x32_bf16 v[108:111], v[140:143], v[186:189], 0
	v_mfma_f32_16x16x32_bf16 v[104:107], v[148:151], v[186:189], 0
	v_mfma_f32_16x16x32_bf16 v[92:95], v[140:143], v[194:197], 0
	v_mfma_f32_16x16x32_bf16 v[88:91], v[148:151], v[194:197], 0
	v_mfma_f32_16x16x32_bf16 v[76:79], v[140:143], v[202:205], 0
	v_mfma_f32_16x16x32_bf16 v[72:75], v[148:151], v[202:205], 0
	v_mfma_f32_16x16x32_bf16 v[124:127], v[144:147], v[182:185], v[124:127]
	v_mfma_f32_16x16x32_bf16 v[120:123], v[152:155], v[182:185], v[120:123]
	v_mfma_f32_16x16x32_bf16 v[108:111], v[144:147], v[190:193], v[108:111]
	v_mfma_f32_16x16x32_bf16 v[104:107], v[152:155], v[190:193], v[104:107]
	v_mfma_f32_16x16x32_bf16 v[92:95], v[144:147], v[198:201], v[92:95]
	v_mfma_f32_16x16x32_bf16 v[88:91], v[152:155], v[198:201], v[88:91]
	v_mfma_f32_16x16x32_bf16 v[76:79], v[144:147], v[206:209], v[76:79]
	v_mfma_f32_16x16x32_bf16 v[72:75], v[152:155], v[206:209], v[72:75]
	s_setprio 0
	s_setprio 1
	v_mfma_f32_16x16x32_bf16 v[116:119], v[162:165], v[178:181], 0
	v_mfma_f32_16x16x32_bf16 v[112:115], v[170:173], v[178:181], 0
	v_mfma_f32_16x16x32_bf16 v[100:103], v[162:165], v[186:189], 0
	v_mfma_f32_16x16x32_bf16 v[96:99], v[170:173], v[186:189], 0
	v_mfma_f32_16x16x32_bf16 v[84:87], v[162:165], v[194:197], 0
	v_mfma_f32_16x16x32_bf16 v[80:83], v[170:173], v[194:197], 0
	v_mfma_f32_16x16x32_bf16 v[68:71], v[162:165], v[202:205], 0
	v_mfma_f32_16x16x32_bf16 v[64:67], v[170:173], v[202:205], 0
	v_mfma_f32_16x16x32_bf16 v[116:119], v[166:169], v[182:185], v[116:119]
	v_mfma_f32_16x16x32_bf16 v[112:115], v[174:177], v[182:185], v[112:115]
	v_mfma_f32_16x16x32_bf16 v[100:103], v[166:169], v[190:193], v[100:103]
	v_mfma_f32_16x16x32_bf16 v[96:99], v[174:177], v[190:193], v[96:99]
	v_mfma_f32_16x16x32_bf16 v[84:87], v[166:169], v[198:201], v[84:87]
	v_mfma_f32_16x16x32_bf16 v[80:83], v[174:177], v[198:201], v[80:83]
	v_mfma_f32_16x16x32_bf16 v[68:71], v[166:169], v[206:209], v[68:71]
	v_mfma_f32_16x16x32_bf16 v[64:67], v[174:177], v[206:209], v[64:67]
	s_setprio 0
	s_barrier
	s_add_i32 s58, s48, s39
	v_lshl_add_u64 v[210:211], s[34:35], 0, v[130:131]
	s_mov_b32 m0, s58
	ds_read_b128 v[178:181], v161 offset:16384
	ds_read_b128 v[182:185], v161 offset:17408
	ds_read_b128 v[186:189], v161 offset:18432
	ds_read_b128 v[190:193], v161 offset:19456
	ds_read_b128 v[194:197], v161 offset:20480
	ds_read_b128 v[198:201], v161 offset:21504
	ds_read_b128 v[202:205], v161 offset:22528
	ds_read_b128 v[206:209], v161 offset:23552
	global_load_lds_dwordx4 v[210:211], off
	s_add_i32 m0, s58, 0x2000
	s_add_u32 s58, s34, 0x40000
	v_lshl_add_u64 v[212:213], s[34:35], 0, v[134:135]
	s_addc_u32 s59, s35, 0
	s_add_i32 s60, s49, s39
	global_load_lds_dwordx4 v[212:213], off
	v_lshl_add_u64 v[214:215], s[58:59], 0, v[130:131]
	s_mov_b32 m0, s60
	v_lshl_add_u64 v[216:217], s[36:37], 0, v[132:133]
	global_load_lds_dwordx4 v[214:215], off
	v_lshl_add_u64 v[214:215], s[58:59], 0, v[134:135]
	s_add_i32 m0, s60, 0x2000
	s_nop 0
	global_load_lds_dwordx4 v[214:215], off
	v_lshl_add_u64 v[214:215], s[36:37], 0, v[128:129]
	s_mov_b32 m0, s27
	s_nop 0
	global_load_lds_dwordx4 v[214:215], off
	s_mov_b32 m0, s29
	s_nop 0
	global_load_lds_dwordx4 v[216:217], off
	s_waitcnt vmcnt(8)
	s_waitcnt lgkmcnt(0)
	s_barrier
; #define PG8_STAGE(bufoff, gbase, voff) do { _Pragma("unroll") for (int _i = 0; _i < 2; ++_i) \
;         __builtin_amdgcn_global_load_lds((const unsigned*)((const char*)(gbase) + (voff)[_i]), (LAS unsigned*)(lds + (bufoff) + ldsw + _i * 8192), 16, 0, 0); } while (0)
; #define PG8_LDA(dst, b, h) do { _Pragma("unroll") for (int m = 0; m < 4; ++m) _Pragma("unroll") for (int k = 0; k < 2; ++k) dst[m][k] = *(const LAS bf16x8*)(lds + PG8_SA(b, h) + aoff + m * 2048 + k * 1024); } while (0)
; #define PG8_LDB(dst, b, h) do { _Pragma("unroll") for (int n = 0; n < 2; ++n) _Pragma("unroll") for (int k = 0; k < 2; ++k) dst[n][k] = *(const LAS bf16x8*)(lds + PG8_SB(b, h) + boff + n * 2048 + k * 1024); } while (0)
; #define PG8_MMA(ai, bj, At, Bt) do { __builtin_amdgcn_s_setprio(1); _Pragma("unroll") for (int m = 0; m < 4; ++m) _Pragma("unroll") for (int n = 0; n < 2; ++n) _Pragma("unroll") for (int k = 0; k < 2; ++k) \
;         acc[ai][bj][m][n] = __builtin_amdgcn_mfma_f32_16x16x32_bf16(Bt[n][k], At[m][k], acc[ai][bj][m][n], 0, 0, 0); __builtin_amdgcn_s_setprio(0); } while (0)
; #define PG8_WAIT_V(n) asm volatile("s_waitcnt vmcnt(" #n ")" ::: "memory")
; #define PG8_WAIT_L(n) asm volatile("s_waitcnt lgkmcnt(" #n ")" ::: "memory")
; #define PG8_BAR __builtin_amdgcn_s_barrier()
; #define PG8_SCHED __builtin_amdgcn_sched_barrier(0)
; template <class Epi, class Sched>
; __device__ __forceinline__ void gemm_phase(LAS unsigned char* lds, const Gemm g, const Sched& S, const Epi& E, int wave_id) {
;     ...
;             PG8_WAIT_V(8); PG8_WAIT_L(0); PG8_BAR; PG8_MMA(1, 0, At, B0); PG8_MMA(1, 1, At, B1); PG8_BAR; PG8_SCHED;
;             PG8_LDB(B0, 1, 0); PG8_LDB(B1, 1, 1); PG8_SCHED; PG8_LDA(At, 1, 0); PG8_STAGE(PG8_SA(0, 1), a2 + hstepA, voffA);
;             PG8_WAIT_V(8); PG8_WAIT_L(0); PG8_BAR; PG8_MMA(0, 0, At, B0); PG8_MMA(0, 1, At, B1); PG8_BAR; PG8_SCHED;
	s_setprio 1
	s_waitcnt lgkmcnt(0)
	v_mfma_f32_16x16x32_bf16 v[60:63], v[140:143], v[178:181], 0
	v_mfma_f32_16x16x32_bf16 v[56:59], v[148:151], v[178:181], 0
	v_mfma_f32_16x16x32_bf16 v[44:47], v[140:143], v[186:189], 0
	v_mfma_f32_16x16x32_bf16 v[40:43], v[148:151], v[186:189], 0
	v_mfma_f32_16x16x32_bf16 v[28:31], v[140:143], v[194:197], 0
	v_mfma_f32_16x16x32_bf16 v[24:27], v[148:151], v[194:197], 0
	v_mfma_f32_16x16x32_bf16 v[12:15], v[140:143], v[202:205], 0
	v_mfma_f32_16x16x32_bf16 v[8:11], v[148:151], v[202:205], 0
	v_mfma_f32_16x16x32_bf16 v[60:63], v[144:147], v[182:185], v[60:63]
	v_mfma_f32_16x16x32_bf16 v[56:59], v[152:155], v[182:185], v[56:59]
	v_mfma_f32_16x16x32_bf16 v[44:47], v[144:147], v[190:193], v[44:47]
	v_mfma_f32_16x16x32_bf16 v[40:43], v[152:155], v[190:193], v[40:43]
	v_mfma_f32_16x16x32_bf16 v[28:31], v[144:147], v[198:201], v[28:31]
	v_mfma_f32_16x16x32_bf16 v[24:27], v[152:155], v[198:201], v[24:27]
	v_mfma_f32_16x16x32_bf16 v[12:15], v[144:147], v[206:209], v[12:15]
	v_mfma_f32_16x16x32_bf16 v[8:11], v[152:155], v[206:209], v[8:11]
	s_setprio 0
	s_setprio 1
	v_mfma_f32_16x16x32_bf16 v[52:55], v[162:165], v[178:181], 0
	v_mfma_f32_16x16x32_bf16 v[48:51], v[170:173], v[178:181], 0
	v_mfma_f32_16x16x32_bf16 v[36:39], v[162:165], v[186:189], 0
	v_mfma_f32_16x16x32_bf16 v[32:35], v[170:173], v[186:189], 0
	v_mfma_f32_16x16x32_bf16 v[20:23], v[162:165], v[194:197], 0
	v_mfma_f32_16x16x32_bf16 v[16:19], v[170:173], v[194:197], 0
	v_mfma_f32_16x16x32_bf16 v[4:7], v[162:165], v[202:205], 0
	v_mfma_f32_16x16x32_bf16 v[0:3], v[170:173], v[202:205], 0
	v_mfma_f32_16x16x32_bf16 v[52:55], v[166:169], v[182:185], v[52:55]
	v_mfma_f32_16x16x32_bf16 v[48:51], v[174:177], v[182:185], v[48:51]
	v_mfma_f32_16x16x32_bf16 v[36:39], v[166:169], v[190:193], v[36:39]
	v_mfma_f32_16x16x32_bf16 v[32:35], v[174:177], v[190:193], v[32:35]
	v_mfma_f32_16x16x32_bf16 v[20:23], v[166:169], v[198:201], v[20:23]
	v_mfma_f32_16x16x32_bf16 v[16:19], v[174:177], v[198:201], v[16:19]
	v_mfma_f32_16x16x32_bf16 v[4:7], v[166:169], v[206:209], v[4:7]
	v_mfma_f32_16x16x32_bf16 v[0:3], v[174:177], v[206:209], v[0:3]
	s_setprio 0
	s_barrier
	s_add_i32 s58, 0, 0x18000
	s_add_i32 s59, 0, 0x1c000
	v_add_u32_e32 v152, s58, v157
	v_add_u32_e32 v174, s59, v157
	ds_read_b128 v[140:143], v152
	ds_read_b128 v[144:147], v152 offset:1024
	ds_read_b128 v[148:151], v152 offset:2048
	ds_read_b128 v[152:155], v152 offset:3072
	ds_read_b128 v[162:165], v174
	ds_read_b128 v[166:169], v174 offset:1024
	ds_read_b128 v[170:173], v174 offset:2048
	ds_read_b128 v[174:177], v174 offset:3072
	s_add_u32 s36, s36, 0x40000
	s_addc_u32 s37, s37, 0
	s_mov_b32 m0, s44
	v_lshl_add_u64 v[218:219], s[36:37], 0, v[128:129]
	ds_read_b128 v[178:181], v161 offset:32768
	ds_read_b128 v[182:185], v161 offset:33792
	ds_read_b128 v[186:189], v161 offset:34816
	ds_read_b128 v[190:193], v161 offset:35840
	ds_read_b128 v[194:197], v161 offset:36864
	ds_read_b128 v[198:201], v161 offset:37888
	ds_read_b128 v[202:205], v161 offset:38912
	ds_read_b128 v[206:209], v161 offset:39936
	global_load_lds_dwordx4 v[218:219], off
	v_lshl_add_u64 v[218:219], s[36:37], 0, v[132:133]
	s_mov_b32 m0, s45
	s_nop 0
	global_load_lds_dwordx4 v[218:219], off
	s_waitcnt vmcnt(8)
	s_waitcnt lgkmcnt(0)
	s_barrier
	s_setprio 1
	s_waitcnt lgkmcnt(0)
	v_mfma_f32_16x16x32_bf16 v[124:127], v[140:143], v[178:181], v[124:127]
	v_mfma_f32_16x16x32_bf16 v[120:123], v[148:151], v[178:181], v[120:123]
	v_mfma_f32_16x16x32_bf16 v[108:111], v[140:143], v[186:189], v[108:111]
	v_mfma_f32_16x16x32_bf16 v[104:107], v[148:151], v[186:189], v[104:107]
	v_mfma_f32_16x16x32_bf16 v[92:95], v[140:143], v[194:197], v[92:95]
	v_mfma_f32_16x16x32_bf16 v[88:91], v[148:151], v[194:197], v[88:91]
	v_mfma_f32_16x16x32_bf16 v[76:79], v[140:143], v[202:205], v[76:79]
	v_mfma_f32_16x16x32_bf16 v[72:75], v[148:151], v[202:205], v[72:75]
	v_mfma_f32_16x16x32_bf16 v[124:127], v[144:147], v[182:185], v[124:127]
	v_mfma_f32_16x16x32_bf16 v[120:123], v[152:155], v[182:185], v[120:123]
	v_mfma_f32_16x16x32_bf16 v[108:111], v[144:147], v[190:193], v[108:111]
	v_mfma_f32_16x16x32_bf16 v[104:107], v[152:155], v[190:193], v[104:107]
	v_mfma_f32_16x16x32_bf16 v[92:95], v[144:147], v[198:201], v[92:95]
	v_mfma_f32_16x16x32_bf16 v[88:91], v[152:155], v[198:201], v[88:91]
	v_mfma_f32_16x16x32_bf16 v[76:79], v[144:147], v[206:209], v[76:79]
	v_mfma_f32_16x16x32_bf16 v[72:75], v[152:155], v[206:209], v[72:75]
	s_setprio 0
	s_setprio 1
	v_mfma_f32_16x16x32_bf16 v[116:119], v[162:165], v[178:181], v[116:119]
	v_mfma_f32_16x16x32_bf16 v[112:115], v[170:173], v[178:181], v[112:115]
	v_mfma_f32_16x16x32_bf16 v[100:103], v[162:165], v[186:189], v[100:103]
	v_mfma_f32_16x16x32_bf16 v[96:99], v[170:173], v[186:189], v[96:99]
	v_mfma_f32_16x16x32_bf16 v[84:87], v[162:165], v[194:197], v[84:87]
	v_mfma_f32_16x16x32_bf16 v[80:83], v[170:173], v[194:197], v[80:83]
	v_mfma_f32_16x16x32_bf16 v[68:71], v[162:165], v[202:205], v[68:71]
	v_mfma_f32_16x16x32_bf16 v[64:67], v[170:173], v[202:205], v[64:67]
	v_mfma_f32_16x16x32_bf16 v[116:119], v[166:169], v[182:185], v[116:119]
	v_mfma_f32_16x16x32_bf16 v[112:115], v[174:177], v[182:185], v[112:115]
	v_mfma_f32_16x16x32_bf16 v[100:103], v[166:169], v[190:193], v[100:103]
	v_mfma_f32_16x16x32_bf16 v[96:99], v[174:177], v[190:193], v[96:99]
	v_mfma_f32_16x16x32_bf16 v[84:87], v[166:169], v[198:201], v[84:87]
	v_mfma_f32_16x16x32_bf16 v[80:83], v[174:177], v[198:201], v[80:83]
	v_mfma_f32_16x16x32_bf16 v[68:71], v[166:169], v[206:209], v[68:71]
	v_mfma_f32_16x16x32_bf16 v[64:67], v[174:177], v[206:209], v[64:67]
	s_setprio 0
	s_barrier
; #define PG8_STAGE(bufoff, gbase, voff) do { _Pragma("unroll") for (int _i = 0; _i < 2; ++_i) \
;         __builtin_amdgcn_global_load_lds((const unsigned*)((const char*)(gbase) + (voff)[_i]), (LAS unsigned*)(lds + (bufoff) + ldsw + _i * 8192), 16, 0, 0); } while (0)
; #define PG8_LDA(dst, b, h) do { _Pragma("unroll") for (int m = 0; m < 4; ++m) _Pragma("unroll") for (int k = 0; k < 2; ++k) dst[m][k] = *(const LAS bf16x8*)(lds + PG8_SA(b, h) + aoff + m * 2048 + k * 1024); } while (0)
; #define PG8_MMA(ai, bj, At, Bt) do { __builtin_amdgcn_s_setprio(1); _Pragma("unroll") for (int m = 0; m < 4; ++m) _Pragma("unroll") for (int n = 0; n < 2; ++n) _Pragma("unroll") for (int k = 0; k < 2; ++k) \
;         acc[ai][bj][m][n] = __builtin_amdgcn_mfma_f32_16x16x32_bf16(Bt[n][k], At[m][k], acc[ai][bj][m][n], 0, 0, 0); __builtin_amdgcn_s_setprio(0); } while (0)
; #define PG8_WAIT_V(n) asm volatile("s_waitcnt vmcnt(" #n ")" ::: "memory")
; #define PG8_WAIT_L(n) asm volatile("s_waitcnt lgkmcnt(" #n ")" ::: "memory")
; #define PG8_BAR __builtin_amdgcn_s_barrier()
; #define PG8_SCHED __builtin_amdgcn_sched_barrier(0)
; template <class Epi, class Sched>
; __device__ __forceinline__ void gemm_phase(LAS unsigned char* lds, const Gemm g, const Sched& S, const Epi& E, int wave_id) {
;     ...
;             PG8_LDA(At, 1, 1); PG8_STAGE(PG8_SB(1, 0), b3, voffB); PG8_STAGE(PG8_SB(1, 1), b3 + hstepB, voffB); PG8_STAGE(PG8_SA(1, 0), a3, voffA);
;             PG8_WAIT_V(8); PG8_WAIT_L(0); PG8_BAR; PG8_MMA(1, 0, At, B0); PG8_MMA(1, 1, At, B1); PG8_BAR; PG8_SCHED;
;         }
	s_add_i32 s36, s58, s39
	v_lshl_add_u64 v[210:211], v[210:211], 0, s[8:9]
	s_mov_b32 m0, s36
	ds_read_b128 v[178:181], v161 offset:49152
	ds_read_b128 v[182:185], v161 offset:50176
	ds_read_b128 v[186:189], v161 offset:51200
	ds_read_b128 v[190:193], v161 offset:52224
	ds_read_b128 v[194:197], v161 offset:53248
	ds_read_b128 v[198:201], v161 offset:54272
	ds_read_b128 v[202:205], v161 offset:55296
	ds_read_b128 v[206:209], v161 offset:56320
	global_load_lds_dwordx4 v[210:211], off
	s_add_i32 m0, s36, 0x2000
	s_add_u32 s34, s34, 0x40080
	v_lshl_add_u64 v[210:211], v[212:213], 0, s[8:9]
	s_addc_u32 s35, s35, 0
	s_add_i32 s36, s59, s39
	global_load_lds_dwordx4 v[210:211], off
	v_lshl_add_u64 v[210:211], s[34:35], 0, v[130:131]
	s_mov_b32 m0, s36
	s_nop 0
	global_load_lds_dwordx4 v[210:211], off
	v_lshl_add_u64 v[210:211], s[34:35], 0, v[134:135]
	s_add_i32 m0, s36, 0x2000
	s_nop 0
	global_load_lds_dwordx4 v[210:211], off
	v_lshl_add_u64 v[210:211], v[214:215], 0, s[8:9]
	s_mov_b32 m0, s46
	s_nop 0
	global_load_lds_dwordx4 v[210:211], off
	v_lshl_add_u64 v[210:211], v[216:217], 0, s[8:9]
	s_mov_b32 m0, s47
	s_nop 0
	global_load_lds_dwordx4 v[210:211], off
	s_waitcnt vmcnt(8)
	s_waitcnt lgkmcnt(0)
	s_barrier
	s_setprio 1
	s_waitcnt lgkmcnt(0)
	v_mfma_f32_16x16x32_bf16 v[60:63], v[140:143], v[178:181], v[60:63]
	v_mfma_f32_16x16x32_bf16 v[56:59], v[148:151], v[178:181], v[56:59]
	v_mfma_f32_16x16x32_bf16 v[44:47], v[140:143], v[186:189], v[44:47]
	v_mfma_f32_16x16x32_bf16 v[40:43], v[148:151], v[186:189], v[40:43]
	v_mfma_f32_16x16x32_bf16 v[28:31], v[140:143], v[194:197], v[28:31]
	v_mfma_f32_16x16x32_bf16 v[24:27], v[148:151], v[194:197], v[24:27]
	v_mfma_f32_16x16x32_bf16 v[12:15], v[140:143], v[202:205], v[12:15]
	v_mfma_f32_16x16x32_bf16 v[8:11], v[148:151], v[202:205], v[8:11]
	v_mfma_f32_16x16x32_bf16 v[60:63], v[144:147], v[182:185], v[60:63]
	v_mfma_f32_16x16x32_bf16 v[56:59], v[152:155], v[182:185], v[56:59]
	v_mfma_f32_16x16x32_bf16 v[44:47], v[144:147], v[190:193], v[44:47]
	v_mfma_f32_16x16x32_bf16 v[40:43], v[152:155], v[190:193], v[40:43]
	v_mfma_f32_16x16x32_bf16 v[28:31], v[144:147], v[198:201], v[28:31]
	v_mfma_f32_16x16x32_bf16 v[24:27], v[152:155], v[198:201], v[24:27]
	v_mfma_f32_16x16x32_bf16 v[12:15], v[144:147], v[206:209], v[12:15]
	v_mfma_f32_16x16x32_bf16 v[8:11], v[152:155], v[206:209], v[8:11]
	s_setprio 0
	s_setprio 1
	v_mfma_f32_16x16x32_bf16 v[52:55], v[162:165], v[178:181], v[52:55]
	v_mfma_f32_16x16x32_bf16 v[48:51], v[170:173], v[178:181], v[48:51]
	v_mfma_f32_16x16x32_bf16 v[36:39], v[162:165], v[186:189], v[36:39]
	v_mfma_f32_16x16x32_bf16 v[32:35], v[170:173], v[186:189], v[32:35]
	v_mfma_f32_16x16x32_bf16 v[20:23], v[162:165], v[194:197], v[20:23]
	v_mfma_f32_16x16x32_bf16 v[16:19], v[170:173], v[194:197], v[16:19]
	v_mfma_f32_16x16x32_bf16 v[4:7], v[162:165], v[202:205], v[4:7]
	v_mfma_f32_16x16x32_bf16 v[0:3], v[170:173], v[202:205], v[0:3]
	v_mfma_f32_16x16x32_bf16 v[52:55], v[166:169], v[182:185], v[52:55]
	v_mfma_f32_16x16x32_bf16 v[48:51], v[174:177], v[182:185], v[48:51]
	v_mfma_f32_16x16x32_bf16 v[36:39], v[166:169], v[190:193], v[36:39]
	v_mfma_f32_16x16x32_bf16 v[32:35], v[174:177], v[190:193], v[32:35]
	v_mfma_f32_16x16x32_bf16 v[20:23], v[166:169], v[198:201], v[20:23]
	v_mfma_f32_16x16x32_bf16 v[16:19], v[174:177], v[198:201], v[16:19]
	v_mfma_f32_16x16x32_bf16 v[4:7], v[166:169], v[206:209], v[4:7]
	v_mfma_f32_16x16x32_bf16 v[0:3], v[174:177], v[206:209], v[0:3]
	s_setprio 0
	s_barrier
	s_add_i32 s55, s55, 2
	s_add_u32 s30, s30, 0x100
	s_addc_u32 s31, s31, 0
	s_add_u32 s53, s53, 0x100
	s_addc_u32 s54, s54, 0
	s_cmp_gt_u32 s55, 13

;     __device__ bool next(int i, Unit& u) const { if (r0 + i >= r1) return false; return base.next(r0 + i, u); }
;     __device__ bool next(int i, Unit& u) const { const int L = i * G + c; if (L >= 256) return false; u.pm = L; u.pn = L >> 3; return true; }
; #define PG8_STAGE(bufoff, gbase, voff) do { _Pragma("unroll") for (int _i = 0; _i < 2; ++_i) \
;         __builtin_amdgcn_global_load_lds((const unsigned*)((const char*)(gbase) + (voff)[_i]), (LAS unsigned*)(lds + (bufoff) + ldsw + _i * 8192), 16, 0, 0); } while (0)
; #define PG8_LDA(dst, b, h) do { _Pragma("unroll") for (int m = 0; m < 4; ++m) _Pragma("unroll") for (int k = 0; k < 2; ++k) dst[m][k] = *(const LAS bf16x8*)(lds + PG8_SA(b, h) + aoff + m * 2048 + k * 1024); } while (0)
; #define PG8_LDB(dst, b, h) do { _Pragma("unroll") for (int n = 0; n < 2; ++n) _Pragma("unroll") for (int k = 0; k < 2; ++k) dst[n][k] = *(const LAS bf16x8*)(lds + PG8_SB(b, h) + boff + n * 2048 + k * 1024); } while (0)
; template <class Epi, class Sched>
; __device__ __forceinline__ void gemm_phase(LAS unsigned char* lds, const Gemm g, const Sched& S, const Epi& E, int wave_id) {
;     ...
;         const bool has_next = S.next(ui + 1, nxt);
;         const char* nA = has_next ? (const char*)g.A + (size_t)nxt.pm * tstepA : cA; const char* nB = has_next ? (const char*)g.Bt + (size_t)nxt.pn * tstepB : cB;
;         for (int t = 0; t < nt; t += 2) {
;             const bool last = (t == nt - 2);
;             const char* a1 = cA + (size_t)(t + 1) * kstep;
;             const char* a2 = last ? nA : cA + (size_t)(t + 2) * kstep; const char* b2 = last ? nB : cB + (size_t)(t + 2) * kstep;
;             const char* a3 = a2 + kstep; const char* b3 = b2 + kstep;
;             PG8_LDB(B0, 0, 0); PG8_LDB(B1, 0, 1); PG8_SCHED; PG8_LDA(At, 0, 0); PG8_STAGE(PG8_SA(1, 1), a1 + hstepA, voffA);
;             PG8_WAIT_V(8); PG8_WAIT_L(0); PG8_BAR; PG8_MMA(0, 0, At, B0); PG8_MMA(0, 1, At, B1); PG8_BAR; PG8_SCHED;
;             PG8_LDA(At, 0, 1); PG8_STAGE(PG8_SB(0, 0), b2, voffB); PG8_STAGE(PG8_SB(0, 1), b2 + hstepB, voffB); PG8_STAGE(PG8_SA(0, 0), a2, voffA);
;     ...
;         for (int a = 0; a < 2; ++a)
; #pragma unroll
;             for (int b = 0; b < 2; ++b)
; #pragma unroll
;                 for (int m = 0; m < 4; ++m)
; #pragma unroll
;                     for (int n = 0; n < 2; ++n) acc[a][b][m][n] = (f32x4){0.f, 0.f, 0.f, 0.f};
.LBB0_862:
	s_ashr_i32 s19, s18, 31
	s_andn2_b64 vcc, exec, s[36:37]
	s_lshl_b64 s[22:23], s[18:19], 19
	s_add_u32 s22, s2, s22
	s_addc_u32 s23, s3, s23
	s_and_b64 s[24:25], s[36:37], exec
	s_cselect_b32 s19, s23, s31
	s_cselect_b32 s46, s22, s30
	s_ashr_i32 s17, s16, 31
	s_lshl_b64 s[24:25], s[16:17], 19
	s_add_u32 s24, s21, s24
	s_addc_u32 s25, s33, s25
	v_cndmask_b32_e64 v0, 0, 1, s[36:37]
	s_and_b64 s[36:37], s[36:37], exec
	s_cselect_b32 s17, s25, s35
	s_cselect_b32 s47, s24, s34
	s_add_u32 s30, s30, 0x40080
	s_addc_u32 s31, s31, 0
	v_cmp_ne_u32_e64 s[4:5], 1, v0
	s_add_u32 s48, s34, 0x100
	s_addc_u32 s49, s35, 0
	s_mov_b32 s50, -2
	s_waitcnt vmcnt(0)
	ds_read_b128 v[140:143], v159
	ds_read_b128 v[144:147], v159 offset:1024
	ds_read_b128 v[148:151], v159 offset:2048
	ds_read_b128 v[152:155], v159 offset:3072
	ds_read_b128 v[162:165], v160
	ds_read_b128 v[166:169], v160 offset:1024
	ds_read_b128 v[170:173], v160 offset:2048
	ds_read_b128 v[174:177], v160 offset:3072
	s_add_u32 s34, s30, 0xfffc0080
	s_addc_u32 s35, s31, -1
	s_cmp_eq_u32 s50, 12
	s_cselect_b32 s37, s19, s35
	s_cselect_b32 s36, s46, s34
	s_cselect_b32 s35, s17, s49
	s_cselect_b32 s34, s47, s48
	v_lshl_add_u64 v[210:211], s[30:31], 0, v[136:137]
	s_add_i32 m0, s27, 0xc000
	ds_read_b128 v[178:181], v161
	ds_read_b128 v[182:185], v161 offset:1024
	ds_read_b128 v[186:189], v161 offset:2048
	ds_read_b128 v[190:193], v161 offset:3072
	ds_read_b128 v[194:197], v161 offset:4096
	ds_read_b128 v[198:201], v161 offset:5120
	ds_read_b128 v[202:205], v161 offset:6144
	ds_read_b128 v[206:209], v161 offset:7168
	global_load_lds_dwordx4 v[210:211], off
	v_lshl_add_u64 v[210:211], s[30:31], 0, v[138:139]
	s_add_i32 m0, s27, 0xe000
	s_nop 0
	global_load_lds_dwordx4 v[210:211], off
	s_waitcnt vmcnt(8)
	s_waitcnt lgkmcnt(0)
	s_barrier
	s_setprio 1
	s_waitcnt lgkmcnt(0)
	v_mfma_f32_16x16x32_bf16 v[124:127], v[140:143], v[178:181], 0
	v_mfma_f32_16x16x32_bf16 v[120:123], v[148:151], v[178:181], 0
	v_mfma_f32_16x16x32_bf16 v[108:111], v[140:143], v[186:189], 0
	v_mfma_f32_16x16x32_bf16 v[104:107], v[148:151], v[186:189], 0
	v_mfma_f32_16x16x32_bf16 v[92:95], v[140:143], v[194:197], 0
	v_mfma_f32_16x16x32_bf16 v[88:91], v[148:151], v[194:197], 0
	v_mfma_f32_16x16x32_bf16 v[76:79], v[140:143], v[202:205], 0
	v_mfma_f32_16x16x32_bf16 v[72:75], v[148:151], v[202:205], 0
	v_mfma_f32_16x16x32_bf16 v[124:127], v[144:147], v[182:185], v[124:127]
	v_mfma_f32_16x16x32_bf16 v[120:123], v[152:155], v[182:185], v[120:123]
	v_mfma_f32_16x16x32_bf16 v[108:111], v[144:147], v[190:193], v[108:111]
	v_mfma_f32_16x16x32_bf16 v[104:107], v[152:155], v[190:193], v[104:107]
	v_mfma_f32_16x16x32_bf16 v[92:95], v[144:147], v[198:201], v[92:95]
	v_mfma_f32_16x16x32_bf16 v[88:91], v[152:155], v[198:201], v[88:91]
	v_mfma_f32_16x16x32_bf16 v[76:79], v[144:147], v[206:209], v[76:79]
	v_mfma_f32_16x16x32_bf16 v[72:75], v[152:155], v[206:209], v[72:75]
	s_setprio 0
	s_setprio 1
	v_mfma_f32_16x16x32_bf16 v[116:119], v[162:165], v[178:181], 0
	v_mfma_f32_16x16x32_bf16 v[112:115], v[170:173], v[178:181], 0
	v_mfma_f32_16x16x32_bf16 v[100:103], v[162:165], v[186:189], 0
	v_mfma_f32_16x16x32_bf16 v[96:99], v[170:173], v[186:189], 0
	v_mfma_f32_16x16x32_bf16 v[84:87], v[162:165], v[194:197], 0
	v_mfma_f32_16x16x32_bf16 v[80:83], v[170:173], v[194:197], 0
	v_mfma_f32_16x16x32_bf16 v[68:71], v[162:165], v[202:205], 0
	v_mfma_f32_16x16x32_bf16 v[64:67], v[170:173], v[202:205], 0
	v_mfma_f32_16x16x32_bf16 v[116:119], v[166:169], v[182:185], v[116:119]
	v_mfma_f32_16x16x32_bf16 v[112:115], v[174:177], v[182:185], v[112:115]
	v_mfma_f32_16x16x32_bf16 v[100:103], v[166:169], v[190:193], v[100:103]
	v_mfma_f32_16x16x32_bf16 v[96:99], v[174:177], v[190:193], v[96:99]
	v_mfma_f32_16x16x32_bf16 v[84:87], v[166:169], v[198:201], v[84:87]
	v_mfma_f32_16x16x32_bf16 v[80:83], v[174:177], v[198:201], v[80:83]
	v_mfma_f32_16x16x32_bf16 v[68:71], v[166:169], v[206:209], v[68:71]
	v_mfma_f32_16x16x32_bf16 v[64:67], v[174:177], v[206:209], v[64:67]
	s_setprio 0
	s_barrier
	s_add_i32 s51, s43, s38
	v_lshl_add_u64 v[210:211], s[34:35], 0, v[130:131]
	s_mov_b32 m0, s51
	ds_read_b128 v[178:181], v161 offset:16384
	ds_read_b128 v[182:185], v161 offset:17408
	ds_read_b128 v[186:189], v161 offset:18432
	ds_read_b128 v[190:193], v161 offset:19456
	ds_read_b128 v[194:197], v161 offset:20480
	ds_read_b128 v[198:201], v161 offset:21504
	ds_read_b128 v[202:205], v161 offset:22528
	ds_read_b128 v[206:209], v161 offset:23552
	global_load_lds_dwordx4 v[210:211], off
	s_add_i32 m0, s51, 0x2000
	s_add_u32 s52, s34, 0x40000
	v_lshl_add_u64 v[212:213], s[34:35], 0, v[134:135]
	s_addc_u32 s53, s35, 0
	s_add_i32 s51, s44, s38
	global_load_lds_dwordx4 v[212:213], off
	v_lshl_add_u64 v[214:215], s[52:53], 0, v[130:131]
	s_mov_b32 m0, s51
	v_lshl_add_u64 v[216:217], s[36:37], 0, v[132:133]
	global_load_lds_dwordx4 v[214:215], off
	v_lshl_add_u64 v[214:215], s[52:53], 0, v[134:135]
	s_add_i32 m0, s51, 0x2000
	s_nop 0
	global_load_lds_dwordx4 v[214:215], off
	v_lshl_add_u64 v[214:215], s[36:37], 0, v[128:129]
	s_mov_b32 m0, s27
	s_nop 0
	global_load_lds_dwordx4 v[214:215], off
	s_mov_b32 m0, s29
	s_nop 0
	global_load_lds_dwordx4 v[216:217], off
	s_waitcnt vmcnt(8)
	s_waitcnt lgkmcnt(0)
	s_barrier
; #define PG8_STAGE(bufoff, gbase, voff) do { _Pragma("unroll") for (int _i = 0; _i < 2; ++_i) \
;         __builtin_amdgcn_global_load_lds((const unsigned*)((const char*)(gbase) + (voff)[_i]), (LAS unsigned*)(lds + (bufoff) + ldsw + _i * 8192), 16, 0, 0); } while (0)
; #define PG8_LDA(dst, b, h) do { _Pragma("unroll") for (int m = 0; m < 4; ++m) _Pragma("unroll") for (int k = 0; k < 2; ++k) dst[m][k] = *(const LAS bf16x8*)(lds + PG8_SA(b, h) + aoff + m * 2048 + k * 1024); } while (0)
; #define PG8_LDB(dst, b, h) do { _Pragma("unroll") for (int n = 0; n < 2; ++n) _Pragma("unroll") for (int k = 0; k < 2; ++k) dst[n][k] = *(const LAS bf16x8*)(lds + PG8_SB(b, h) + boff + n * 2048 + k * 1024); } while (0)
; #define PG8_MMA(ai, bj, At, Bt) do { __builtin_amdgcn_s_setprio(1); _Pragma("unroll") for (int m = 0; m < 4; ++m) _Pragma("unroll") for (int n = 0; n < 2; ++n) _Pragma("unroll") for (int k = 0; k < 2; ++k) \
;         acc[ai][bj][m][n] = __builtin_amdgcn_mfma_f32_16x16x32_bf16(Bt[n][k], At[m][k], acc[ai][bj][m][n], 0, 0, 0); __builtin_amdgcn_s_setprio(0); } while (0)
; #define PG8_WAIT_V(n) asm volatile("s_waitcnt vmcnt(" #n ")" ::: "memory")
; #define PG8_WAIT_L(n) asm volatile("s_waitcnt lgkmcnt(" #n ")" ::: "memory")
; #define PG8_BAR __builtin_amdgcn_s_barrier()
; #define PG8_SCHED __builtin_amdgcn_sched_barrier(0)
; template <class Epi, class Sched>
; __device__ __forceinline__ void gemm_phase(LAS unsigned char* lds, const Gemm g, const Sched& S, const Epi& E, int wave_id) {
;     ...
;             PG8_WAIT_V(8); PG8_WAIT_L(0); PG8_BAR; PG8_MMA(1, 0, At, B0); PG8_MMA(1, 1, At, B1); PG8_BAR; PG8_SCHED;
;             PG8_LDB(B0, 1, 0); PG8_LDB(B1, 1, 1); PG8_SCHED; PG8_LDA(At, 1, 0); PG8_STAGE(PG8_SA(0, 1), a2 + hstepA, voffA);
;             PG8_WAIT_V(8); PG8_WAIT_L(0); PG8_BAR; PG8_MMA(0, 0, At, B0); PG8_MMA(0, 1, At, B1); PG8_BAR; PG8_SCHED;
	s_setprio 1
	s_waitcnt lgkmcnt(0)
	v_mfma_f32_16x16x32_bf16 v[60:63], v[140:143], v[178:181], 0
	v_mfma_f32_16x16x32_bf16 v[56:59], v[148:151], v[178:181], 0
	v_mfma_f32_16x16x32_bf16 v[44:47], v[140:143], v[186:189], 0
	v_mfma_f32_16x16x32_bf16 v[40:43], v[148:151], v[186:189], 0
	v_mfma_f32_16x16x32_bf16 v[28:31], v[140:143], v[194:197], 0
	v_mfma_f32_16x16x32_bf16 v[24:27], v[148:151], v[194:197], 0
	v_mfma_f32_16x16x32_bf16 v[12:15], v[140:143], v[202:205], 0
	v_mfma_f32_16x16x32_bf16 v[8:11], v[148:151], v[202:205], 0
	v_mfma_f32_16x16x32_bf16 v[60:63], v[144:147], v[182:185], v[60:63]
	v_mfma_f32_16x16x32_bf16 v[56:59], v[152:155], v[182:185], v[56:59]
	v_mfma_f32_16x16x32_bf16 v[44:47], v[144:147], v[190:193], v[44:47]
	v_mfma_f32_16x16x32_bf16 v[40:43], v[152:155], v[190:193], v[40:43]
	v_mfma_f32_16x16x32_bf16 v[28:31], v[144:147], v[198:201], v[28:31]
	v_mfma_f32_16x16x32_bf16 v[24:27], v[152:155], v[198:201], v[24:27]
	v_mfma_f32_16x16x32_bf16 v[12:15], v[144:147], v[206:209], v[12:15]
	v_mfma_f32_16x16x32_bf16 v[8:11], v[152:155], v[206:209], v[8:11]
	s_setprio 0
	s_setprio 1
	v_mfma_f32_16x16x32_bf16 v[52:55], v[162:165], v[178:181], 0
	v_mfma_f32_16x16x32_bf16 v[48:51], v[170:173], v[178:181], 0
	v_mfma_f32_16x16x32_bf16 v[36:39], v[162:165], v[186:189], 0
	v_mfma_f32_16x16x32_bf16 v[32:35], v[170:173], v[186:189], 0
	v_mfma_f32_16x16x32_bf16 v[20:23], v[162:165], v[194:197], 0
	v_mfma_f32_16x16x32_bf16 v[16:19], v[170:173], v[194:197], 0
	v_mfma_f32_16x16x32_bf16 v[4:7], v[162:165], v[202:205], 0
	v_mfma_f32_16x16x32_bf16 v[0:3], v[170:173], v[202:205], 0
	v_mfma_f32_16x16x32_bf16 v[52:55], v[166:169], v[182:185], v[52:55]
	v_mfma_f32_16x16x32_bf16 v[48:51], v[174:177], v[182:185], v[48:51]
	v_mfma_f32_16x16x32_bf16 v[36:39], v[166:169], v[190:193], v[36:39]
	v_mfma_f32_16x16x32_bf16 v[32:35], v[174:177], v[190:193], v[32:35]
	v_mfma_f32_16x16x32_bf16 v[20:23], v[166:169], v[198:201], v[20:23]
	v_mfma_f32_16x16x32_bf16 v[16:19], v[174:177], v[198:201], v[16:19]
	v_mfma_f32_16x16x32_bf16 v[4:7], v[166:169], v[206:209], v[4:7]
	v_mfma_f32_16x16x32_bf16 v[0:3], v[174:177], v[206:209], v[0:3]
	s_setprio 0
	s_barrier
	s_add_i32 s51, 0, 0x18000
	s_add_i32 s52, 0, 0x1c000
	v_add_u32_e32 v152, s51, v157
	v_add_u32_e32 v174, s52, v157
	ds_read_b128 v[140:143], v152
	ds_read_b128 v[144:147], v152 offset:1024
	ds_read_b128 v[148:151], v152 offset:2048
	ds_read_b128 v[152:155], v152 offset:3072
	ds_read_b128 v[162:165], v174
	ds_read_b128 v[166:169], v174 offset:1024
	ds_read_b128 v[170:173], v174 offset:2048
	ds_read_b128 v[174:177], v174 offset:3072
	s_add_u32 s36, s36, 0x40000
	s_addc_u32 s37, s37, 0
	s_mov_b32 m0, s39
	v_lshl_add_u64 v[218:219], s[36:37], 0, v[128:129]
	ds_read_b128 v[178:181], v161 offset:32768
	ds_read_b128 v[182:185], v161 offset:33792
	ds_read_b128 v[186:189], v161 offset:34816
	ds_read_b128 v[190:193], v161 offset:35840
	ds_read_b128 v[194:197], v161 offset:36864
	ds_read_b128 v[198:201], v161 offset:37888
	ds_read_b128 v[202:205], v161 offset:38912
	ds_read_b128 v[206:209], v161 offset:39936
	global_load_lds_dwordx4 v[218:219], off
	v_lshl_add_u64 v[218:219], s[36:37], 0, v[132:133]
	s_mov_b32 m0, s40
	s_nop 0
	global_load_lds_dwordx4 v[218:219], off
	s_waitcnt vmcnt(8)
	s_waitcnt lgkmcnt(0)
	s_barrier
	s_setprio 1
	s_waitcnt lgkmcnt(0)
	v_mfma_f32_16x16x32_bf16 v[124:127], v[140:143], v[178:181], v[124:127]
	v_mfma_f32_16x16x32_bf16 v[120:123], v[148:151], v[178:181], v[120:123]
	v_mfma_f32_16x16x32_bf16 v[108:111], v[140:143], v[186:189], v[108:111]
	v_mfma_f32_16x16x32_bf16 v[104:107], v[148:151], v[186:189], v[104:107]
	v_mfma_f32_16x16x32_bf16 v[92:95], v[140:143], v[194:197], v[92:95]
	v_mfma_f32_16x16x32_bf16 v[88:91], v[148:151], v[194:197], v[88:91]
	v_mfma_f32_16x16x32_bf16 v[76:79], v[140:143], v[202:205], v[76:79]
	v_mfma_f32_16x16x32_bf16 v[72:75], v[148:151], v[202:205], v[72:75]
	v_mfma_f32_16x16x32_bf16 v[124:127], v[144:147], v[182:185], v[124:127]
	v_mfma_f32_16x16x32_bf16 v[120:123], v[152:155], v[182:185], v[120:123]
	v_mfma_f32_16x16x32_bf16 v[108:111], v[144:147], v[190:193], v[108:111]
	v_mfma_f32_16x16x32_bf16 v[104:107], v[152:155], v[190:193], v[104:107]
	v_mfma_f32_16x16x32_bf16 v[92:95], v[144:147], v[198:201], v[92:95]
	v_mfma_f32_16x16x32_bf16 v[88:91], v[152:155], v[198:201], v[88:91]
	v_mfma_f32_16x16x32_bf16 v[76:79], v[144:147], v[206:209], v[76:79]
	v_mfma_f32_16x16x32_bf16 v[72:75], v[152:155], v[206:209], v[72:75]
	s_setprio 0
	s_setprio 1
	v_mfma_f32_16x16x32_bf16 v[116:119], v[162:165], v[178:181], v[116:119]
	v_mfma_f32_16x16x32_bf16 v[112:115], v[170:173], v[178:181], v[112:115]
	v_mfma_f32_16x16x32_bf16 v[100:103], v[162:165], v[186:189], v[100:103]
	v_mfma_f32_16x16x32_bf16 v[96:99], v[170:173], v[186:189], v[96:99]
	v_mfma_f32_16x16x32_bf16 v[84:87], v[162:165], v[194:197], v[84:87]
	v_mfma_f32_16x16x32_bf16 v[80:83], v[170:173], v[194:197], v[80:83]
	v_mfma_f32_16x16x32_bf16 v[68:71], v[162:165], v[202:205], v[68:71]
	v_mfma_f32_16x16x32_bf16 v[64:67], v[170:173], v[202:205], v[64:67]
	v_mfma_f32_16x16x32_bf16 v[116:119], v[166:169], v[182:185], v[116:119]
	v_mfma_f32_16x16x32_bf16 v[112:115], v[174:177], v[182:185], v[112:115]
	v_mfma_f32_16x16x32_bf16 v[100:103], v[166:169], v[190:193], v[100:103]
	v_mfma_f32_16x16x32_bf16 v[96:99], v[174:177], v[190:193], v[96:99]
	v_mfma_f32_16x16x32_bf16 v[84:87], v[166:169], v[198:201], v[84:87]
	v_mfma_f32_16x16x32_bf16 v[80:83], v[174:177], v[198:201], v[80:83]
	v_mfma_f32_16x16x32_bf16 v[68:71], v[166:169], v[206:209], v[68:71]
	v_mfma_f32_16x16x32_bf16 v[64:67], v[174:177], v[206:209], v[64:67]
	s_setprio 0
	s_barrier
; #define PG8_STAGE(bufoff, gbase, voff) do { _Pragma("unroll") for (int _i = 0; _i < 2; ++_i) \
;         __builtin_amdgcn_global_load_lds((const unsigned*)((const char*)(gbase) + (voff)[_i]), (LAS unsigned*)(lds + (bufoff) + ldsw + _i * 8192), 16, 0, 0); } while (0)
; #define PG8_LDA(dst, b, h) do { _Pragma("unroll") for (int m = 0; m < 4; ++m) _Pragma("unroll") for (int k = 0; k < 2; ++k) dst[m][k] = *(const LAS bf16x8*)(lds + PG8_SA(b, h) + aoff + m * 2048 + k * 1024); } while (0)
; #define PG8_MMA(ai, bj, At, Bt) do { __builtin_amdgcn_s_setprio(1); _Pragma("unroll") for (int m = 0; m < 4; ++m) _Pragma("unroll") for (int n = 0; n < 2; ++n) _Pragma("unroll") for (int k = 0; k < 2; ++k) \
;         acc[ai][bj][m][n] = __builtin_amdgcn_mfma_f32_16x16x32_bf16(Bt[n][k], At[m][k], acc[ai][bj][m][n], 0, 0, 0); __builtin_amdgcn_s_setprio(0); } while (0)
; #define PG8_WAIT_V(n) asm volatile("s_waitcnt vmcnt(" #n ")" ::: "memory")
; #define PG8_WAIT_L(n) asm volatile("s_waitcnt lgkmcnt(" #n ")" ::: "memory")
; #define PG8_BAR __builtin_amdgcn_s_barrier()
; #define PG8_SCHED __builtin_amdgcn_sched_barrier(0)
; template <class Epi, class Sched>
; __device__ __forceinline__ void gemm_phase(LAS unsigned char* lds, const Gemm g, const Sched& S, const Epi& E, int wave_id) {
;     ...
;             PG8_LDA(At, 1, 1); PG8_STAGE(PG8_SB(1, 0), b3, voffB); PG8_STAGE(PG8_SB(1, 1), b3 + hstepB, voffB); PG8_STAGE(PG8_SA(1, 0), a3, voffA);
;             PG8_WAIT_V(8); PG8_WAIT_L(0); PG8_BAR; PG8_MMA(1, 0, At, B0); PG8_MMA(1, 1, At, B1); PG8_BAR; PG8_SCHED;
;         }
	s_add_i32 s36, s51, s38
	v_lshl_add_u64 v[210:211], v[210:211], 0, s[8:9]
	s_mov_b32 m0, s36
	ds_read_b128 v[178:181], v161 offset:49152
	ds_read_b128 v[182:185], v161 offset:50176
	ds_read_b128 v[186:189], v161 offset:51200
	ds_read_b128 v[190:193], v161 offset:52224
	ds_read_b128 v[194:197], v161 offset:53248
	ds_read_b128 v[198:201], v161 offset:54272
	ds_read_b128 v[202:205], v161 offset:55296
	ds_read_b128 v[206:209], v161 offset:56320
	global_load_lds_dwordx4 v[210:211], off
	s_add_i32 m0, s36, 0x2000
	s_add_u32 s34, s34, 0x40080
	v_lshl_add_u64 v[210:211], v[212:213], 0, s[8:9]
	s_addc_u32 s35, s35, 0
	s_add_i32 s36, s52, s38
	global_load_lds_dwordx4 v[210:211], off
	v_lshl_add_u64 v[210:211], s[34:35], 0, v[130:131]
	s_mov_b32 m0, s36
	s_nop 0
	global_load_lds_dwordx4 v[210:211], off
	v_lshl_add_u64 v[210:211], s[34:35], 0, v[134:135]
	s_add_i32 m0, s36, 0x2000
	s_nop 0
	global_load_lds_dwordx4 v[210:211], off
	v_lshl_add_u64 v[210:211], v[214:215], 0, s[8:9]
	s_mov_b32 m0, s41
	s_nop 0
	global_load_lds_dwordx4 v[210:211], off
	v_lshl_add_u64 v[210:211], v[216:217], 0, s[8:9]
	s_mov_b32 m0, s42
	s_nop 0
	global_load_lds_dwordx4 v[210:211], off
	s_waitcnt vmcnt(8)
	s_waitcnt lgkmcnt(0)
	s_barrier
	s_setprio 1
	s_waitcnt lgkmcnt(0)
	v_mfma_f32_16x16x32_bf16 v[60:63], v[140:143], v[178:181], v[60:63]
	v_mfma_f32_16x16x32_bf16 v[56:59], v[148:151], v[178:181], v[56:59]
	v_mfma_f32_16x16x32_bf16 v[44:47], v[140:143], v[186:189], v[44:47]
	v_mfma_f32_16x16x32_bf16 v[40:43], v[148:151], v[186:189], v[40:43]
	v_mfma_f32_16x16x32_bf16 v[28:31], v[140:143], v[194:197], v[28:31]
	v_mfma_f32_16x16x32_bf16 v[24:27], v[148:151], v[194:197], v[24:27]
	v_mfma_f32_16x16x32_bf16 v[12:15], v[140:143], v[202:205], v[12:15]
	v_mfma_f32_16x16x32_bf16 v[8:11], v[148:151], v[202:205], v[8:11]
	v_mfma_f32_16x16x32_bf16 v[60:63], v[144:147], v[182:185], v[60:63]
	v_mfma_f32_16x16x32_bf16 v[56:59], v[152:155], v[182:185], v[56:59]
	v_mfma_f32_16x16x32_bf16 v[44:47], v[144:147], v[190:193], v[44:47]
	v_mfma_f32_16x16x32_bf16 v[40:43], v[152:155], v[190:193], v[40:43]
	v_mfma_f32_16x16x32_bf16 v[28:31], v[144:147], v[198:201], v[28:31]
	v_mfma_f32_16x16x32_bf16 v[24:27], v[152:155], v[198:201], v[24:27]
	v_mfma_f32_16x16x32_bf16 v[12:15], v[144:147], v[206:209], v[12:15]
	v_mfma_f32_16x16x32_bf16 v[8:11], v[152:155], v[206:209], v[8:11]
	s_setprio 0
	s_setprio 1
	v_mfma_f32_16x16x32_bf16 v[52:55], v[162:165], v[178:181], v[52:55]
	v_mfma_f32_16x16x32_bf16 v[48:51], v[170:173], v[178:181], v[48:51]
	v_mfma_f32_16x16x32_bf16 v[36:39], v[162:165], v[186:189], v[36:39]
	v_mfma_f32_16x16x32_bf16 v[32:35], v[170:173], v[186:189], v[32:35]
	v_mfma_f32_16x16x32_bf16 v[20:23], v[162:165], v[194:197], v[20:23]
	v_mfma_f32_16x16x32_bf16 v[16:19], v[170:173], v[194:197], v[16:19]
	v_mfma_f32_16x16x32_bf16 v[4:7], v[162:165], v[202:205], v[4:7]
	v_mfma_f32_16x16x32_bf16 v[0:3], v[170:173], v[202:205], v[0:3]
	v_mfma_f32_16x16x32_bf16 v[52:55], v[166:169], v[182:185], v[52:55]
	v_mfma_f32_16x16x32_bf16 v[48:51], v[174:177], v[182:185], v[48:51]
	v_mfma_f32_16x16x32_bf16 v[36:39], v[166:169], v[190:193], v[36:39]
	v_mfma_f32_16x16x32_bf16 v[32:35], v[174:177], v[190:193], v[32:35]
	v_mfma_f32_16x16x32_bf16 v[20:23], v[166:169], v[198:201], v[20:23]
	v_mfma_f32_16x16x32_bf16 v[16:19], v[174:177], v[198:201], v[16:19]
	v_mfma_f32_16x16x32_bf16 v[4:7], v[166:169], v[206:209], v[4:7]
	v_mfma_f32_16x16x32_bf16 v[0:3], v[174:177], v[206:209], v[0:3]
	s_setprio 0
	s_barrier
	s_add_i32 s50, s50, 2
	s_add_u32 s30, s30, 0x100
	s_addc_u32 s31, s31, 0
	s_add_u32 s48, s48, 0x100
	s_addc_u32 s49, s49, 0
	s_cmp_gt_u32 s50, 13

;     __device__ bool next(int i, Unit& u) const { if (r0 + i >= r1) return false; return base.next(r0 + i, u); }
;     __device__ bool next(int i, Unit& u) const { const int L = i * G + c; if (L >= 256) return false; u.pm = L; u.pn = L >> 3; return true; }
; #define PG8_STAGE(bufoff, gbase, voff) do { _Pragma("unroll") for (int _i = 0; _i < 2; ++_i) \
;         __builtin_amdgcn_global_load_lds((const unsigned*)((const char*)(gbase) + (voff)[_i]), (LAS unsigned*)(lds + (bufoff) + ldsw + _i * 8192), 16, 0, 0); } while (0)
; #define PG8_LDA(dst, b, h) do { _Pragma("unroll") for (int m = 0; m < 4; ++m) _Pragma("unroll") for (int k = 0; k < 2; ++k) dst[m][k] = *(const LAS bf16x8*)(lds + PG8_SA(b, h) + aoff + m * 2048 + k * 1024); } while (0)
; #define PG8_LDB(dst, b, h) do { _Pragma("unroll") for (int n = 0; n < 2; ++n) _Pragma("unroll") for (int k = 0; k < 2; ++k) dst[n][k] = *(const LAS bf16x8*)(lds + PG8_SB(b, h) + boff + n * 2048 + k * 1024); } while (0)
; template <class Epi, class Sched>
; __device__ __forceinline__ void gemm_phase(LAS unsigned char* lds, const Gemm g, const Sched& S, const Epi& E, int wave_id) {
;     ...
;         const bool has_next = S.next(ui + 1, nxt);
;         const char* nA = has_next ? (const char*)g.A + (size_t)nxt.pm * tstepA : cA; const char* nB = has_next ? (const char*)g.Bt + (size_t)nxt.pn * tstepB : cB;
;         for (int t = 0; t < nt; t += 2) {
;             const bool last = (t == nt - 2);
;             const char* a1 = cA + (size_t)(t + 1) * kstep;
;             const char* a2 = last ? nA : cA + (size_t)(t + 2) * kstep; const char* b2 = last ? nB : cB + (size_t)(t + 2) * kstep;
;             const char* a3 = a2 + kstep; const char* b3 = b2 + kstep;
;             PG8_LDB(B0, 0, 0); PG8_LDB(B1, 0, 1); PG8_SCHED; PG8_LDA(At, 0, 0); PG8_STAGE(PG8_SA(1, 1), a1 + hstepA, voffA);
;             PG8_WAIT_V(8); PG8_WAIT_L(0); PG8_BAR; PG8_MMA(0, 0, At, B0); PG8_MMA(0, 1, At, B1); PG8_BAR; PG8_SCHED;
;             PG8_LDA(At, 0, 1); PG8_STAGE(PG8_SB(0, 0), b2, voffB); PG8_STAGE(PG8_SB(0, 1), b2 + hstepB, voffB); PG8_STAGE(PG8_SA(0, 0), a2, voffA);
;     ...
;         for (int a = 0; a < 2; ++a)
; #pragma unroll
;             for (int b = 0; b < 2; ++b)
; #pragma unroll
;                 for (int m = 0; m < 4; ++m)
; #pragma unroll
;                     for (int n = 0; n < 2; ++n) acc[a][b][m][n] = (f32x4){0.f, 0.f, 0.f, 0.f};
.LBB0_959:
	s_ashr_i32 s17, s16, 31
	s_lshl_b64 s[18:19], s[16:17], 19
	s_add_u32 s18, s31, s18
	s_addc_u32 s19, s34, s19
	s_and_b64 s[20:21], s[4:5], exec
	s_cselect_b32 s17, s19, s25
	s_cselect_b32 s49, s18, s24
	s_ashr_i32 s15, s14, 31
	s_lshl_b64 s[20:21], s[14:15], 19
	s_add_u32 s20, s35, s20
	s_addc_u32 s21, s36, s21
	s_and_b64 s[28:29], s[4:5], exec
	s_cselect_b32 s15, s21, s27
	s_cselect_b32 s50, s20, s26
	s_add_u32 s24, s24, 0x40080
	s_addc_u32 s25, s25, 0
	s_add_u32 s51, s26, 0x100
	s_addc_u32 s52, s27, 0
	s_mov_b32 s53, -2
	ds_read_b128 v[156:159], v151
	ds_read_b128 v[160:163], v151 offset:1024
	ds_read_b128 v[164:167], v151 offset:2048
	ds_read_b128 v[168:171], v151 offset:3072
	ds_read_b128 v[172:175], v152
	ds_read_b128 v[176:179], v152 offset:1024
	ds_read_b128 v[180:183], v152 offset:2048
	ds_read_b128 v[184:187], v152 offset:3072
	s_add_u32 s26, s24, 0xfffc0080
	s_addc_u32 s27, s25, -1
	s_cmp_eq_u32 s53, 12
	s_cselect_b32 s29, s17, s27
	s_cselect_b32 s28, s49, s26
	s_cselect_b32 s27, s15, s52
	s_cselect_b32 s26, s50, s51
	v_lshl_add_u64 v[220:221], s[24:25], 0, v[142:143]
	s_add_i32 m0, s37, 0xc000
	ds_read_b128 v[188:191], v153
	ds_read_b128 v[192:195], v153 offset:1024
	ds_read_b128 v[196:199], v153 offset:2048
	ds_read_b128 v[200:203], v153 offset:3072
	ds_read_b128 v[204:207], v153 offset:4096
	ds_read_b128 v[208:211], v153 offset:5120
	ds_read_b128 v[212:215], v153 offset:6144
	ds_read_b128 v[216:219], v153 offset:7168
	global_load_lds_dwordx4 v[220:221], off
	v_lshl_add_u64 v[220:221], s[24:25], 0, v[144:145]
	s_add_i32 m0, s37, 0xe000
	s_nop 0
	global_load_lds_dwordx4 v[220:221], off
	s_waitcnt vmcnt(8)
	s_waitcnt lgkmcnt(0)
	s_barrier
	s_setprio 1
	s_waitcnt lgkmcnt(0)
	v_mfma_f32_16x16x32_bf16 v[124:127], v[156:159], v[188:191], 0
	v_mfma_f32_16x16x32_bf16 v[120:123], v[164:167], v[188:191], 0
	v_mfma_f32_16x16x32_bf16 v[108:111], v[156:159], v[196:199], 0
	v_mfma_f32_16x16x32_bf16 v[104:107], v[164:167], v[196:199], 0
	v_mfma_f32_16x16x32_bf16 v[92:95], v[156:159], v[204:207], 0
	v_mfma_f32_16x16x32_bf16 v[88:91], v[164:167], v[204:207], 0
	v_mfma_f32_16x16x32_bf16 v[76:79], v[156:159], v[212:215], 0
	v_mfma_f32_16x16x32_bf16 v[72:75], v[164:167], v[212:215], 0
	v_mfma_f32_16x16x32_bf16 v[124:127], v[160:163], v[192:195], v[124:127]
	v_mfma_f32_16x16x32_bf16 v[120:123], v[168:171], v[192:195], v[120:123]
	v_mfma_f32_16x16x32_bf16 v[108:111], v[160:163], v[200:203], v[108:111]
	v_mfma_f32_16x16x32_bf16 v[104:107], v[168:171], v[200:203], v[104:107]
	v_mfma_f32_16x16x32_bf16 v[92:95], v[160:163], v[208:211], v[92:95]
	v_mfma_f32_16x16x32_bf16 v[88:91], v[168:171], v[208:211], v[88:91]
	v_mfma_f32_16x16x32_bf16 v[76:79], v[160:163], v[216:219], v[76:79]
	v_mfma_f32_16x16x32_bf16 v[72:75], v[168:171], v[216:219], v[72:75]
	s_setprio 0
	s_setprio 1
	v_mfma_f32_16x16x32_bf16 v[116:119], v[172:175], v[188:191], 0
	v_mfma_f32_16x16x32_bf16 v[112:115], v[180:183], v[188:191], 0
	v_mfma_f32_16x16x32_bf16 v[100:103], v[172:175], v[196:199], 0
	v_mfma_f32_16x16x32_bf16 v[96:99], v[180:183], v[196:199], 0
	v_mfma_f32_16x16x32_bf16 v[84:87], v[172:175], v[204:207], 0
	v_mfma_f32_16x16x32_bf16 v[80:83], v[180:183], v[204:207], 0
	v_mfma_f32_16x16x32_bf16 v[68:71], v[172:175], v[212:215], 0
	v_mfma_f32_16x16x32_bf16 v[64:67], v[180:183], v[212:215], 0
	v_mfma_f32_16x16x32_bf16 v[116:119], v[176:179], v[192:195], v[116:119]
	v_mfma_f32_16x16x32_bf16 v[112:115], v[184:187], v[192:195], v[112:115]
	v_mfma_f32_16x16x32_bf16 v[100:103], v[176:179], v[200:203], v[100:103]
	v_mfma_f32_16x16x32_bf16 v[96:99], v[184:187], v[200:203], v[96:99]
	v_mfma_f32_16x16x32_bf16 v[84:87], v[176:179], v[208:211], v[84:87]
	v_mfma_f32_16x16x32_bf16 v[80:83], v[184:187], v[208:211], v[80:83]
	v_mfma_f32_16x16x32_bf16 v[68:71], v[176:179], v[216:219], v[68:71]
	v_mfma_f32_16x16x32_bf16 v[64:67], v[184:187], v[216:219], v[64:67]
	s_setprio 0
	s_barrier
	s_add_i32 s54, s47, s2
	v_lshl_add_u64 v[220:221], s[26:27], 0, v[130:131]
	s_mov_b32 m0, s54
	ds_read_b128 v[188:191], v153 offset:16384
	ds_read_b128 v[192:195], v153 offset:17408
	ds_read_b128 v[196:199], v153 offset:18432
	ds_read_b128 v[200:203], v153 offset:19456
	ds_read_b128 v[204:207], v153 offset:20480
	ds_read_b128 v[208:211], v153 offset:21504
	ds_read_b128 v[212:215], v153 offset:22528
	ds_read_b128 v[216:219], v153 offset:23552
	global_load_lds_dwordx4 v[220:221], off
	s_add_i32 m0, s54, 0x2000
	s_add_u32 s54, s26, 0x40000
	v_lshl_add_u64 v[222:223], s[26:27], 0, v[134:135]
	s_addc_u32 s55, s27, 0
	s_add_i32 s58, s48, s2
	global_load_lds_dwordx4 v[222:223], off
	v_lshl_add_u64 v[224:225], s[54:55], 0, v[130:131]
	s_mov_b32 m0, s58
	v_lshl_add_u64 v[226:227], s[28:29], 0, v[132:133]
	global_load_lds_dwordx4 v[224:225], off
	v_lshl_add_u64 v[224:225], s[54:55], 0, v[134:135]
	s_add_i32 m0, s58, 0x2000
	s_nop 0
	global_load_lds_dwordx4 v[224:225], off
	v_lshl_add_u64 v[224:225], s[28:29], 0, v[128:129]
	s_mov_b32 m0, s37
	s_nop 0
	global_load_lds_dwordx4 v[224:225], off
	s_mov_b32 m0, s38
	s_nop 0
	global_load_lds_dwordx4 v[226:227], off
	s_waitcnt vmcnt(8)
	s_waitcnt lgkmcnt(0)
	s_barrier
; #define PG8_STAGE(bufoff, gbase, voff) do { _Pragma("unroll") for (int _i = 0; _i < 2; ++_i) \
;         __builtin_amdgcn_global_load_lds((const unsigned*)((const char*)(gbase) + (voff)[_i]), (LAS unsigned*)(lds + (bufoff) + ldsw + _i * 8192), 16, 0, 0); } while (0)
; #define PG8_LDA(dst, b, h) do { _Pragma("unroll") for (int m = 0; m < 4; ++m) _Pragma("unroll") for (int k = 0; k < 2; ++k) dst[m][k] = *(const LAS bf16x8*)(lds + PG8_SA(b, h) + aoff + m * 2048 + k * 1024); } while (0)
; #define PG8_LDB(dst, b, h) do { _Pragma("unroll") for (int n = 0; n < 2; ++n) _Pragma("unroll") for (int k = 0; k < 2; ++k) dst[n][k] = *(const LAS bf16x8*)(lds + PG8_SB(b, h) + boff + n * 2048 + k * 1024); } while (0)
; #define PG8_MMA(ai, bj, At, Bt) do { __builtin_amdgcn_s_setprio(1); _Pragma("unroll") for (int m = 0; m < 4; ++m) _Pragma("unroll") for (int n = 0; n < 2; ++n) _Pragma("unroll") for (int k = 0; k < 2; ++k) \
;         acc[ai][bj][m][n] = __builtin_amdgcn_mfma_f32_16x16x32_bf16(Bt[n][k], At[m][k], acc[ai][bj][m][n], 0, 0, 0); __builtin_amdgcn_s_setprio(0); } while (0)
; #define PG8_WAIT_V(n) asm volatile("s_waitcnt vmcnt(" #n ")" ::: "memory")
; #define PG8_WAIT_L(n) asm volatile("s_waitcnt lgkmcnt(" #n ")" ::: "memory")
; #define PG8_BAR __builtin_amdgcn_s_barrier()
; #define PG8_SCHED __builtin_amdgcn_sched_barrier(0)
; template <class Epi, class Sched>
; __device__ __forceinline__ void gemm_phase(LAS unsigned char* lds, const Gemm g, const Sched& S, const Epi& E, int wave_id) {
;     ...
;             PG8_WAIT_V(8); PG8_WAIT_L(0); PG8_BAR; PG8_MMA(1, 0, At, B0); PG8_MMA(1, 1, At, B1); PG8_BAR; PG8_SCHED;
;             PG8_LDB(B0, 1, 0); PG8_LDB(B1, 1, 1); PG8_SCHED; PG8_LDA(At, 1, 0); PG8_STAGE(PG8_SA(0, 1), a2 + hstepA, voffA);
;             PG8_WAIT_V(8); PG8_WAIT_L(0); PG8_BAR; PG8_MMA(0, 0, At, B0); PG8_MMA(0, 1, At, B1); PG8_BAR; PG8_SCHED;
	s_setprio 1
	s_waitcnt lgkmcnt(0)
	v_mfma_f32_16x16x32_bf16 v[60:63], v[156:159], v[188:191], 0
	v_mfma_f32_16x16x32_bf16 v[56:59], v[164:167], v[188:191], 0
	v_mfma_f32_16x16x32_bf16 v[44:47], v[156:159], v[196:199], 0
	v_mfma_f32_16x16x32_bf16 v[40:43], v[164:167], v[196:199], 0
	v_mfma_f32_16x16x32_bf16 v[28:31], v[156:159], v[204:207], 0
	v_mfma_f32_16x16x32_bf16 v[24:27], v[164:167], v[204:207], 0
	v_mfma_f32_16x16x32_bf16 v[12:15], v[156:159], v[212:215], 0
	v_mfma_f32_16x16x32_bf16 v[8:11], v[164:167], v[212:215], 0
	v_mfma_f32_16x16x32_bf16 v[60:63], v[160:163], v[192:195], v[60:63]
	v_mfma_f32_16x16x32_bf16 v[56:59], v[168:171], v[192:195], v[56:59]
	v_mfma_f32_16x16x32_bf16 v[44:47], v[160:163], v[200:203], v[44:47]
	v_mfma_f32_16x16x32_bf16 v[40:43], v[168:171], v[200:203], v[40:43]
	v_mfma_f32_16x16x32_bf16 v[28:31], v[160:163], v[208:211], v[28:31]
	v_mfma_f32_16x16x32_bf16 v[24:27], v[168:171], v[208:211], v[24:27]
	v_mfma_f32_16x16x32_bf16 v[12:15], v[160:163], v[216:219], v[12:15]
	v_mfma_f32_16x16x32_bf16 v[8:11], v[168:171], v[216:219], v[8:11]
	s_setprio 0
	s_setprio 1
	v_mfma_f32_16x16x32_bf16 v[52:55], v[172:175], v[188:191], 0
	v_mfma_f32_16x16x32_bf16 v[48:51], v[180:183], v[188:191], 0
	v_mfma_f32_16x16x32_bf16 v[36:39], v[172:175], v[196:199], 0
	v_mfma_f32_16x16x32_bf16 v[32:35], v[180:183], v[196:199], 0
	v_mfma_f32_16x16x32_bf16 v[20:23], v[172:175], v[204:207], 0
	v_mfma_f32_16x16x32_bf16 v[16:19], v[180:183], v[204:207], 0
	v_mfma_f32_16x16x32_bf16 v[4:7], v[172:175], v[212:215], 0
	v_mfma_f32_16x16x32_bf16 v[0:3], v[180:183], v[212:215], 0
	v_mfma_f32_16x16x32_bf16 v[52:55], v[176:179], v[192:195], v[52:55]
	v_mfma_f32_16x16x32_bf16 v[48:51], v[184:187], v[192:195], v[48:51]
	v_mfma_f32_16x16x32_bf16 v[36:39], v[176:179], v[200:203], v[36:39]
	v_mfma_f32_16x16x32_bf16 v[32:35], v[184:187], v[200:203], v[32:35]
	v_mfma_f32_16x16x32_bf16 v[20:23], v[176:179], v[208:211], v[20:23]
	v_mfma_f32_16x16x32_bf16 v[16:19], v[184:187], v[208:211], v[16:19]
	v_mfma_f32_16x16x32_bf16 v[4:7], v[176:179], v[216:219], v[4:7]
	v_mfma_f32_16x16x32_bf16 v[0:3], v[184:187], v[216:219], v[0:3]
	s_setprio 0
	s_barrier
	s_add_i32 s54, 0, 0x18000
	s_add_i32 s55, 0, 0x1c000
	v_add_u32_e32 v168, s54, v150
	v_add_u32_e32 v184, s55, v150
	ds_read_b128 v[156:159], v168
	ds_read_b128 v[160:163], v168 offset:1024
	ds_read_b128 v[164:167], v168 offset:2048
	ds_read_b128 v[168:171], v168 offset:3072
	ds_read_b128 v[172:175], v184
	ds_read_b128 v[176:179], v184 offset:1024
	ds_read_b128 v[180:183], v184 offset:2048
	ds_read_b128 v[184:187], v184 offset:3072
	s_add_u32 s28, s28, 0x40000
	s_addc_u32 s29, s29, 0
	s_mov_b32 m0, s39
	v_lshl_add_u64 v[228:229], s[28:29], 0, v[128:129]
	ds_read_b128 v[188:191], v153 offset:32768
	ds_read_b128 v[192:195], v153 offset:33792
	ds_read_b128 v[196:199], v153 offset:34816
	ds_read_b128 v[200:203], v153 offset:35840
	ds_read_b128 v[204:207], v153 offset:36864
	ds_read_b128 v[208:211], v153 offset:37888
	ds_read_b128 v[212:215], v153 offset:38912
	ds_read_b128 v[216:219], v153 offset:39936
	global_load_lds_dwordx4 v[228:229], off
	v_lshl_add_u64 v[228:229], s[28:29], 0, v[132:133]
	s_mov_b32 m0, s40
	s_nop 0
	global_load_lds_dwordx4 v[228:229], off
	s_waitcnt vmcnt(8)
	s_waitcnt lgkmcnt(0)
	s_barrier
	s_setprio 1
	s_waitcnt lgkmcnt(0)
	v_mfma_f32_16x16x32_bf16 v[124:127], v[156:159], v[188:191], v[124:127]
	v_mfma_f32_16x16x32_bf16 v[120:123], v[164:167], v[188:191], v[120:123]
	v_mfma_f32_16x16x32_bf16 v[108:111], v[156:159], v[196:199], v[108:111]
	v_mfma_f32_16x16x32_bf16 v[104:107], v[164:167], v[196:199], v[104:107]
	v_mfma_f32_16x16x32_bf16 v[92:95], v[156:159], v[204:207], v[92:95]
	v_mfma_f32_16x16x32_bf16 v[88:91], v[164:167], v[204:207], v[88:91]
	v_mfma_f32_16x16x32_bf16 v[76:79], v[156:159], v[212:215], v[76:79]
	v_mfma_f32_16x16x32_bf16 v[72:75], v[164:167], v[212:215], v[72:75]
	v_mfma_f32_16x16x32_bf16 v[124:127], v[160:163], v[192:195], v[124:127]
	v_mfma_f32_16x16x32_bf16 v[120:123], v[168:171], v[192:195], v[120:123]
	v_mfma_f32_16x16x32_bf16 v[108:111], v[160:163], v[200:203], v[108:111]
	v_mfma_f32_16x16x32_bf16 v[104:107], v[168:171], v[200:203], v[104:107]
	v_mfma_f32_16x16x32_bf16 v[92:95], v[160:163], v[208:211], v[92:95]
	v_mfma_f32_16x16x32_bf16 v[88:91], v[168:171], v[208:211], v[88:91]
	v_mfma_f32_16x16x32_bf16 v[76:79], v[160:163], v[216:219], v[76:79]
	v_mfma_f32_16x16x32_bf16 v[72:75], v[168:171], v[216:219], v[72:75]
	s_setprio 0
	s_setprio 1
	v_mfma_f32_16x16x32_bf16 v[116:119], v[172:175], v[188:191], v[116:119]
	v_mfma_f32_16x16x32_bf16 v[112:115], v[180:183], v[188:191], v[112:115]
	v_mfma_f32_16x16x32_bf16 v[100:103], v[172:175], v[196:199], v[100:103]
	v_mfma_f32_16x16x32_bf16 v[96:99], v[180:183], v[196:199], v[96:99]
	v_mfma_f32_16x16x32_bf16 v[84:87], v[172:175], v[204:207], v[84:87]
	v_mfma_f32_16x16x32_bf16 v[80:83], v[180:183], v[204:207], v[80:83]
	v_mfma_f32_16x16x32_bf16 v[68:71], v[172:175], v[212:215], v[68:71]
	v_mfma_f32_16x16x32_bf16 v[64:67], v[180:183], v[212:215], v[64:67]
	v_mfma_f32_16x16x32_bf16 v[116:119], v[176:179], v[192:195], v[116:119]
	v_mfma_f32_16x16x32_bf16 v[112:115], v[184:187], v[192:195], v[112:115]
	v_mfma_f32_16x16x32_bf16 v[100:103], v[176:179], v[200:203], v[100:103]
	v_mfma_f32_16x16x32_bf16 v[96:99], v[184:187], v[200:203], v[96:99]
	v_mfma_f32_16x16x32_bf16 v[84:87], v[176:179], v[208:211], v[84:87]
	v_mfma_f32_16x16x32_bf16 v[80:83], v[184:187], v[208:211], v[80:83]
	v_mfma_f32_16x16x32_bf16 v[68:71], v[176:179], v[216:219], v[68:71]
	v_mfma_f32_16x16x32_bf16 v[64:67], v[184:187], v[216:219], v[64:67]
	s_setprio 0
	s_barrier
; #define PG8_STAGE(bufoff, gbase, voff) do { _Pragma("unroll") for (int _i = 0; _i < 2; ++_i) \
;         __builtin_amdgcn_global_load_lds((const unsigned*)((const char*)(gbase) + (voff)[_i]), (LAS unsigned*)(lds + (bufoff) + ldsw + _i * 8192), 16, 0, 0); } while (0)
; #define PG8_LDA(dst, b, h) do { _Pragma("unroll") for (int m = 0; m < 4; ++m) _Pragma("unroll") for (int k = 0; k < 2; ++k) dst[m][k] = *(const LAS bf16x8*)(lds + PG8_SA(b, h) + aoff + m * 2048 + k * 1024); } while (0)
; #define PG8_MMA(ai, bj, At, Bt) do { __builtin_amdgcn_s_setprio(1); _Pragma("unroll") for (int m = 0; m < 4; ++m) _Pragma("unroll") for (int n = 0; n < 2; ++n) _Pragma("unroll") for (int k = 0; k < 2; ++k) \
;         acc[ai][bj][m][n] = __builtin_amdgcn_mfma_f32_16x16x32_bf16(Bt[n][k], At[m][k], acc[ai][bj][m][n], 0, 0, 0); __builtin_amdgcn_s_setprio(0); } while (0)
; #define PG8_WAIT_V(n) asm volatile("s_waitcnt vmcnt(" #n ")" ::: "memory")
; #define PG8_WAIT_L(n) asm volatile("s_waitcnt lgkmcnt(" #n ")" ::: "memory")
; #define PG8_BAR __builtin_amdgcn_s_barrier()
; #define PG8_SCHED __builtin_amdgcn_sched_barrier(0)
; template <class Epi, class Sched>
; __device__ __forceinline__ void gemm_phase(LAS unsigned char* lds, const Gemm g, const Sched& S, const Epi& E, int wave_id) {
;     ...
;             PG8_LDA(At, 1, 1); PG8_STAGE(PG8_SB(1, 0), b3, voffB); PG8_STAGE(PG8_SB(1, 1), b3 + hstepB, voffB); PG8_STAGE(PG8_SA(1, 0), a3, voffA);
;             PG8_WAIT_V(8); PG8_WAIT_L(0); PG8_BAR; PG8_MMA(1, 0, At, B0); PG8_MMA(1, 1, At, B1); PG8_BAR; PG8_SCHED;
;         }
	s_add_i32 s28, s54, s2
	v_lshl_add_u64 v[220:221], v[220:221], 0, s[10:11]
	s_mov_b32 m0, s28
	ds_read_b128 v[188:191], v153 offset:49152
	ds_read_b128 v[192:195], v153 offset:50176
	ds_read_b128 v[196:199], v153 offset:51200
	ds_read_b128 v[200:203], v153 offset:52224
	ds_read_b128 v[204:207], v153 offset:53248
	ds_read_b128 v[208:211], v153 offset:54272
	ds_read_b128 v[212:215], v153 offset:55296
	ds_read_b128 v[216:219], v153 offset:56320
	global_load_lds_dwordx4 v[220:221], off
	s_add_i32 m0, s28, 0x2000
	s_add_u32 s26, s26, 0x40080
	v_lshl_add_u64 v[220:221], v[222:223], 0, s[10:11]
	s_addc_u32 s27, s27, 0
	s_add_i32 s28, s55, s2
	global_load_lds_dwordx4 v[220:221], off
	v_lshl_add_u64 v[220:221], s[26:27], 0, v[130:131]
	s_mov_b32 m0, s28
	s_nop 0
	global_load_lds_dwordx4 v[220:221], off
	v_lshl_add_u64 v[220:221], s[26:27], 0, v[134:135]
	s_add_i32 m0, s28, 0x2000
	s_nop 0
	global_load_lds_dwordx4 v[220:221], off
	v_lshl_add_u64 v[220:221], v[224:225], 0, s[10:11]
	s_mov_b32 m0, s45
	s_nop 0
	global_load_lds_dwordx4 v[220:221], off
	v_lshl_add_u64 v[220:221], v[226:227], 0, s[10:11]
	s_mov_b32 m0, s46
	s_nop 0
	global_load_lds_dwordx4 v[220:221], off
	s_waitcnt vmcnt(8)
	s_waitcnt lgkmcnt(0)
	s_barrier
	s_setprio 1
	s_waitcnt lgkmcnt(0)
	v_mfma_f32_16x16x32_bf16 v[60:63], v[156:159], v[188:191], v[60:63]
	v_mfma_f32_16x16x32_bf16 v[56:59], v[164:167], v[188:191], v[56:59]
	v_mfma_f32_16x16x32_bf16 v[44:47], v[156:159], v[196:199], v[44:47]
	v_mfma_f32_16x16x32_bf16 v[40:43], v[164:167], v[196:199], v[40:43]
	v_mfma_f32_16x16x32_bf16 v[28:31], v[156:159], v[204:207], v[28:31]
	v_mfma_f32_16x16x32_bf16 v[24:27], v[164:167], v[204:207], v[24:27]
	v_mfma_f32_16x16x32_bf16 v[12:15], v[156:159], v[212:215], v[12:15]
	v_mfma_f32_16x16x32_bf16 v[8:11], v[164:167], v[212:215], v[8:11]
	v_mfma_f32_16x16x32_bf16 v[60:63], v[160:163], v[192:195], v[60:63]
	v_mfma_f32_16x16x32_bf16 v[56:59], v[168:171], v[192:195], v[56:59]
	v_mfma_f32_16x16x32_bf16 v[44:47], v[160:163], v[200:203], v[44:47]
	v_mfma_f32_16x16x32_bf16 v[40:43], v[168:171], v[200:203], v[40:43]
	v_mfma_f32_16x16x32_bf16 v[28:31], v[160:163], v[208:211], v[28:31]
	v_mfma_f32_16x16x32_bf16 v[24:27], v[168:171], v[208:211], v[24:27]
	v_mfma_f32_16x16x32_bf16 v[12:15], v[160:163], v[216:219], v[12:15]
	v_mfma_f32_16x16x32_bf16 v[8:11], v[168:171], v[216:219], v[8:11]
	s_setprio 0
	s_setprio 1
	v_mfma_f32_16x16x32_bf16 v[52:55], v[172:175], v[188:191], v[52:55]
	v_mfma_f32_16x16x32_bf16 v[48:51], v[180:183], v[188:191], v[48:51]
	v_mfma_f32_16x16x32_bf16 v[36:39], v[172:175], v[196:199], v[36:39]
	v_mfma_f32_16x16x32_bf16 v[32:35], v[180:183], v[196:199], v[32:35]
	v_mfma_f32_16x16x32_bf16 v[20:23], v[172:175], v[204:207], v[20:23]
	v_mfma_f32_16x16x32_bf16 v[16:19], v[180:183], v[204:207], v[16:19]
	v_mfma_f32_16x16x32_bf16 v[4:7], v[172:175], v[212:215], v[4:7]
	v_mfma_f32_16x16x32_bf16 v[0:3], v[180:183], v[212:215], v[0:3]
	v_mfma_f32_16x16x32_bf16 v[52:55], v[176:179], v[192:195], v[52:55]
	v_mfma_f32_16x16x32_bf16 v[48:51], v[184:187], v[192:195], v[48:51]
	v_mfma_f32_16x16x32_bf16 v[36:39], v[176:179], v[200:203], v[36:39]
	v_mfma_f32_16x16x32_bf16 v[32:35], v[184:187], v[200:203], v[32:35]
	v_mfma_f32_16x16x32_bf16 v[20:23], v[176:179], v[208:211], v[20:23]
	v_mfma_f32_16x16x32_bf16 v[16:19], v[184:187], v[208:211], v[16:19]
	v_mfma_f32_16x16x32_bf16 v[4:7], v[176:179], v[216:219], v[4:7]
	v_mfma_f32_16x16x32_bf16 v[0:3], v[184:187], v[216:219], v[0:3]
	s_setprio 0
	s_barrier
	s_add_i32 s53, s53, 2
	s_add_u32 s24, s24, 0x100
	s_addc_u32 s25, s25, 0
	s_add_u32 s51, s51, 0x100
	s_addc_u32 s52, s52, 0
	s_cmp_gt_u32 s53, 13

;     __device__ bool next(int i, Unit& u) const { if (r0 + i >= r1) return false; return base.next(r0 + i, u); }
;     __device__ bool next(int i, Unit& u) const { const int L = i * G + c; if (L >= 256) return false; u.pm = L; u.pn = L >> 3; return true; }
; #define PG8_STAGE(bufoff, gbase, voff) do { _Pragma("unroll") for (int _i = 0; _i < 2; ++_i) \
;         __builtin_amdgcn_global_load_lds((const unsigned*)((const char*)(gbase) + (voff)[_i]), (LAS unsigned*)(lds + (bufoff) + ldsw + _i * 8192), 16, 0, 0); } while (0)
; #define PG8_LDA(dst, b, h) do { _Pragma("unroll") for (int m = 0; m < 4; ++m) _Pragma("unroll") for (int k = 0; k < 2; ++k) dst[m][k] = *(const LAS bf16x8*)(lds + PG8_SA(b, h) + aoff + m * 2048 + k * 1024); } while (0)
; #define PG8_LDB(dst, b, h) do { _Pragma("unroll") for (int n = 0; n < 2; ++n) _Pragma("unroll") for (int k = 0; k < 2; ++k) dst[n][k] = *(const LAS bf16x8*)(lds + PG8_SB(b, h) + boff + n * 2048 + k * 1024); } while (0)
; template <class Epi, class Sched>
; __device__ __forceinline__ void gemm_phase(LAS unsigned char* lds, const Gemm g, const Sched& S, const Epi& E, int wave_id) {
;     ...
;         const bool has_next = S.next(ui + 1, nxt);
;         const char* nA = has_next ? (const char*)g.A + (size_t)nxt.pm * tstepA : cA; const char* nB = has_next ? (const char*)g.Bt + (size_t)nxt.pn * tstepB : cB;
;         for (int t = 0; t < nt; t += 2) {
;             const bool last = (t == nt - 2);
;             const char* a1 = cA + (size_t)(t + 1) * kstep;
;             const char* a2 = last ? nA : cA + (size_t)(t + 2) * kstep; const char* b2 = last ? nB : cB + (size_t)(t + 2) * kstep;
;             const char* a3 = a2 + kstep; const char* b3 = b2 + kstep;
;             PG8_LDB(B0, 0, 0); PG8_LDB(B1, 0, 1); PG8_SCHED; PG8_LDA(At, 0, 0); PG8_STAGE(PG8_SA(1, 1), a1 + hstepA, voffA);
;             PG8_WAIT_V(8); PG8_WAIT_L(0); PG8_BAR; PG8_MMA(0, 0, At, B0); PG8_MMA(0, 1, At, B1); PG8_BAR; PG8_SCHED;
;             PG8_LDA(At, 0, 1); PG8_STAGE(PG8_SB(0, 0), b2, voffB); PG8_STAGE(PG8_SB(0, 1), b2 + hstepB, voffB); PG8_STAGE(PG8_SA(0, 0), a2, voffA);
;     ...
;         for (int a = 0; a < 2; ++a)
; #pragma unroll
;             for (int b = 0; b < 2; ++b)
; #pragma unroll
;                 for (int m = 0; m < 4; ++m)
; #pragma unroll
;                     for (int n = 0; n < 2; ++n) acc[a][b][m][n] = (f32x4){0.f, 0.f, 0.f, 0.f};
.LBB0_1040:
	s_ashr_i32 s19, s18, 31
	s_lshl_b64 s[20:21], s[18:19], 18
	s_add_u32 s20, s3, s20
	s_addc_u32 s21, s33, s21
	s_and_b64 s[22:23], s[4:5], exec
	s_cselect_b32 s19, s21, s27
	s_cselect_b32 s48, s20, s26
	s_ashr_i32 s17, s16, 31
	s_lshl_b64 s[22:23], s[16:17], 18
	s_add_u32 s22, s34, s22
	s_addc_u32 s23, s35, s23
	s_and_b64 s[30:31], s[4:5], exec
	s_cselect_b32 s17, s23, s29
	s_cselect_b32 s49, s22, s28
	s_add_u32 s26, s26, 0x20080
	s_addc_u32 s27, s27, 0
	s_add_u32 s50, s28, 0x100
	s_addc_u32 s51, s29, 0
	s_mov_b32 s52, -2
	s_waitcnt vmcnt(0)
	ds_read_b128 v[116:119], v201
	ds_read_b128 v[120:123], v201 offset:1024
	ds_read_b128 v[124:127], v201 offset:2048
	ds_read_b128 v[136:139], v201 offset:3072
	ds_read_b128 v[140:143], v202
	ds_read_b128 v[148:151], v202 offset:1024
	ds_read_b128 v[152:155], v202 offset:2048
	ds_read_b128 v[156:159], v202 offset:3072
	s_add_u32 s28, s26, 0xfffe0080
	s_addc_u32 s29, s27, -1
	s_cmp_eq_u32 s52, 4
	s_cselect_b32 s31, s19, s29
	s_cselect_b32 s30, s48, s28
	s_cselect_b32 s29, s17, s51
	s_cselect_b32 s28, s49, s50
	v_lshl_add_u64 v[216:217], s[26:27], 0, v[178:179]
	s_add_i32 m0, s25, 0xc000
	ds_read_b128 v[160:163], v203
	ds_read_b128 v[164:167], v203 offset:1024
	ds_read_b128 v[186:189], v203 offset:2048
	ds_read_b128 v[190:193], v203 offset:3072
	ds_read_b128 v[194:197], v203 offset:4096
	ds_read_b128 v[204:207], v203 offset:5120
	ds_read_b128 v[208:211], v203 offset:6144
	ds_read_b128 v[212:215], v203 offset:7168
	global_load_lds_dwordx4 v[216:217], off
	v_lshl_add_u64 v[216:217], s[26:27], 0, v[180:181]
	s_add_i32 m0, s25, 0xe000
	s_nop 0
	global_load_lds_dwordx4 v[216:217], off
	s_waitcnt vmcnt(8)
	s_waitcnt lgkmcnt(0)
	s_barrier
	s_setprio 1
	s_waitcnt lgkmcnt(0)
	v_mfma_f32_16x16x32_bf16 v[144:147], v[116:119], v[160:163], 0
	v_mfma_f32_16x16x32_bf16 v[128:131], v[124:127], v[160:163], 0
	v_mfma_f32_16x16x32_bf16 v[108:111], v[116:119], v[186:189], 0
	v_mfma_f32_16x16x32_bf16 v[100:103], v[124:127], v[186:189], 0
	v_mfma_f32_16x16x32_bf16 v[92:95], v[116:119], v[194:197], 0
	v_mfma_f32_16x16x32_bf16 v[84:87], v[124:127], v[194:197], 0
	v_mfma_f32_16x16x32_bf16 v[76:79], v[116:119], v[208:211], 0
	v_mfma_f32_16x16x32_bf16 v[68:71], v[124:127], v[208:211], 0
	v_mfma_f32_16x16x32_bf16 v[144:147], v[120:123], v[164:167], v[144:147]
	v_mfma_f32_16x16x32_bf16 v[128:131], v[136:139], v[164:167], v[128:131]
	v_mfma_f32_16x16x32_bf16 v[108:111], v[120:123], v[190:193], v[108:111]
	v_mfma_f32_16x16x32_bf16 v[100:103], v[136:139], v[190:193], v[100:103]
	v_mfma_f32_16x16x32_bf16 v[92:95], v[120:123], v[204:207], v[92:95]
	v_mfma_f32_16x16x32_bf16 v[84:87], v[136:139], v[204:207], v[84:87]
	v_mfma_f32_16x16x32_bf16 v[76:79], v[120:123], v[212:215], v[76:79]
	v_mfma_f32_16x16x32_bf16 v[68:71], v[136:139], v[212:215], v[68:71]
	s_setprio 0
	s_setprio 1
	v_mfma_f32_16x16x32_bf16 v[132:135], v[140:143], v[160:163], 0
	v_mfma_f32_16x16x32_bf16 v[112:115], v[152:155], v[160:163], 0
	v_mfma_f32_16x16x32_bf16 v[104:107], v[140:143], v[186:189], 0
	v_mfma_f32_16x16x32_bf16 v[96:99], v[152:155], v[186:189], 0
	v_mfma_f32_16x16x32_bf16 v[88:91], v[140:143], v[194:197], 0
	v_mfma_f32_16x16x32_bf16 v[80:83], v[152:155], v[194:197], 0
	v_mfma_f32_16x16x32_bf16 v[72:75], v[140:143], v[208:211], 0
	v_mfma_f32_16x16x32_bf16 v[64:67], v[152:155], v[208:211], 0
	v_mfma_f32_16x16x32_bf16 v[132:135], v[148:151], v[164:167], v[132:135]
	v_mfma_f32_16x16x32_bf16 v[112:115], v[156:159], v[164:167], v[112:115]
	v_mfma_f32_16x16x32_bf16 v[104:107], v[148:151], v[190:193], v[104:107]
	v_mfma_f32_16x16x32_bf16 v[96:99], v[156:159], v[190:193], v[96:99]
	v_mfma_f32_16x16x32_bf16 v[88:91], v[148:151], v[204:207], v[88:91]
	v_mfma_f32_16x16x32_bf16 v[80:83], v[156:159], v[204:207], v[80:83]
	v_mfma_f32_16x16x32_bf16 v[72:75], v[148:151], v[212:215], v[72:75]
	v_mfma_f32_16x16x32_bf16 v[64:67], v[156:159], v[212:215], v[64:67]
	s_setprio 0
	s_barrier
	s_add_i32 s53, s45, s36
	v_lshl_add_u64 v[216:217], s[28:29], 0, v[170:171]
	s_mov_b32 m0, s53
	ds_read_b128 v[160:163], v203 offset:16384
	ds_read_b128 v[164:167], v203 offset:17408
	ds_read_b128 v[186:189], v203 offset:18432
	ds_read_b128 v[190:193], v203 offset:19456
	ds_read_b128 v[194:197], v203 offset:20480
	ds_read_b128 v[204:207], v203 offset:21504
	ds_read_b128 v[208:211], v203 offset:22528
	ds_read_b128 v[212:215], v203 offset:23552
	global_load_lds_dwordx4 v[216:217], off
	s_add_i32 m0, s53, 0x2000
	s_add_u32 s54, s28, 0x20000
	v_lshl_add_u64 v[218:219], s[28:29], 0, v[174:175]
	s_addc_u32 s55, s29, 0
	s_add_i32 s53, s46, s36
	global_load_lds_dwordx4 v[218:219], off
	v_lshl_add_u64 v[220:221], s[54:55], 0, v[170:171]
	s_mov_b32 m0, s53
	v_lshl_add_u64 v[222:223], s[30:31], 0, v[172:173]
	global_load_lds_dwordx4 v[220:221], off
	v_lshl_add_u64 v[220:221], s[54:55], 0, v[174:175]
	s_add_i32 m0, s53, 0x2000
	s_nop 0
	global_load_lds_dwordx4 v[220:221], off
	v_lshl_add_u64 v[220:221], s[30:31], 0, v[168:169]
	s_mov_b32 m0, s25
	s_nop 0
	global_load_lds_dwordx4 v[220:221], off
	s_mov_b32 m0, s37
	s_nop 0
	global_load_lds_dwordx4 v[222:223], off
	s_waitcnt vmcnt(8)
	s_waitcnt lgkmcnt(0)
	s_barrier
; #define PG8_STAGE(bufoff, gbase, voff) do { _Pragma("unroll") for (int _i = 0; _i < 2; ++_i) \
;         __builtin_amdgcn_global_load_lds((const unsigned*)((const char*)(gbase) + (voff)[_i]), (LAS unsigned*)(lds + (bufoff) + ldsw + _i * 8192), 16, 0, 0); } while (0)
; #define PG8_LDA(dst, b, h) do { _Pragma("unroll") for (int m = 0; m < 4; ++m) _Pragma("unroll") for (int k = 0; k < 2; ++k) dst[m][k] = *(const LAS bf16x8*)(lds + PG8_SA(b, h) + aoff + m * 2048 + k * 1024); } while (0)
; #define PG8_LDB(dst, b, h) do { _Pragma("unroll") for (int n = 0; n < 2; ++n) _Pragma("unroll") for (int k = 0; k < 2; ++k) dst[n][k] = *(const LAS bf16x8*)(lds + PG8_SB(b, h) + boff + n * 2048 + k * 1024); } while (0)
; #define PG8_MMA(ai, bj, At, Bt) do { __builtin_amdgcn_s_setprio(1); _Pragma("unroll") for (int m = 0; m < 4; ++m) _Pragma("unroll") for (int n = 0; n < 2; ++n) _Pragma("unroll") for (int k = 0; k < 2; ++k) \
;         acc[ai][bj][m][n] = __builtin_amdgcn_mfma_f32_16x16x32_bf16(Bt[n][k], At[m][k], acc[ai][bj][m][n], 0, 0, 0); __builtin_amdgcn_s_setprio(0); } while (0)
; #define PG8_WAIT_V(n) asm volatile("s_waitcnt vmcnt(" #n ")" ::: "memory")
; #define PG8_WAIT_L(n) asm volatile("s_waitcnt lgkmcnt(" #n ")" ::: "memory")
; #define PG8_BAR __builtin_amdgcn_s_barrier()
; #define PG8_SCHED __builtin_amdgcn_sched_barrier(0)
; template <class Epi, class Sched>
; __device__ __forceinline__ void gemm_phase(LAS unsigned char* lds, const Gemm g, const Sched& S, const Epi& E, int wave_id) {
;     ...
;             PG8_WAIT_V(8); PG8_WAIT_L(0); PG8_BAR; PG8_MMA(1, 0, At, B0); PG8_MMA(1, 1, At, B1); PG8_BAR; PG8_SCHED;
;             PG8_LDB(B0, 1, 0); PG8_LDB(B1, 1, 1); PG8_SCHED; PG8_LDA(At, 1, 0); PG8_STAGE(PG8_SA(0, 1), a2 + hstepA, voffA);
;             PG8_WAIT_V(8); PG8_WAIT_L(0); PG8_BAR; PG8_MMA(0, 0, At, B0); PG8_MMA(0, 1, At, B1); PG8_BAR; PG8_SCHED;
	s_setprio 1
	s_waitcnt lgkmcnt(0)
	v_mfma_f32_16x16x32_bf16 v[60:63], v[116:119], v[160:163], 0
	v_mfma_f32_16x16x32_bf16 v[52:55], v[124:127], v[160:163], 0
	v_mfma_f32_16x16x32_bf16 v[44:47], v[116:119], v[186:189], 0
	v_mfma_f32_16x16x32_bf16 v[36:39], v[124:127], v[186:189], 0
	v_mfma_f32_16x16x32_bf16 v[28:31], v[116:119], v[194:197], 0
	v_mfma_f32_16x16x32_bf16 v[20:23], v[124:127], v[194:197], 0
	v_mfma_f32_16x16x32_bf16 v[12:15], v[116:119], v[208:211], 0
	v_mfma_f32_16x16x32_bf16 v[4:7], v[124:127], v[208:211], 0
	v_mfma_f32_16x16x32_bf16 v[60:63], v[120:123], v[164:167], v[60:63]
	v_mfma_f32_16x16x32_bf16 v[52:55], v[136:139], v[164:167], v[52:55]
	v_mfma_f32_16x16x32_bf16 v[44:47], v[120:123], v[190:193], v[44:47]
	v_mfma_f32_16x16x32_bf16 v[36:39], v[136:139], v[190:193], v[36:39]
	v_mfma_f32_16x16x32_bf16 v[28:31], v[120:123], v[204:207], v[28:31]
	v_mfma_f32_16x16x32_bf16 v[20:23], v[136:139], v[204:207], v[20:23]
	v_mfma_f32_16x16x32_bf16 v[12:15], v[120:123], v[212:215], v[12:15]
	v_mfma_f32_16x16x32_bf16 v[4:7], v[136:139], v[212:215], v[4:7]
	s_setprio 0
	s_setprio 1
	v_mfma_f32_16x16x32_bf16 v[56:59], v[140:143], v[160:163], 0
	v_mfma_f32_16x16x32_bf16 v[48:51], v[152:155], v[160:163], 0
	v_mfma_f32_16x16x32_bf16 v[40:43], v[140:143], v[186:189], 0
	v_mfma_f32_16x16x32_bf16 v[32:35], v[152:155], v[186:189], 0
	v_mfma_f32_16x16x32_bf16 v[24:27], v[140:143], v[194:197], 0
	v_mfma_f32_16x16x32_bf16 v[16:19], v[152:155], v[194:197], 0
	v_mfma_f32_16x16x32_bf16 v[8:11], v[140:143], v[208:211], 0
	v_mfma_f32_16x16x32_bf16 v[0:3], v[152:155], v[208:211], 0
	v_mfma_f32_16x16x32_bf16 v[56:59], v[148:151], v[164:167], v[56:59]
	v_mfma_f32_16x16x32_bf16 v[48:51], v[156:159], v[164:167], v[48:51]
	v_mfma_f32_16x16x32_bf16 v[40:43], v[148:151], v[190:193], v[40:43]
	v_mfma_f32_16x16x32_bf16 v[32:35], v[156:159], v[190:193], v[32:35]
	v_mfma_f32_16x16x32_bf16 v[24:27], v[148:151], v[204:207], v[24:27]
	v_mfma_f32_16x16x32_bf16 v[16:19], v[156:159], v[204:207], v[16:19]
	v_mfma_f32_16x16x32_bf16 v[8:11], v[148:151], v[212:215], v[8:11]
	v_mfma_f32_16x16x32_bf16 v[0:3], v[156:159], v[212:215], v[0:3]
	s_setprio 0
	s_barrier
	s_add_i32 s53, 0, 0x18000
	s_add_i32 s54, 0, 0x1c000
	v_add_u32_e32 v136, s53, v199
	v_add_u32_e32 v156, s54, v199
	ds_read_b128 v[116:119], v136
	ds_read_b128 v[120:123], v136 offset:1024
	ds_read_b128 v[124:127], v136 offset:2048
	ds_read_b128 v[136:139], v136 offset:3072
	ds_read_b128 v[140:143], v156
	ds_read_b128 v[148:151], v156 offset:1024
	ds_read_b128 v[152:155], v156 offset:2048
	ds_read_b128 v[156:159], v156 offset:3072
	s_add_u32 s30, s30, 0x20000
	s_addc_u32 s31, s31, 0
	s_mov_b32 m0, s38
	v_lshl_add_u64 v[224:225], s[30:31], 0, v[168:169]
	ds_read_b128 v[160:163], v203 offset:32768
	ds_read_b128 v[164:167], v203 offset:33792
	ds_read_b128 v[186:189], v203 offset:34816
	ds_read_b128 v[190:193], v203 offset:35840
	ds_read_b128 v[194:197], v203 offset:36864
	ds_read_b128 v[204:207], v203 offset:37888
	ds_read_b128 v[208:211], v203 offset:38912
	ds_read_b128 v[212:215], v203 offset:39936
	global_load_lds_dwordx4 v[224:225], off
	v_lshl_add_u64 v[224:225], s[30:31], 0, v[172:173]
	s_mov_b32 m0, s39
	s_nop 0
	global_load_lds_dwordx4 v[224:225], off
	s_waitcnt vmcnt(8)
	s_waitcnt lgkmcnt(0)
	s_barrier
	s_setprio 1
	s_waitcnt lgkmcnt(0)
	v_mfma_f32_16x16x32_bf16 v[144:147], v[116:119], v[160:163], v[144:147]
	v_mfma_f32_16x16x32_bf16 v[128:131], v[124:127], v[160:163], v[128:131]
	v_mfma_f32_16x16x32_bf16 v[108:111], v[116:119], v[186:189], v[108:111]
	v_mfma_f32_16x16x32_bf16 v[100:103], v[124:127], v[186:189], v[100:103]
	v_mfma_f32_16x16x32_bf16 v[92:95], v[116:119], v[194:197], v[92:95]
	v_mfma_f32_16x16x32_bf16 v[84:87], v[124:127], v[194:197], v[84:87]
	v_mfma_f32_16x16x32_bf16 v[76:79], v[116:119], v[208:211], v[76:79]
	v_mfma_f32_16x16x32_bf16 v[68:71], v[124:127], v[208:211], v[68:71]
	v_mfma_f32_16x16x32_bf16 v[144:147], v[120:123], v[164:167], v[144:147]
	v_mfma_f32_16x16x32_bf16 v[128:131], v[136:139], v[164:167], v[128:131]
	v_mfma_f32_16x16x32_bf16 v[108:111], v[120:123], v[190:193], v[108:111]
	v_mfma_f32_16x16x32_bf16 v[100:103], v[136:139], v[190:193], v[100:103]
	v_mfma_f32_16x16x32_bf16 v[92:95], v[120:123], v[204:207], v[92:95]
	v_mfma_f32_16x16x32_bf16 v[84:87], v[136:139], v[204:207], v[84:87]
	v_mfma_f32_16x16x32_bf16 v[76:79], v[120:123], v[212:215], v[76:79]
	v_mfma_f32_16x16x32_bf16 v[68:71], v[136:139], v[212:215], v[68:71]
	s_setprio 0
	s_setprio 1
	v_mfma_f32_16x16x32_bf16 v[132:135], v[140:143], v[160:163], v[132:135]
	v_mfma_f32_16x16x32_bf16 v[112:115], v[152:155], v[160:163], v[112:115]
	v_mfma_f32_16x16x32_bf16 v[104:107], v[140:143], v[186:189], v[104:107]
	v_mfma_f32_16x16x32_bf16 v[96:99], v[152:155], v[186:189], v[96:99]
	v_mfma_f32_16x16x32_bf16 v[88:91], v[140:143], v[194:197], v[88:91]
	v_mfma_f32_16x16x32_bf16 v[80:83], v[152:155], v[194:197], v[80:83]
	v_mfma_f32_16x16x32_bf16 v[72:75], v[140:143], v[208:211], v[72:75]
	v_mfma_f32_16x16x32_bf16 v[64:67], v[152:155], v[208:211], v[64:67]
	v_mfma_f32_16x16x32_bf16 v[132:135], v[148:151], v[164:167], v[132:135]
	v_mfma_f32_16x16x32_bf16 v[112:115], v[156:159], v[164:167], v[112:115]
	v_mfma_f32_16x16x32_bf16 v[104:107], v[148:151], v[190:193], v[104:107]
	v_mfma_f32_16x16x32_bf16 v[96:99], v[156:159], v[190:193], v[96:99]
	v_mfma_f32_16x16x32_bf16 v[88:91], v[148:151], v[204:207], v[88:91]
	v_mfma_f32_16x16x32_bf16 v[80:83], v[156:159], v[204:207], v[80:83]
	v_mfma_f32_16x16x32_bf16 v[72:75], v[148:151], v[212:215], v[72:75]
	v_mfma_f32_16x16x32_bf16 v[64:67], v[156:159], v[212:215], v[64:67]
	s_setprio 0
	s_barrier
; #define PG8_STAGE(bufoff, gbase, voff) do { _Pragma("unroll") for (int _i = 0; _i < 2; ++_i) \
;         __builtin_amdgcn_global_load_lds((const unsigned*)((const char*)(gbase) + (voff)[_i]), (LAS unsigned*)(lds + (bufoff) + ldsw + _i * 8192), 16, 0, 0); } while (0)
; #define PG8_LDA(dst, b, h) do { _Pragma("unroll") for (int m = 0; m < 4; ++m) _Pragma("unroll") for (int k = 0; k < 2; ++k) dst[m][k] = *(const LAS bf16x8*)(lds + PG8_SA(b, h) + aoff + m * 2048 + k * 1024); } while (0)
; #define PG8_MMA(ai, bj, At, Bt) do { __builtin_amdgcn_s_setprio(1); _Pragma("unroll") for (int m = 0; m < 4; ++m) _Pragma("unroll") for (int n = 0; n < 2; ++n) _Pragma("unroll") for (int k = 0; k < 2; ++k) \
;         acc[ai][bj][m][n] = __builtin_amdgcn_mfma_f32_16x16x32_bf16(Bt[n][k], At[m][k], acc[ai][bj][m][n], 0, 0, 0); __builtin_amdgcn_s_setprio(0); } while (0)
; #define PG8_WAIT_V(n) asm volatile("s_waitcnt vmcnt(" #n ")" ::: "memory")
; #define PG8_WAIT_L(n) asm volatile("s_waitcnt lgkmcnt(" #n ")" ::: "memory")
; #define PG8_BAR __builtin_amdgcn_s_barrier()
; #define PG8_SCHED __builtin_amdgcn_sched_barrier(0)
; template <class Epi, class Sched>
; __device__ __forceinline__ void gemm_phase(LAS unsigned char* lds, const Gemm g, const Sched& S, const Epi& E, int wave_id) {
;     ...
;             PG8_LDA(At, 1, 1); PG8_STAGE(PG8_SB(1, 0), b3, voffB); PG8_STAGE(PG8_SB(1, 1), b3 + hstepB, voffB); PG8_STAGE(PG8_SA(1, 0), a3, voffA);
;             PG8_WAIT_V(8); PG8_WAIT_L(0); PG8_BAR; PG8_MMA(1, 0, At, B0); PG8_MMA(1, 1, At, B1); PG8_BAR; PG8_SCHED;
;         }
	s_add_i32 s30, s53, s36
	v_lshl_add_u64 v[216:217], v[216:217], 0, s[10:11]
	s_mov_b32 m0, s30
	ds_read_b128 v[160:163], v203 offset:49152
	ds_read_b128 v[164:167], v203 offset:50176
	ds_read_b128 v[186:189], v203 offset:51200
	ds_read_b128 v[190:193], v203 offset:52224
	ds_read_b128 v[194:197], v203 offset:53248
	ds_read_b128 v[204:207], v203 offset:54272
	ds_read_b128 v[208:211], v203 offset:55296
	ds_read_b128 v[212:215], v203 offset:56320
	global_load_lds_dwordx4 v[216:217], off
	s_add_i32 m0, s30, 0x2000
	s_add_u32 s28, s28, 0x20080
	v_lshl_add_u64 v[216:217], v[218:219], 0, s[10:11]
	s_addc_u32 s29, s29, 0
	s_add_i32 s30, s54, s36
	global_load_lds_dwordx4 v[216:217], off
	v_lshl_add_u64 v[216:217], s[28:29], 0, v[170:171]
	s_mov_b32 m0, s30
	s_nop 0
	global_load_lds_dwordx4 v[216:217], off
	v_lshl_add_u64 v[216:217], s[28:29], 0, v[174:175]
	s_add_i32 m0, s30, 0x2000
	s_nop 0
	global_load_lds_dwordx4 v[216:217], off
	v_lshl_add_u64 v[216:217], v[220:221], 0, s[10:11]
	s_mov_b32 m0, s41
	s_nop 0
	global_load_lds_dwordx4 v[216:217], off
	v_lshl_add_u64 v[216:217], v[222:223], 0, s[10:11]
	s_mov_b32 m0, s42
	s_nop 0
	global_load_lds_dwordx4 v[216:217], off
	s_waitcnt vmcnt(8)
	s_waitcnt lgkmcnt(0)
	s_barrier
	s_setprio 1
	s_waitcnt lgkmcnt(0)
	v_mfma_f32_16x16x32_bf16 v[60:63], v[116:119], v[160:163], v[60:63]
	v_mfma_f32_16x16x32_bf16 v[52:55], v[124:127], v[160:163], v[52:55]
	v_mfma_f32_16x16x32_bf16 v[44:47], v[116:119], v[186:189], v[44:47]
	v_mfma_f32_16x16x32_bf16 v[36:39], v[124:127], v[186:189], v[36:39]
	v_mfma_f32_16x16x32_bf16 v[28:31], v[116:119], v[194:197], v[28:31]
	v_mfma_f32_16x16x32_bf16 v[20:23], v[124:127], v[194:197], v[20:23]
	v_mfma_f32_16x16x32_bf16 v[12:15], v[116:119], v[208:211], v[12:15]
	v_mfma_f32_16x16x32_bf16 v[4:7], v[124:127], v[208:211], v[4:7]
	v_mfma_f32_16x16x32_bf16 v[60:63], v[120:123], v[164:167], v[60:63]
	v_mfma_f32_16x16x32_bf16 v[52:55], v[136:139], v[164:167], v[52:55]
	v_mfma_f32_16x16x32_bf16 v[44:47], v[120:123], v[190:193], v[44:47]
	v_mfma_f32_16x16x32_bf16 v[36:39], v[136:139], v[190:193], v[36:39]
	v_mfma_f32_16x16x32_bf16 v[28:31], v[120:123], v[204:207], v[28:31]
	v_mfma_f32_16x16x32_bf16 v[20:23], v[136:139], v[204:207], v[20:23]
	v_mfma_f32_16x16x32_bf16 v[12:15], v[120:123], v[212:215], v[12:15]
	v_mfma_f32_16x16x32_bf16 v[4:7], v[136:139], v[212:215], v[4:7]
	s_setprio 0
	s_setprio 1
	v_mfma_f32_16x16x32_bf16 v[56:59], v[140:143], v[160:163], v[56:59]
	v_mfma_f32_16x16x32_bf16 v[48:51], v[152:155], v[160:163], v[48:51]
	v_mfma_f32_16x16x32_bf16 v[40:43], v[140:143], v[186:189], v[40:43]
	v_mfma_f32_16x16x32_bf16 v[32:35], v[152:155], v[186:189], v[32:35]
	v_mfma_f32_16x16x32_bf16 v[24:27], v[140:143], v[194:197], v[24:27]
	v_mfma_f32_16x16x32_bf16 v[16:19], v[152:155], v[194:197], v[16:19]
	v_mfma_f32_16x16x32_bf16 v[8:11], v[140:143], v[208:211], v[8:11]
	v_mfma_f32_16x16x32_bf16 v[0:3], v[152:155], v[208:211], v[0:3]
	v_mfma_f32_16x16x32_bf16 v[56:59], v[148:151], v[164:167], v[56:59]
	v_mfma_f32_16x16x32_bf16 v[48:51], v[156:159], v[164:167], v[48:51]
	v_mfma_f32_16x16x32_bf16 v[40:43], v[148:151], v[190:193], v[40:43]
	v_mfma_f32_16x16x32_bf16 v[32:35], v[156:159], v[190:193], v[32:35]
	v_mfma_f32_16x16x32_bf16 v[24:27], v[148:151], v[204:207], v[24:27]
	v_mfma_f32_16x16x32_bf16 v[16:19], v[156:159], v[204:207], v[16:19]
	v_mfma_f32_16x16x32_bf16 v[8:11], v[148:151], v[212:215], v[8:11]
	v_mfma_f32_16x16x32_bf16 v[0:3], v[156:159], v[212:215], v[0:3]
	s_setprio 0
	s_barrier
	s_add_i32 s52, s52, 2
	s_add_u32 s26, s26, 0x100
	s_addc_u32 s27, s27, 0
	s_add_u32 s50, s50, 0x100
	s_addc_u32 s51, s51, 0
	s_cmp_gt_u32 s52, 5

;     __device__ bool next(int i, Unit& u) const { if (r0 + i >= r1) return false; return base.next(r0 + i, u); }
;     __device__ bool next(int i, Unit& u) const { const int L = i * G + c; if (L >= 256) return false; u.pm = L; u.pn = L >> 3; return true; }
; #define PG8_STAGE(bufoff, gbase, voff) do { _Pragma("unroll") for (int _i = 0; _i < 2; ++_i) \
;         __builtin_amdgcn_global_load_lds((const unsigned*)((const char*)(gbase) + (voff)[_i]), (LAS unsigned*)(lds + (bufoff) + ldsw + _i * 8192), 16, 0, 0); } while (0)
; #define PG8_LDA(dst, b, h) do { _Pragma("unroll") for (int m = 0; m < 4; ++m) _Pragma("unroll") for (int k = 0; k < 2; ++k) dst[m][k] = *(const LAS bf16x8*)(lds + PG8_SA(b, h) + aoff + m * 2048 + k * 1024); } while (0)
; #define PG8_LDB(dst, b, h) do { _Pragma("unroll") for (int n = 0; n < 2; ++n) _Pragma("unroll") for (int k = 0; k < 2; ++k) dst[n][k] = *(const LAS bf16x8*)(lds + PG8_SB(b, h) + boff + n * 2048 + k * 1024); } while (0)
; template <class Epi, class Sched>
; __device__ __forceinline__ void gemm_phase(LAS unsigned char* lds, const Gemm g, const Sched& S, const Epi& E, int wave_id) {
;     ...
;         const bool has_next = S.next(ui + 1, nxt);
;         const char* nA = has_next ? (const char*)g.A + (size_t)nxt.pm * tstepA : cA; const char* nB = has_next ? (const char*)g.Bt + (size_t)nxt.pn * tstepB : cB;
;         for (int t = 0; t < nt; t += 2) {
;             const bool last = (t == nt - 2);
;             const char* a1 = cA + (size_t)(t + 1) * kstep;
;             const char* a2 = last ? nA : cA + (size_t)(t + 2) * kstep; const char* b2 = last ? nB : cB + (size_t)(t + 2) * kstep;
;             const char* a3 = a2 + kstep; const char* b3 = b2 + kstep;
;             PG8_LDB(B0, 0, 0); PG8_LDB(B1, 0, 1); PG8_SCHED; PG8_LDA(At, 0, 0); PG8_STAGE(PG8_SA(1, 1), a1 + hstepA, voffA);
;             PG8_WAIT_V(8); PG8_WAIT_L(0); PG8_BAR; PG8_MMA(0, 0, At, B0); PG8_MMA(0, 1, At, B1); PG8_BAR; PG8_SCHED;
;             PG8_LDA(At, 0, 1); PG8_STAGE(PG8_SB(0, 0), b2, voffB); PG8_STAGE(PG8_SB(0, 1), b2 + hstepB, voffB); PG8_STAGE(PG8_SA(0, 0), a2, voffA);
;     ...
;         for (int a = 0; a < 2; ++a)
; #pragma unroll
;             for (int b = 0; b < 2; ++b)
; #pragma unroll
;                 for (int m = 0; m < 4; ++m)
; #pragma unroll
;                     for (int n = 0; n < 2; ++n) acc[a][b][m][n] = (f32x4){0.f, 0.f, 0.f, 0.f};
.LBB0_1145:
	s_ashr_i32 s21, s20, 31
	s_lshl_b64 s[22:23], s[20:21], 18
	s_add_u32 s22, s3, s22
	s_addc_u32 s23, s17, s23
	s_and_b64 s[24:25], s[4:5], exec
	s_cselect_b32 s21, s23, s29
	s_cselect_b32 s56, s22, s28
	s_ashr_i32 s19, s18, 31
	s_lshl_b64 s[24:25], s[18:19], 18
	s_add_u32 s24, s33, s24
	s_addc_u32 s25, s36, s25
	s_and_b64 s[34:35], s[4:5], exec
	s_cselect_b32 s19, s25, s31
	s_cselect_b32 s57, s24, s30
	s_add_u32 s28, s28, 0x20080
	s_addc_u32 s29, s29, 0
	s_add_u32 s58, s30, 0x100
	s_addc_u32 s59, s31, 0
	s_mov_b32 s60, -2
	s_waitcnt vmcnt(0)
	ds_read_b128 v[128:131], v206
	ds_read_b128 v[132:135], v206 offset:1024
	ds_read_b128 v[136:139], v206 offset:2048
	ds_read_b128 v[140:143], v206 offset:3072
	ds_read_b128 v[144:147], v207
	ds_read_b128 v[148:151], v207 offset:1024
	ds_read_b128 v[178:181], v207 offset:2048
	ds_read_b128 v[182:185], v207 offset:3072
	s_add_u32 s30, s28, 0xfffe0080
	s_addc_u32 s31, s29, -1
	s_cmp_eq_u32 s60, 4
	s_cselect_b32 s35, s21, s31
	s_cselect_b32 s34, s56, s30
	s_cselect_b32 s31, s19, s59
	s_cselect_b32 s30, s57, s58
	v_lshl_add_u64 v[202:203], s[28:29], 0, v[170:171]
	s_add_i32 m0, s38, 0xc000
	ds_read_b128 v[186:189], v208
	ds_read_b128 v[190:193], v208 offset:1024
	ds_read_b128 v[194:197], v208 offset:2048
	ds_read_b128 v[198:201], v208 offset:3072
	ds_read_b128 v[212:215], v208 offset:4096
	ds_read_b128 v[216:219], v208 offset:5120
	ds_read_b128 v[220:223], v208 offset:6144
	ds_read_b128 v[224:227], v208 offset:7168
	global_load_lds_dwordx4 v[202:203], off
	v_lshl_add_u64 v[202:203], s[28:29], 0, v[172:173]
	s_add_i32 m0, s38, 0xe000
	s_nop 0
	global_load_lds_dwordx4 v[202:203], off
	s_waitcnt vmcnt(8)
	s_waitcnt lgkmcnt(0)
	s_barrier
	s_setprio 1
	s_waitcnt lgkmcnt(0)
	v_mfma_f32_16x16x32_bf16 v[124:127], v[128:131], v[186:189], 0
	v_mfma_f32_16x16x32_bf16 v[120:123], v[136:139], v[186:189], 0
	v_mfma_f32_16x16x32_bf16 v[108:111], v[128:131], v[194:197], 0
	v_mfma_f32_16x16x32_bf16 v[104:107], v[136:139], v[194:197], 0
	v_mfma_f32_16x16x32_bf16 v[92:95], v[128:131], v[212:215], 0
	v_mfma_f32_16x16x32_bf16 v[88:91], v[136:139], v[212:215], 0
	v_mfma_f32_16x16x32_bf16 v[76:79], v[128:131], v[220:223], 0
	v_mfma_f32_16x16x32_bf16 v[72:75], v[136:139], v[220:223], 0
	v_mfma_f32_16x16x32_bf16 v[124:127], v[132:135], v[190:193], v[124:127]
	v_mfma_f32_16x16x32_bf16 v[120:123], v[140:143], v[190:193], v[120:123]
	v_mfma_f32_16x16x32_bf16 v[108:111], v[132:135], v[198:201], v[108:111]
	v_mfma_f32_16x16x32_bf16 v[104:107], v[140:143], v[198:201], v[104:107]
	v_mfma_f32_16x16x32_bf16 v[92:95], v[132:135], v[216:219], v[92:95]
	v_mfma_f32_16x16x32_bf16 v[88:91], v[140:143], v[216:219], v[88:91]
	v_mfma_f32_16x16x32_bf16 v[76:79], v[132:135], v[224:227], v[76:79]
	v_mfma_f32_16x16x32_bf16 v[72:75], v[140:143], v[224:227], v[72:75]
	s_setprio 0
	s_setprio 1
	v_mfma_f32_16x16x32_bf16 v[116:119], v[144:147], v[186:189], 0
	v_mfma_f32_16x16x32_bf16 v[112:115], v[178:181], v[186:189], 0
	v_mfma_f32_16x16x32_bf16 v[100:103], v[144:147], v[194:197], 0
	v_mfma_f32_16x16x32_bf16 v[96:99], v[178:181], v[194:197], 0
	v_mfma_f32_16x16x32_bf16 v[84:87], v[144:147], v[212:215], 0
	v_mfma_f32_16x16x32_bf16 v[80:83], v[178:181], v[212:215], 0
	v_mfma_f32_16x16x32_bf16 v[68:71], v[144:147], v[220:223], 0
	v_mfma_f32_16x16x32_bf16 v[64:67], v[178:181], v[220:223], 0
	v_mfma_f32_16x16x32_bf16 v[116:119], v[148:151], v[190:193], v[116:119]
	v_mfma_f32_16x16x32_bf16 v[112:115], v[182:185], v[190:193], v[112:115]
	v_mfma_f32_16x16x32_bf16 v[100:103], v[148:151], v[198:201], v[100:103]
	v_mfma_f32_16x16x32_bf16 v[96:99], v[182:185], v[198:201], v[96:99]
	v_mfma_f32_16x16x32_bf16 v[84:87], v[148:151], v[216:219], v[84:87]
	v_mfma_f32_16x16x32_bf16 v[80:83], v[182:185], v[216:219], v[80:83]
	v_mfma_f32_16x16x32_bf16 v[68:71], v[148:151], v[224:227], v[68:71]
	v_mfma_f32_16x16x32_bf16 v[64:67], v[182:185], v[224:227], v[64:67]
	s_setprio 0
	s_barrier
	s_add_i32 s61, s54, s37
	v_lshl_add_u64 v[202:203], s[30:31], 0, v[154:155]
	s_mov_b32 m0, s61
	ds_read_b128 v[186:189], v208 offset:16384
	ds_read_b128 v[190:193], v208 offset:17408
	ds_read_b128 v[194:197], v208 offset:18432
	ds_read_b128 v[198:201], v208 offset:19456
	ds_read_b128 v[212:215], v208 offset:20480
	ds_read_b128 v[216:219], v208 offset:21504
	ds_read_b128 v[220:223], v208 offset:22528
	ds_read_b128 v[224:227], v208 offset:23552
	global_load_lds_dwordx4 v[202:203], off
	s_add_i32 m0, s61, 0x2000
	s_add_u32 s62, s30, 0x20000
	v_lshl_add_u64 v[228:229], s[30:31], 0, v[158:159]
	s_addc_u32 s63, s31, 0
	s_add_i32 s61, s55, s37
	global_load_lds_dwordx4 v[228:229], off
	v_lshl_add_u64 v[230:231], s[62:63], 0, v[154:155]
	s_mov_b32 m0, s61
	v_lshl_add_u64 v[232:233], s[34:35], 0, v[156:157]
	global_load_lds_dwordx4 v[230:231], off
	v_lshl_add_u64 v[230:231], s[62:63], 0, v[158:159]
	s_add_i32 m0, s61, 0x2000
	s_nop 0
	global_load_lds_dwordx4 v[230:231], off
	v_lshl_add_u64 v[230:231], s[34:35], 0, v[152:153]
	s_mov_b32 m0, s38
	s_nop 0
	global_load_lds_dwordx4 v[230:231], off
	s_mov_b32 m0, s39
	s_nop 0
	global_load_lds_dwordx4 v[232:233], off
	s_waitcnt vmcnt(8)
	s_waitcnt lgkmcnt(0)
	s_barrier
; #define PG8_STAGE(bufoff, gbase, voff) do { _Pragma("unroll") for (int _i = 0; _i < 2; ++_i) \
;         __builtin_amdgcn_global_load_lds((const unsigned*)((const char*)(gbase) + (voff)[_i]), (LAS unsigned*)(lds + (bufoff) + ldsw + _i * 8192), 16, 0, 0); } while (0)
; #define PG8_LDA(dst, b, h) do { _Pragma("unroll") for (int m = 0; m < 4; ++m) _Pragma("unroll") for (int k = 0; k < 2; ++k) dst[m][k] = *(const LAS bf16x8*)(lds + PG8_SA(b, h) + aoff + m * 2048 + k * 1024); } while (0)
; #define PG8_LDB(dst, b, h) do { _Pragma("unroll") for (int n = 0; n < 2; ++n) _Pragma("unroll") for (int k = 0; k < 2; ++k) dst[n][k] = *(const LAS bf16x8*)(lds + PG8_SB(b, h) + boff + n * 2048 + k * 1024); } while (0)
; #define PG8_MMA(ai, bj, At, Bt) do { __builtin_amdgcn_s_setprio(1); _Pragma("unroll") for (int m = 0; m < 4; ++m) _Pragma("unroll") for (int n = 0; n < 2; ++n) _Pragma("unroll") for (int k = 0; k < 2; ++k) \
;         acc[ai][bj][m][n] = __builtin_amdgcn_mfma_f32_16x16x32_bf16(Bt[n][k], At[m][k], acc[ai][bj][m][n], 0, 0, 0); __builtin_amdgcn_s_setprio(0); } while (0)
; #define PG8_WAIT_V(n) asm volatile("s_waitcnt vmcnt(" #n ")" ::: "memory")
; #define PG8_WAIT_L(n) asm volatile("s_waitcnt lgkmcnt(" #n ")" ::: "memory")
; #define PG8_BAR __builtin_amdgcn_s_barrier()
; #define PG8_SCHED __builtin_amdgcn_sched_barrier(0)
; template <class Epi, class Sched>
; __device__ __forceinline__ void gemm_phase(LAS unsigned char* lds, const Gemm g, const Sched& S, const Epi& E, int wave_id) {
;     ...
;             PG8_WAIT_V(8); PG8_WAIT_L(0); PG8_BAR; PG8_MMA(1, 0, At, B0); PG8_MMA(1, 1, At, B1); PG8_BAR; PG8_SCHED;
;             PG8_LDB(B0, 1, 0); PG8_LDB(B1, 1, 1); PG8_SCHED; PG8_LDA(At, 1, 0); PG8_STAGE(PG8_SA(0, 1), a2 + hstepA, voffA);
;             PG8_WAIT_V(8); PG8_WAIT_L(0); PG8_BAR; PG8_MMA(0, 0, At, B0); PG8_MMA(0, 1, At, B1); PG8_BAR; PG8_SCHED;
	s_setprio 1
	s_waitcnt lgkmcnt(0)
	v_mfma_f32_16x16x32_bf16 v[60:63], v[128:131], v[186:189], 0
	v_mfma_f32_16x16x32_bf16 v[56:59], v[136:139], v[186:189], 0
	v_mfma_f32_16x16x32_bf16 v[44:47], v[128:131], v[194:197], 0
	v_mfma_f32_16x16x32_bf16 v[40:43], v[136:139], v[194:197], 0
	v_mfma_f32_16x16x32_bf16 v[28:31], v[128:131], v[212:215], 0
	v_mfma_f32_16x16x32_bf16 v[24:27], v[136:139], v[212:215], 0
	v_mfma_f32_16x16x32_bf16 v[12:15], v[128:131], v[220:223], 0
	v_mfma_f32_16x16x32_bf16 v[8:11], v[136:139], v[220:223], 0
	v_mfma_f32_16x16x32_bf16 v[60:63], v[132:135], v[190:193], v[60:63]
	v_mfma_f32_16x16x32_bf16 v[56:59], v[140:143], v[190:193], v[56:59]
	v_mfma_f32_16x16x32_bf16 v[44:47], v[132:135], v[198:201], v[44:47]
	v_mfma_f32_16x16x32_bf16 v[40:43], v[140:143], v[198:201], v[40:43]
	v_mfma_f32_16x16x32_bf16 v[28:31], v[132:135], v[216:219], v[28:31]
	v_mfma_f32_16x16x32_bf16 v[24:27], v[140:143], v[216:219], v[24:27]
	v_mfma_f32_16x16x32_bf16 v[12:15], v[132:135], v[224:227], v[12:15]
	v_mfma_f32_16x16x32_bf16 v[8:11], v[140:143], v[224:227], v[8:11]
	s_setprio 0
	s_setprio 1
	v_mfma_f32_16x16x32_bf16 v[52:55], v[144:147], v[186:189], 0
	v_mfma_f32_16x16x32_bf16 v[48:51], v[178:181], v[186:189], 0
	v_mfma_f32_16x16x32_bf16 v[36:39], v[144:147], v[194:197], 0
	v_mfma_f32_16x16x32_bf16 v[32:35], v[178:181], v[194:197], 0
	v_mfma_f32_16x16x32_bf16 v[20:23], v[144:147], v[212:215], 0
	v_mfma_f32_16x16x32_bf16 v[16:19], v[178:181], v[212:215], 0
	v_mfma_f32_16x16x32_bf16 v[4:7], v[144:147], v[220:223], 0
	v_mfma_f32_16x16x32_bf16 v[0:3], v[178:181], v[220:223], 0
	v_mfma_f32_16x16x32_bf16 v[52:55], v[148:151], v[190:193], v[52:55]
	v_mfma_f32_16x16x32_bf16 v[48:51], v[182:185], v[190:193], v[48:51]
	v_mfma_f32_16x16x32_bf16 v[36:39], v[148:151], v[198:201], v[36:39]
	v_mfma_f32_16x16x32_bf16 v[32:35], v[182:185], v[198:201], v[32:35]
	v_mfma_f32_16x16x32_bf16 v[20:23], v[148:151], v[216:219], v[20:23]
	v_mfma_f32_16x16x32_bf16 v[16:19], v[182:185], v[216:219], v[16:19]
	v_mfma_f32_16x16x32_bf16 v[4:7], v[148:151], v[224:227], v[4:7]
	v_mfma_f32_16x16x32_bf16 v[0:3], v[182:185], v[224:227], v[0:3]
	s_setprio 0
	s_barrier
	s_add_i32 s61, 0, 0x18000
	s_add_i32 s62, 0, 0x1c000
	v_add_u32_e32 v140, s61, v205
	v_add_u32_e32 v182, s62, v205
	ds_read_b128 v[128:131], v140
	ds_read_b128 v[132:135], v140 offset:1024
	ds_read_b128 v[136:139], v140 offset:2048
	ds_read_b128 v[140:143], v140 offset:3072
	ds_read_b128 v[144:147], v182
	ds_read_b128 v[148:151], v182 offset:1024
	ds_read_b128 v[178:181], v182 offset:2048
	ds_read_b128 v[182:185], v182 offset:3072
	s_add_u32 s34, s34, 0x20000
	s_addc_u32 s35, s35, 0
	s_mov_b32 m0, s40
	v_lshl_add_u64 v[234:235], s[34:35], 0, v[152:153]
	ds_read_b128 v[186:189], v208 offset:32768
	ds_read_b128 v[190:193], v208 offset:33792
	ds_read_b128 v[194:197], v208 offset:34816
	ds_read_b128 v[198:201], v208 offset:35840
	ds_read_b128 v[212:215], v208 offset:36864
	ds_read_b128 v[216:219], v208 offset:37888
	ds_read_b128 v[220:223], v208 offset:38912
	ds_read_b128 v[224:227], v208 offset:39936
	global_load_lds_dwordx4 v[234:235], off
	v_lshl_add_u64 v[234:235], s[34:35], 0, v[156:157]
	s_mov_b32 m0, s41
	s_nop 0
	global_load_lds_dwordx4 v[234:235], off
	s_waitcnt vmcnt(8)
	s_waitcnt lgkmcnt(0)
	s_barrier
	s_setprio 1
	s_waitcnt lgkmcnt(0)
	v_mfma_f32_16x16x32_bf16 v[124:127], v[128:131], v[186:189], v[124:127]
	v_mfma_f32_16x16x32_bf16 v[120:123], v[136:139], v[186:189], v[120:123]
	v_mfma_f32_16x16x32_bf16 v[108:111], v[128:131], v[194:197], v[108:111]
	v_mfma_f32_16x16x32_bf16 v[104:107], v[136:139], v[194:197], v[104:107]
	v_mfma_f32_16x16x32_bf16 v[92:95], v[128:131], v[212:215], v[92:95]
	v_mfma_f32_16x16x32_bf16 v[88:91], v[136:139], v[212:215], v[88:91]
	v_mfma_f32_16x16x32_bf16 v[76:79], v[128:131], v[220:223], v[76:79]
	v_mfma_f32_16x16x32_bf16 v[72:75], v[136:139], v[220:223], v[72:75]
	v_mfma_f32_16x16x32_bf16 v[124:127], v[132:135], v[190:193], v[124:127]
	v_mfma_f32_16x16x32_bf16 v[120:123], v[140:143], v[190:193], v[120:123]
	v_mfma_f32_16x16x32_bf16 v[108:111], v[132:135], v[198:201], v[108:111]
	v_mfma_f32_16x16x32_bf16 v[104:107], v[140:143], v[198:201], v[104:107]
	v_mfma_f32_16x16x32_bf16 v[92:95], v[132:135], v[216:219], v[92:95]
	v_mfma_f32_16x16x32_bf16 v[88:91], v[140:143], v[216:219], v[88:91]
	v_mfma_f32_16x16x32_bf16 v[76:79], v[132:135], v[224:227], v[76:79]
	v_mfma_f32_16x16x32_bf16 v[72:75], v[140:143], v[224:227], v[72:75]
	s_setprio 0
	s_setprio 1
	v_mfma_f32_16x16x32_bf16 v[116:119], v[144:147], v[186:189], v[116:119]
	v_mfma_f32_16x16x32_bf16 v[112:115], v[178:181], v[186:189], v[112:115]
	v_mfma_f32_16x16x32_bf16 v[100:103], v[144:147], v[194:197], v[100:103]
	v_mfma_f32_16x16x32_bf16 v[96:99], v[178:181], v[194:197], v[96:99]
	v_mfma_f32_16x16x32_bf16 v[84:87], v[144:147], v[212:215], v[84:87]
	v_mfma_f32_16x16x32_bf16 v[80:83], v[178:181], v[212:215], v[80:83]
	v_mfma_f32_16x16x32_bf16 v[68:71], v[144:147], v[220:223], v[68:71]
	v_mfma_f32_16x16x32_bf16 v[64:67], v[178:181], v[220:223], v[64:67]
	v_mfma_f32_16x16x32_bf16 v[116:119], v[148:151], v[190:193], v[116:119]
	v_mfma_f32_16x16x32_bf16 v[112:115], v[182:185], v[190:193], v[112:115]
	v_mfma_f32_16x16x32_bf16 v[100:103], v[148:151], v[198:201], v[100:103]
	v_mfma_f32_16x16x32_bf16 v[96:99], v[182:185], v[198:201], v[96:99]
	v_mfma_f32_16x16x32_bf16 v[84:87], v[148:151], v[216:219], v[84:87]
	v_mfma_f32_16x16x32_bf16 v[80:83], v[182:185], v[216:219], v[80:83]
	v_mfma_f32_16x16x32_bf16 v[68:71], v[148:151], v[224:227], v[68:71]
	v_mfma_f32_16x16x32_bf16 v[64:67], v[182:185], v[224:227], v[64:67]
	s_setprio 0
	s_barrier
; #define PG8_STAGE(bufoff, gbase, voff) do { _Pragma("unroll") for (int _i = 0; _i < 2; ++_i) \
;         __builtin_amdgcn_global_load_lds((const unsigned*)((const char*)(gbase) + (voff)[_i]), (LAS unsigned*)(lds + (bufoff) + ldsw + _i * 8192), 16, 0, 0); } while (0)
; #define PG8_LDA(dst, b, h) do { _Pragma("unroll") for (int m = 0; m < 4; ++m) _Pragma("unroll") for (int k = 0; k < 2; ++k) dst[m][k] = *(const LAS bf16x8*)(lds + PG8_SA(b, h) + aoff + m * 2048 + k * 1024); } while (0)
; #define PG8_MMA(ai, bj, At, Bt) do { __builtin_amdgcn_s_setprio(1); _Pragma("unroll") for (int m = 0; m < 4; ++m) _Pragma("unroll") for (int n = 0; n < 2; ++n) _Pragma("unroll") for (int k = 0; k < 2; ++k) \
;         acc[ai][bj][m][n] = __builtin_amdgcn_mfma_f32_16x16x32_bf16(Bt[n][k], At[m][k], acc[ai][bj][m][n], 0, 0, 0); __builtin_amdgcn_s_setprio(0); } while (0)
; #define PG8_WAIT_V(n) asm volatile("s_waitcnt vmcnt(" #n ")" ::: "memory")
; #define PG8_WAIT_L(n) asm volatile("s_waitcnt lgkmcnt(" #n ")" ::: "memory")
; #define PG8_BAR __builtin_amdgcn_s_barrier()
; #define PG8_SCHED __builtin_amdgcn_sched_barrier(0)
; template <class Epi, class Sched>
; __device__ __forceinline__ void gemm_phase(LAS unsigned char* lds, const Gemm g, const Sched& S, const Epi& E, int wave_id) {
;     ...
;             PG8_LDA(At, 1, 1); PG8_STAGE(PG8_SB(1, 0), b3, voffB); PG8_STAGE(PG8_SB(1, 1), b3 + hstepB, voffB); PG8_STAGE(PG8_SA(1, 0), a3, voffA);
;             PG8_WAIT_V(8); PG8_WAIT_L(0); PG8_BAR; PG8_MMA(1, 0, At, B0); PG8_MMA(1, 1, At, B1); PG8_BAR; PG8_SCHED;
;         }
	s_add_i32 s34, s61, s37
	v_lshl_add_u64 v[202:203], v[202:203], 0, s[12:13]
	s_mov_b32 m0, s34
	ds_read_b128 v[186:189], v208 offset:49152
	ds_read_b128 v[190:193], v208 offset:50176
	ds_read_b128 v[194:197], v208 offset:51200
	ds_read_b128 v[198:201], v208 offset:52224
	ds_read_b128 v[212:215], v208 offset:53248
	ds_read_b128 v[216:219], v208 offset:54272
	ds_read_b128 v[220:223], v208 offset:55296
	ds_read_b128 v[224:227], v208 offset:56320
	global_load_lds_dwordx4 v[202:203], off
	s_add_i32 m0, s34, 0x2000
	s_add_u32 s30, s30, 0x20080
	v_lshl_add_u64 v[202:203], v[228:229], 0, s[12:13]
	s_addc_u32 s31, s31, 0
	s_add_i32 s34, s62, s37
	global_load_lds_dwordx4 v[202:203], off
	v_lshl_add_u64 v[202:203], s[30:31], 0, v[154:155]
	s_mov_b32 m0, s34
	s_nop 0
	global_load_lds_dwordx4 v[202:203], off
	v_lshl_add_u64 v[202:203], s[30:31], 0, v[158:159]
	s_add_i32 m0, s34, 0x2000
	s_nop 0
	global_load_lds_dwordx4 v[202:203], off
	v_lshl_add_u64 v[202:203], v[230:231], 0, s[12:13]
	s_mov_b32 m0, s44
	s_nop 0
	global_load_lds_dwordx4 v[202:203], off
	v_lshl_add_u64 v[202:203], v[232:233], 0, s[12:13]
	s_mov_b32 m0, s45
	s_nop 0
	global_load_lds_dwordx4 v[202:203], off
	s_waitcnt vmcnt(8)
	s_waitcnt lgkmcnt(0)
	s_barrier
	s_setprio 1
	s_waitcnt lgkmcnt(0)
	v_mfma_f32_16x16x32_bf16 v[60:63], v[128:131], v[186:189], v[60:63]
	v_mfma_f32_16x16x32_bf16 v[56:59], v[136:139], v[186:189], v[56:59]
	v_mfma_f32_16x16x32_bf16 v[44:47], v[128:131], v[194:197], v[44:47]
	v_mfma_f32_16x16x32_bf16 v[40:43], v[136:139], v[194:197], v[40:43]
	v_mfma_f32_16x16x32_bf16 v[28:31], v[128:131], v[212:215], v[28:31]
	v_mfma_f32_16x16x32_bf16 v[24:27], v[136:139], v[212:215], v[24:27]
	v_mfma_f32_16x16x32_bf16 v[12:15], v[128:131], v[220:223], v[12:15]
	v_mfma_f32_16x16x32_bf16 v[8:11], v[136:139], v[220:223], v[8:11]
	v_mfma_f32_16x16x32_bf16 v[60:63], v[132:135], v[190:193], v[60:63]
	v_mfma_f32_16x16x32_bf16 v[56:59], v[140:143], v[190:193], v[56:59]
	v_mfma_f32_16x16x32_bf16 v[44:47], v[132:135], v[198:201], v[44:47]
	v_mfma_f32_16x16x32_bf16 v[40:43], v[140:143], v[198:201], v[40:43]
	v_mfma_f32_16x16x32_bf16 v[28:31], v[132:135], v[216:219], v[28:31]
	v_mfma_f32_16x16x32_bf16 v[24:27], v[140:143], v[216:219], v[24:27]
	v_mfma_f32_16x16x32_bf16 v[12:15], v[132:135], v[224:227], v[12:15]
	v_mfma_f32_16x16x32_bf16 v[8:11], v[140:143], v[224:227], v[8:11]
	s_setprio 0
	s_setprio 1
	v_mfma_f32_16x16x32_bf16 v[52:55], v[144:147], v[186:189], v[52:55]
	v_mfma_f32_16x16x32_bf16 v[48:51], v[178:181], v[186:189], v[48:51]
	v_mfma_f32_16x16x32_bf16 v[36:39], v[144:147], v[194:197], v[36:39]
	v_mfma_f32_16x16x32_bf16 v[32:35], v[178:181], v[194:197], v[32:35]
	v_mfma_f32_16x16x32_bf16 v[20:23], v[144:147], v[212:215], v[20:23]
	v_mfma_f32_16x16x32_bf16 v[16:19], v[178:181], v[212:215], v[16:19]
	v_mfma_f32_16x16x32_bf16 v[4:7], v[144:147], v[220:223], v[4:7]
	v_mfma_f32_16x16x32_bf16 v[0:3], v[178:181], v[220:223], v[0:3]
	v_mfma_f32_16x16x32_bf16 v[52:55], v[148:151], v[190:193], v[52:55]
	v_mfma_f32_16x16x32_bf16 v[48:51], v[182:185], v[190:193], v[48:51]
	v_mfma_f32_16x16x32_bf16 v[36:39], v[148:151], v[198:201], v[36:39]
	v_mfma_f32_16x16x32_bf16 v[32:35], v[182:185], v[198:201], v[32:35]
	v_mfma_f32_16x16x32_bf16 v[20:23], v[148:151], v[216:219], v[20:23]
	v_mfma_f32_16x16x32_bf16 v[16:19], v[182:185], v[216:219], v[16:19]
	v_mfma_f32_16x16x32_bf16 v[4:7], v[148:151], v[224:227], v[4:7]
	v_mfma_f32_16x16x32_bf16 v[0:3], v[182:185], v[224:227], v[0:3]
	s_setprio 0
	s_barrier
	s_add_i32 s60, s60, 2
	s_add_u32 s28, s28, 0x100
	s_addc_u32 s29, s29, 0
	s_add_u32 s58, s58, 0x100
	s_addc_u32 s59, s59, 0
	s_cmp_gt_u32 s60, 5

;     __device__ bool next(int i, Unit& u) const { if (r0 + i >= r1) return false; return base.next(r0 + i, u); }
;     __device__ bool next(int i, Unit& u) const { const int L = i * G + c; if (L >= 256) return false; u.pm = L; u.pn = L >> 3; return true; }
; #define PG8_STAGE(bufoff, gbase, voff) do { _Pragma("unroll") for (int _i = 0; _i < 2; ++_i) \
;         __builtin_amdgcn_global_load_lds((const unsigned*)((const char*)(gbase) + (voff)[_i]), (LAS unsigned*)(lds + (bufoff) + ldsw + _i * 8192), 16, 0, 0); } while (0)
; #define PG8_LDA(dst, b, h) do { _Pragma("unroll") for (int m = 0; m < 4; ++m) _Pragma("unroll") for (int k = 0; k < 2; ++k) dst[m][k] = *(const LAS bf16x8*)(lds + PG8_SA(b, h) + aoff + m * 2048 + k * 1024); } while (0)
; #define PG8_LDB(dst, b, h) do { _Pragma("unroll") for (int n = 0; n < 2; ++n) _Pragma("unroll") for (int k = 0; k < 2; ++k) dst[n][k] = *(const LAS bf16x8*)(lds + PG8_SB(b, h) + boff + n * 2048 + k * 1024); } while (0)
; #define PG8_WAIT_V(n) asm volatile("s_waitcnt vmcnt(" #n ")" ::: "memory")
; #define PG8_WAIT_L(n) asm volatile("s_waitcnt lgkmcnt(" #n ")" ::: "memory")
; template <class Epi, class Sched>
; __device__ __forceinline__ void gemm_phase(LAS unsigned char* lds, const Gemm g, const Sched& S, const Epi& E, int wave_id) {
;     ...
;         const bool has_next = S.next(ui + 1, nxt);
;         const char* nA = has_next ? (const char*)g.A + (size_t)nxt.pm * tstepA : cA; const char* nB = has_next ? (const char*)g.Bt + (size_t)nxt.pn * tstepB : cB;
;         for (int t = 0; t < nt; t += 2) {
;             const bool last = (t == nt - 2);
;             const char* a1 = cA + (size_t)(t + 1) * kstep;
;             const char* a2 = last ? nA : cA + (size_t)(t + 2) * kstep; const char* b2 = last ? nB : cB + (size_t)(t + 2) * kstep;
;             const char* a3 = a2 + kstep; const char* b3 = b2 + kstep;
;             PG8_LDB(B0, 0, 0); PG8_LDB(B1, 0, 1); PG8_SCHED; PG8_LDA(At, 0, 0); PG8_STAGE(PG8_SA(1, 1), a1 + hstepA, voffA);
;             PG8_WAIT_V(8); PG8_WAIT_L(0); PG8_BAR; PG8_MMA(0, 0, At, B0); PG8_MMA(0, 1, At, B1); PG8_BAR; PG8_SCHED;
;             PG8_LDA(At, 0, 1); PG8_STAGE(PG8_SB(0, 0), b2, voffB); PG8_STAGE(PG8_SB(0, 1), b2 + hstepB, voffB); PG8_STAGE(PG8_SA(0, 0), a2, voffA);
;             PG8_WAIT_V(8); PG8_WAIT_L(0); PG8_BAR; PG8_MMA(1, 0, At, B0); PG8_MMA(1, 1, At, B1); PG8_BAR; PG8_SCHED;
.LBB0_1250:
	s_ashr_i32 s25, s24, 31
	s_lshl_b64 s[26:27], s[24:25], 19
	s_add_u32 s26, s45, s26
	s_addc_u32 s27, s46, s27
	s_and_b64 s[28:29], s[6:7], exec
	s_cselect_b32 s25, s27, s35
	s_cselect_b32 s63, s26, s34
	s_ashr_i32 s23, s22, 31
	s_lshl_b64 s[28:29], s[22:23], 19
	s_add_u32 s28, s47, s28
	s_addc_u32 s29, s48, s29
	s_and_b64 s[38:39], s[6:7], exec
	s_cselect_b32 s23, s29, s37
	s_cselect_b32 s64, s28, s36
	s_add_u32 s34, s34, 0x40080
	s_addc_u32 s35, s35, 0
	s_add_u32 s65, s36, 0x100
	s_addc_u32 s66, s37, 0
	s_mov_b32 s67, -2
	s_waitcnt lgkmcnt(0)
	s_waitcnt vmcnt(0)
	ds_read_b128 v[128:131], v178
	ds_read_b128 v[132:135], v178 offset:1024
	ds_read_b128 v[136:139], v178 offset:2048
	ds_read_b128 v[140:143], v178 offset:3072
	ds_read_b128 v[170:173], v179
	ds_read_b128 v[184:187], v179 offset:1024
	ds_read_b128 v[188:191], v179 offset:2048
	ds_read_b128 v[192:195], v179 offset:3072
	s_add_u32 s36, s34, 0xfffc0080
	s_addc_u32 s37, s35, -1
	s_cmp_eq_u32 s67, 12
	s_cselect_b32 s39, s25, s37
	s_cselect_b32 s38, s63, s36
	s_cselect_b32 s37, s23, s66
	s_cselect_b32 s36, s64, s65
	v_lshl_add_u64 v[174:175], s[34:35], 0, v[162:163]
	s_add_i32 m0, s49, 0xc000
	ds_read_b128 v[196:199], v180
	ds_read_b128 v[200:203], v180 offset:1024
	ds_read_b128 v[204:207], v180 offset:2048
	ds_read_b128 v[208:211], v180 offset:3072
	ds_read_b128 v[212:215], v180 offset:4096
	ds_read_b128 v[216:219], v180 offset:5120
	ds_read_b128 v[220:223], v180 offset:6144
	ds_read_b128 v[224:227], v180 offset:7168
	global_load_lds_dwordx4 v[174:175], off
	v_lshl_add_u64 v[174:175], s[34:35], 0, v[164:165]
	s_add_i32 m0, s49, 0xe000
	s_nop 0
	global_load_lds_dwordx4 v[174:175], off
	s_waitcnt vmcnt(8)
	s_waitcnt lgkmcnt(0)
	s_barrier
	s_setprio 1
	s_waitcnt lgkmcnt(0)
	v_mfma_f32_16x16x32_bf16 v[124:127], v[128:131], v[196:199], 0
	v_mfma_f32_16x16x32_bf16 v[120:123], v[136:139], v[196:199], 0
	v_mfma_f32_16x16x32_bf16 v[108:111], v[128:131], v[204:207], 0
	v_mfma_f32_16x16x32_bf16 v[104:107], v[136:139], v[204:207], 0
	v_mfma_f32_16x16x32_bf16 v[92:95], v[128:131], v[212:215], 0
	v_mfma_f32_16x16x32_bf16 v[88:91], v[136:139], v[212:215], 0
	v_mfma_f32_16x16x32_bf16 v[76:79], v[128:131], v[220:223], 0
	v_mfma_f32_16x16x32_bf16 v[72:75], v[136:139], v[220:223], 0
	v_mfma_f32_16x16x32_bf16 v[124:127], v[132:135], v[200:203], v[124:127]
	v_mfma_f32_16x16x32_bf16 v[120:123], v[140:143], v[200:203], v[120:123]
	v_mfma_f32_16x16x32_bf16 v[108:111], v[132:135], v[208:211], v[108:111]
	v_mfma_f32_16x16x32_bf16 v[104:107], v[140:143], v[208:211], v[104:107]
	v_mfma_f32_16x16x32_bf16 v[92:95], v[132:135], v[216:219], v[92:95]
	v_mfma_f32_16x16x32_bf16 v[88:91], v[140:143], v[216:219], v[88:91]
	v_mfma_f32_16x16x32_bf16 v[76:79], v[132:135], v[224:227], v[76:79]
	v_mfma_f32_16x16x32_bf16 v[72:75], v[140:143], v[224:227], v[72:75]
	s_setprio 0
	s_setprio 1
	v_mfma_f32_16x16x32_bf16 v[116:119], v[170:173], v[196:199], 0
	v_mfma_f32_16x16x32_bf16 v[112:115], v[188:191], v[196:199], 0
	v_mfma_f32_16x16x32_bf16 v[100:103], v[170:173], v[204:207], 0
	v_mfma_f32_16x16x32_bf16 v[96:99], v[188:191], v[204:207], 0
	v_mfma_f32_16x16x32_bf16 v[84:87], v[170:173], v[212:215], 0
	v_mfma_f32_16x16x32_bf16 v[80:83], v[188:191], v[212:215], 0
	v_mfma_f32_16x16x32_bf16 v[68:71], v[170:173], v[220:223], 0
	v_mfma_f32_16x16x32_bf16 v[64:67], v[188:191], v[220:223], 0
	v_mfma_f32_16x16x32_bf16 v[116:119], v[184:187], v[200:203], v[116:119]
	v_mfma_f32_16x16x32_bf16 v[112:115], v[192:195], v[200:203], v[112:115]
	v_mfma_f32_16x16x32_bf16 v[100:103], v[184:187], v[208:211], v[100:103]
	v_mfma_f32_16x16x32_bf16 v[96:99], v[192:195], v[208:211], v[96:99]
	v_mfma_f32_16x16x32_bf16 v[84:87], v[184:187], v[216:219], v[84:87]
	v_mfma_f32_16x16x32_bf16 v[80:83], v[192:195], v[216:219], v[80:83]
	v_mfma_f32_16x16x32_bf16 v[68:71], v[184:187], v[224:227], v[68:71]
	v_mfma_f32_16x16x32_bf16 v[64:67], v[192:195], v[224:227], v[64:67]
	s_setprio 0
	s_barrier
	s_add_i32 s72, s60, s2
	v_lshl_add_u64 v[174:175], s[36:37], 0, v[146:147]
	s_mov_b32 m0, s72
	ds_read_b128 v[196:199], v180 offset:16384
	ds_read_b128 v[200:203], v180 offset:17408
	ds_read_b128 v[204:207], v180 offset:18432
	ds_read_b128 v[208:211], v180 offset:19456
	ds_read_b128 v[212:215], v180 offset:20480
	ds_read_b128 v[216:219], v180 offset:21504
	ds_read_b128 v[220:223], v180 offset:22528
	ds_read_b128 v[224:227], v180 offset:23552
	global_load_lds_dwordx4 v[174:175], off
	s_add_i32 m0, s72, 0x2000
	s_add_u32 s72, s36, 0x40000
	v_lshl_add_u64 v[228:229], s[36:37], 0, v[150:151]
	s_addc_u32 s73, s37, 0
	s_add_i32 s74, s61, s2
	global_load_lds_dwordx4 v[228:229], off
	v_lshl_add_u64 v[230:231], s[72:73], 0, v[146:147]
	s_mov_b32 m0, s74
	v_lshl_add_u64 v[232:233], s[38:39], 0, v[148:149]
	global_load_lds_dwordx4 v[230:231], off
	v_lshl_add_u64 v[230:231], s[72:73], 0, v[150:151]
	s_add_i32 m0, s74, 0x2000
	s_nop 0
	global_load_lds_dwordx4 v[230:231], off
	v_lshl_add_u64 v[230:231], s[38:39], 0, v[144:145]
	s_mov_b32 m0, s49
	s_nop 0
	global_load_lds_dwordx4 v[230:231], off
	s_mov_b32 m0, s50
	s_nop 0
	global_load_lds_dwordx4 v[232:233], off
	s_waitcnt vmcnt(8)
	s_waitcnt lgkmcnt(0)
	s_barrier
; #define PG8_STAGE(bufoff, gbase, voff) do { _Pragma("unroll") for (int _i = 0; _i < 2; ++_i) \
;         __builtin_amdgcn_global_load_lds((const unsigned*)((const char*)(gbase) + (voff)[_i]), (LAS unsigned*)(lds + (bufoff) + ldsw + _i * 8192), 16, 0, 0); } while (0)
; #define PG8_LDA(dst, b, h) do { _Pragma("unroll") for (int m = 0; m < 4; ++m) _Pragma("unroll") for (int k = 0; k < 2; ++k) dst[m][k] = *(const LAS bf16x8*)(lds + PG8_SA(b, h) + aoff + m * 2048 + k * 1024); } while (0)
; #define PG8_LDB(dst, b, h) do { _Pragma("unroll") for (int n = 0; n < 2; ++n) _Pragma("unroll") for (int k = 0; k < 2; ++k) dst[n][k] = *(const LAS bf16x8*)(lds + PG8_SB(b, h) + boff + n * 2048 + k * 1024); } while (0)
; #define PG8_MMA(ai, bj, At, Bt) do { __builtin_amdgcn_s_setprio(1); _Pragma("unroll") for (int m = 0; m < 4; ++m) _Pragma("unroll") for (int n = 0; n < 2; ++n) _Pragma("unroll") for (int k = 0; k < 2; ++k) \
;         acc[ai][bj][m][n] = __builtin_amdgcn_mfma_f32_16x16x32_bf16(Bt[n][k], At[m][k], acc[ai][bj][m][n], 0, 0, 0); __builtin_amdgcn_s_setprio(0); } while (0)
; #define PG8_WAIT_V(n) asm volatile("s_waitcnt vmcnt(" #n ")" ::: "memory")
; #define PG8_WAIT_L(n) asm volatile("s_waitcnt lgkmcnt(" #n ")" ::: "memory")
; #define PG8_BAR __builtin_amdgcn_s_barrier()
; #define PG8_SCHED __builtin_amdgcn_sched_barrier(0)
; template <class Epi, class Sched>
; __device__ __forceinline__ void gemm_phase(LAS unsigned char* lds, const Gemm g, const Sched& S, const Epi& E, int wave_id) {
;     ...
;             PG8_WAIT_V(8); PG8_WAIT_L(0); PG8_BAR; PG8_MMA(1, 0, At, B0); PG8_MMA(1, 1, At, B1); PG8_BAR; PG8_SCHED;
;             PG8_LDB(B0, 1, 0); PG8_LDB(B1, 1, 1); PG8_SCHED; PG8_LDA(At, 1, 0); PG8_STAGE(PG8_SA(0, 1), a2 + hstepA, voffA);
;             PG8_WAIT_V(8); PG8_WAIT_L(0); PG8_BAR; PG8_MMA(0, 0, At, B0); PG8_MMA(0, 1, At, B1); PG8_BAR; PG8_SCHED;
;             PG8_LDA(At, 1, 1); PG8_STAGE(PG8_SB(1, 0), b3, voffB); PG8_STAGE(PG8_SB(1, 1), b3 + hstepB, voffB); PG8_STAGE(PG8_SA(1, 0), a3, voffA);
	s_setprio 1
	s_waitcnt lgkmcnt(0)
	v_mfma_f32_16x16x32_bf16 v[60:63], v[128:131], v[196:199], 0
	v_mfma_f32_16x16x32_bf16 v[56:59], v[136:139], v[196:199], 0
	v_mfma_f32_16x16x32_bf16 v[44:47], v[128:131], v[204:207], 0
	v_mfma_f32_16x16x32_bf16 v[40:43], v[136:139], v[204:207], 0
	v_mfma_f32_16x16x32_bf16 v[28:31], v[128:131], v[212:215], 0
	v_mfma_f32_16x16x32_bf16 v[24:27], v[136:139], v[212:215], 0
	v_mfma_f32_16x16x32_bf16 v[12:15], v[128:131], v[220:223], 0
	v_mfma_f32_16x16x32_bf16 v[8:11], v[136:139], v[220:223], 0
	v_mfma_f32_16x16x32_bf16 v[60:63], v[132:135], v[200:203], v[60:63]
	v_mfma_f32_16x16x32_bf16 v[56:59], v[140:143], v[200:203], v[56:59]
	v_mfma_f32_16x16x32_bf16 v[44:47], v[132:135], v[208:211], v[44:47]
	v_mfma_f32_16x16x32_bf16 v[40:43], v[140:143], v[208:211], v[40:43]
	v_mfma_f32_16x16x32_bf16 v[28:31], v[132:135], v[216:219], v[28:31]
	v_mfma_f32_16x16x32_bf16 v[24:27], v[140:143], v[216:219], v[24:27]
	v_mfma_f32_16x16x32_bf16 v[12:15], v[132:135], v[224:227], v[12:15]
	v_mfma_f32_16x16x32_bf16 v[8:11], v[140:143], v[224:227], v[8:11]
	s_setprio 0
	s_setprio 1
	v_mfma_f32_16x16x32_bf16 v[52:55], v[170:173], v[196:199], 0
	v_mfma_f32_16x16x32_bf16 v[48:51], v[188:191], v[196:199], 0
	v_mfma_f32_16x16x32_bf16 v[36:39], v[170:173], v[204:207], 0
	v_mfma_f32_16x16x32_bf16 v[32:35], v[188:191], v[204:207], 0
	v_mfma_f32_16x16x32_bf16 v[20:23], v[170:173], v[212:215], 0
	v_mfma_f32_16x16x32_bf16 v[16:19], v[188:191], v[212:215], 0
	v_mfma_f32_16x16x32_bf16 v[4:7], v[170:173], v[220:223], 0
	v_mfma_f32_16x16x32_bf16 v[0:3], v[188:191], v[220:223], 0
	v_mfma_f32_16x16x32_bf16 v[52:55], v[184:187], v[200:203], v[52:55]
	v_mfma_f32_16x16x32_bf16 v[48:51], v[192:195], v[200:203], v[48:51]
	v_mfma_f32_16x16x32_bf16 v[36:39], v[184:187], v[208:211], v[36:39]
	v_mfma_f32_16x16x32_bf16 v[32:35], v[192:195], v[208:211], v[32:35]
	v_mfma_f32_16x16x32_bf16 v[20:23], v[184:187], v[216:219], v[20:23]
	v_mfma_f32_16x16x32_bf16 v[16:19], v[192:195], v[216:219], v[16:19]
	v_mfma_f32_16x16x32_bf16 v[4:7], v[184:187], v[224:227], v[4:7]
	v_mfma_f32_16x16x32_bf16 v[0:3], v[192:195], v[224:227], v[0:3]
	s_setprio 0
	s_barrier
	s_add_i32 s72, 0, 0x18000
	s_add_i32 s73, 0, 0x1c000
	v_add_u32_e32 v140, s72, v177
	v_add_u32_e32 v192, s73, v177
	ds_read_b128 v[128:131], v140
	ds_read_b128 v[132:135], v140 offset:1024
	ds_read_b128 v[136:139], v140 offset:2048
	ds_read_b128 v[140:143], v140 offset:3072
	ds_read_b128 v[170:173], v192
	ds_read_b128 v[184:187], v192 offset:1024
	ds_read_b128 v[188:191], v192 offset:2048
	ds_read_b128 v[192:195], v192 offset:3072
	s_add_u32 s38, s38, 0x40000
	s_addc_u32 s39, s39, 0
	s_mov_b32 m0, s51
	v_lshl_add_u64 v[234:235], s[38:39], 0, v[144:145]
	ds_read_b128 v[196:199], v180 offset:32768
	ds_read_b128 v[200:203], v180 offset:33792
	ds_read_b128 v[204:207], v180 offset:34816
	ds_read_b128 v[208:211], v180 offset:35840
	ds_read_b128 v[212:215], v180 offset:36864
	ds_read_b128 v[216:219], v180 offset:37888
	ds_read_b128 v[220:223], v180 offset:38912
	ds_read_b128 v[224:227], v180 offset:39936
	global_load_lds_dwordx4 v[234:235], off
	v_lshl_add_u64 v[234:235], s[38:39], 0, v[148:149]
	s_mov_b32 m0, s52
	s_nop 0
	global_load_lds_dwordx4 v[234:235], off
	s_waitcnt vmcnt(8)
	s_waitcnt lgkmcnt(0)
	s_barrier
	s_setprio 1
	s_waitcnt lgkmcnt(0)
	v_mfma_f32_16x16x32_bf16 v[124:127], v[128:131], v[196:199], v[124:127]
	v_mfma_f32_16x16x32_bf16 v[120:123], v[136:139], v[196:199], v[120:123]
	v_mfma_f32_16x16x32_bf16 v[108:111], v[128:131], v[204:207], v[108:111]
	v_mfma_f32_16x16x32_bf16 v[104:107], v[136:139], v[204:207], v[104:107]
	v_mfma_f32_16x16x32_bf16 v[92:95], v[128:131], v[212:215], v[92:95]
	v_mfma_f32_16x16x32_bf16 v[88:91], v[136:139], v[212:215], v[88:91]
	v_mfma_f32_16x16x32_bf16 v[76:79], v[128:131], v[220:223], v[76:79]
	v_mfma_f32_16x16x32_bf16 v[72:75], v[136:139], v[220:223], v[72:75]
	v_mfma_f32_16x16x32_bf16 v[124:127], v[132:135], v[200:203], v[124:127]
	v_mfma_f32_16x16x32_bf16 v[120:123], v[140:143], v[200:203], v[120:123]
	v_mfma_f32_16x16x32_bf16 v[108:111], v[132:135], v[208:211], v[108:111]
	v_mfma_f32_16x16x32_bf16 v[104:107], v[140:143], v[208:211], v[104:107]
	v_mfma_f32_16x16x32_bf16 v[92:95], v[132:135], v[216:219], v[92:95]
	v_mfma_f32_16x16x32_bf16 v[88:91], v[140:143], v[216:219], v[88:91]
	v_mfma_f32_16x16x32_bf16 v[76:79], v[132:135], v[224:227], v[76:79]
	v_mfma_f32_16x16x32_bf16 v[72:75], v[140:143], v[224:227], v[72:75]
	s_setprio 0
	s_setprio 1
	v_mfma_f32_16x16x32_bf16 v[116:119], v[170:173], v[196:199], v[116:119]
	v_mfma_f32_16x16x32_bf16 v[112:115], v[188:191], v[196:199], v[112:115]
	v_mfma_f32_16x16x32_bf16 v[100:103], v[170:173], v[204:207], v[100:103]
	v_mfma_f32_16x16x32_bf16 v[96:99], v[188:191], v[204:207], v[96:99]
	v_mfma_f32_16x16x32_bf16 v[84:87], v[170:173], v[212:215], v[84:87]
	v_mfma_f32_16x16x32_bf16 v[80:83], v[188:191], v[212:215], v[80:83]
	v_mfma_f32_16x16x32_bf16 v[68:71], v[170:173], v[220:223], v[68:71]
	v_mfma_f32_16x16x32_bf16 v[64:67], v[188:191], v[220:223], v[64:67]
	v_mfma_f32_16x16x32_bf16 v[116:119], v[184:187], v[200:203], v[116:119]
	v_mfma_f32_16x16x32_bf16 v[112:115], v[192:195], v[200:203], v[112:115]
	v_mfma_f32_16x16x32_bf16 v[100:103], v[184:187], v[208:211], v[100:103]
	v_mfma_f32_16x16x32_bf16 v[96:99], v[192:195], v[208:211], v[96:99]
	v_mfma_f32_16x16x32_bf16 v[84:87], v[184:187], v[216:219], v[84:87]
	v_mfma_f32_16x16x32_bf16 v[80:83], v[192:195], v[216:219], v[80:83]
	v_mfma_f32_16x16x32_bf16 v[68:71], v[184:187], v[224:227], v[68:71]
	v_mfma_f32_16x16x32_bf16 v[64:67], v[192:195], v[224:227], v[64:67]
	s_setprio 0
	s_barrier
; #define PG8_STAGE(bufoff, gbase, voff) do { _Pragma("unroll") for (int _i = 0; _i < 2; ++_i) \
;         __builtin_amdgcn_global_load_lds((const unsigned*)((const char*)(gbase) + (voff)[_i]), (LAS unsigned*)(lds + (bufoff) + ldsw + _i * 8192), 16, 0, 0); } while (0)
; #define PG8_LDA(dst, b, h) do { _Pragma("unroll") for (int m = 0; m < 4; ++m) _Pragma("unroll") for (int k = 0; k < 2; ++k) dst[m][k] = *(const LAS bf16x8*)(lds + PG8_SA(b, h) + aoff + m * 2048 + k * 1024); } while (0)
; #define PG8_MMA(ai, bj, At, Bt) do { __builtin_amdgcn_s_setprio(1); _Pragma("unroll") for (int m = 0; m < 4; ++m) _Pragma("unroll") for (int n = 0; n < 2; ++n) _Pragma("unroll") for (int k = 0; k < 2; ++k) \
;         acc[ai][bj][m][n] = __builtin_amdgcn_mfma_f32_16x16x32_bf16(Bt[n][k], At[m][k], acc[ai][bj][m][n], 0, 0, 0); __builtin_amdgcn_s_setprio(0); } while (0)
; #define PG8_WAIT_V(n) asm volatile("s_waitcnt vmcnt(" #n ")" ::: "memory")
; #define PG8_WAIT_L(n) asm volatile("s_waitcnt lgkmcnt(" #n ")" ::: "memory")
; #define PG8_BAR __builtin_amdgcn_s_barrier()
; #define PG8_SCHED __builtin_amdgcn_sched_barrier(0)
; template <class Epi, class Sched>
; __device__ __forceinline__ void gemm_phase(LAS unsigned char* lds, const Gemm g, const Sched& S, const Epi& E, int wave_id) {
;     ...
;             PG8_LDA(At, 1, 1); PG8_STAGE(PG8_SB(1, 0), b3, voffB); PG8_STAGE(PG8_SB(1, 1), b3 + hstepB, voffB); PG8_STAGE(PG8_SA(1, 0), a3, voffA);
;             PG8_WAIT_V(8); PG8_WAIT_L(0); PG8_BAR; PG8_MMA(1, 0, At, B0); PG8_MMA(1, 1, At, B1); PG8_BAR; PG8_SCHED;
	s_add_i32 s38, s72, s2
	v_lshl_add_u64 v[174:175], v[174:175], 0, s[16:17]
	s_mov_b32 m0, s38
	ds_read_b128 v[196:199], v180 offset:49152
	ds_read_b128 v[200:203], v180 offset:50176
	ds_read_b128 v[204:207], v180 offset:51200
	ds_read_b128 v[208:211], v180 offset:52224
	ds_read_b128 v[212:215], v180 offset:53248
	ds_read_b128 v[216:219], v180 offset:54272
	ds_read_b128 v[220:223], v180 offset:55296
	ds_read_b128 v[224:227], v180 offset:56320
	global_load_lds_dwordx4 v[174:175], off
	s_add_i32 m0, s38, 0x2000
	s_add_u32 s36, s36, 0x40080
	v_lshl_add_u64 v[174:175], v[228:229], 0, s[16:17]
	s_addc_u32 s37, s37, 0
	s_add_i32 s38, s73, s2
	global_load_lds_dwordx4 v[174:175], off
	v_lshl_add_u64 v[174:175], s[36:37], 0, v[146:147]
	s_mov_b32 m0, s38
	s_nop 0
	global_load_lds_dwordx4 v[174:175], off
	v_lshl_add_u64 v[174:175], s[36:37], 0, v[150:151]
	s_add_i32 m0, s38, 0x2000
	s_nop 0
	global_load_lds_dwordx4 v[174:175], off
	v_lshl_add_u64 v[174:175], v[230:231], 0, s[16:17]
	s_mov_b32 m0, s54
	s_nop 0
	global_load_lds_dwordx4 v[174:175], off
	v_lshl_add_u64 v[174:175], v[232:233], 0, s[16:17]
	s_mov_b32 m0, s55
	s_nop 0
	global_load_lds_dwordx4 v[174:175], off
	s_waitcnt vmcnt(8)
	s_waitcnt lgkmcnt(0)
	s_barrier
	s_setprio 1
	s_waitcnt lgkmcnt(0)
	v_mfma_f32_16x16x32_bf16 v[60:63], v[128:131], v[196:199], v[60:63]
	v_mfma_f32_16x16x32_bf16 v[56:59], v[136:139], v[196:199], v[56:59]
	v_mfma_f32_16x16x32_bf16 v[44:47], v[128:131], v[204:207], v[44:47]
	v_mfma_f32_16x16x32_bf16 v[40:43], v[136:139], v[204:207], v[40:43]
	v_mfma_f32_16x16x32_bf16 v[28:31], v[128:131], v[212:215], v[28:31]
	v_mfma_f32_16x16x32_bf16 v[24:27], v[136:139], v[212:215], v[24:27]
	v_mfma_f32_16x16x32_bf16 v[12:15], v[128:131], v[220:223], v[12:15]
	v_mfma_f32_16x16x32_bf16 v[8:11], v[136:139], v[220:223], v[8:11]
	v_mfma_f32_16x16x32_bf16 v[60:63], v[132:135], v[200:203], v[60:63]
	v_mfma_f32_16x16x32_bf16 v[56:59], v[140:143], v[200:203], v[56:59]
	v_mfma_f32_16x16x32_bf16 v[44:47], v[132:135], v[208:211], v[44:47]
	v_mfma_f32_16x16x32_bf16 v[40:43], v[140:143], v[208:211], v[40:43]
	v_mfma_f32_16x16x32_bf16 v[28:31], v[132:135], v[216:219], v[28:31]
	v_mfma_f32_16x16x32_bf16 v[24:27], v[140:143], v[216:219], v[24:27]
	v_mfma_f32_16x16x32_bf16 v[12:15], v[132:135], v[224:227], v[12:15]
	v_mfma_f32_16x16x32_bf16 v[8:11], v[140:143], v[224:227], v[8:11]
	s_setprio 0
	s_setprio 1
	v_mfma_f32_16x16x32_bf16 v[52:55], v[170:173], v[196:199], v[52:55]
	v_mfma_f32_16x16x32_bf16 v[48:51], v[188:191], v[196:199], v[48:51]
	v_mfma_f32_16x16x32_bf16 v[36:39], v[170:173], v[204:207], v[36:39]
	v_mfma_f32_16x16x32_bf16 v[32:35], v[188:191], v[204:207], v[32:35]
	v_mfma_f32_16x16x32_bf16 v[20:23], v[170:173], v[212:215], v[20:23]
	v_mfma_f32_16x16x32_bf16 v[16:19], v[188:191], v[212:215], v[16:19]
	v_mfma_f32_16x16x32_bf16 v[4:7], v[170:173], v[220:223], v[4:7]
	v_mfma_f32_16x16x32_bf16 v[0:3], v[188:191], v[220:223], v[0:3]
	v_mfma_f32_16x16x32_bf16 v[52:55], v[184:187], v[200:203], v[52:55]
	v_mfma_f32_16x16x32_bf16 v[48:51], v[192:195], v[200:203], v[48:51]
	v_mfma_f32_16x16x32_bf16 v[36:39], v[184:187], v[208:211], v[36:39]
	v_mfma_f32_16x16x32_bf16 v[32:35], v[192:195], v[208:211], v[32:35]
	v_mfma_f32_16x16x32_bf16 v[20:23], v[184:187], v[216:219], v[20:23]
	v_mfma_f32_16x16x32_bf16 v[16:19], v[192:195], v[216:219], v[16:19]
	v_mfma_f32_16x16x32_bf16 v[4:7], v[184:187], v[224:227], v[4:7]
	v_mfma_f32_16x16x32_bf16 v[0:3], v[192:195], v[224:227], v[0:3]
	s_setprio 0
	s_barrier
	s_add_i32 s67, s67, 2
	s_add_u32 s34, s34, 0x100
	s_addc_u32 s35, s35, 0
	s_add_u32 s65, s65, 0x100
	s_addc_u32 s66, s66, 0
	s_cmp_gt_u32 s67, 13

;     __device__ bool next(int i, Unit& u) const { if (r0 + i >= r1) return false; return base.next(r0 + i, u); }
;     __device__ bool next(int i, Unit& u) const { const int L = i * G + c; if (L >= 256) return false; u.pm = L; u.pn = L >> 3; return true; }
; #define PG8_STAGE(bufoff, gbase, voff) do { _Pragma("unroll") for (int _i = 0; _i < 2; ++_i) \
;         __builtin_amdgcn_global_load_lds((const unsigned*)((const char*)(gbase) + (voff)[_i]), (LAS unsigned*)(lds + (bufoff) + ldsw + _i * 8192), 16, 0, 0); } while (0)
; #define PG8_LDA(dst, b, h) do { _Pragma("unroll") for (int m = 0; m < 4; ++m) _Pragma("unroll") for (int k = 0; k < 2; ++k) dst[m][k] = *(const LAS bf16x8*)(lds + PG8_SA(b, h) + aoff + m * 2048 + k * 1024); } while (0)
; #define PG8_LDB(dst, b, h) do { _Pragma("unroll") for (int n = 0; n < 2; ++n) _Pragma("unroll") for (int k = 0; k < 2; ++k) dst[n][k] = *(const LAS bf16x8*)(lds + PG8_SB(b, h) + boff + n * 2048 + k * 1024); } while (0)
; #define PG8_WAIT_V(n) asm volatile("s_waitcnt vmcnt(" #n ")" ::: "memory")
; #define PG8_WAIT_L(n) asm volatile("s_waitcnt lgkmcnt(" #n ")" ::: "memory")
; template <class Epi, class Sched>
; __device__ __forceinline__ void gemm_phase(LAS unsigned char* lds, const Gemm g, const Sched& S, const Epi& E, int wave_id) {
;     ...
;         const bool has_next = S.next(ui + 1, nxt);
;         const char* nA = has_next ? (const char*)g.A + (size_t)nxt.pm * tstepA : cA; const char* nB = has_next ? (const char*)g.Bt + (size_t)nxt.pn * tstepB : cB;
;         for (int t = 0; t < nt; t += 2) {
;             const bool last = (t == nt - 2);
;             const char* a1 = cA + (size_t)(t + 1) * kstep;
;             const char* a2 = last ? nA : cA + (size_t)(t + 2) * kstep; const char* b2 = last ? nB : cB + (size_t)(t + 2) * kstep;
;             const char* a3 = a2 + kstep; const char* b3 = b2 + kstep;
;             PG8_LDB(B0, 0, 0); PG8_LDB(B1, 0, 1); PG8_SCHED; PG8_LDA(At, 0, 0); PG8_STAGE(PG8_SA(1, 1), a1 + hstepA, voffA);
;             PG8_WAIT_V(8); PG8_WAIT_L(0); PG8_BAR; PG8_MMA(0, 0, At, B0); PG8_MMA(0, 1, At, B1); PG8_BAR; PG8_SCHED;
;             PG8_LDA(At, 0, 1); PG8_STAGE(PG8_SB(0, 0), b2, voffB); PG8_STAGE(PG8_SB(0, 1), b2 + hstepB, voffB); PG8_STAGE(PG8_SA(0, 0), a2, voffA);
;             PG8_WAIT_V(8); PG8_WAIT_L(0); PG8_BAR; PG8_MMA(1, 0, At, B0); PG8_MMA(1, 1, At, B1); PG8_BAR; PG8_SCHED;
.LBB0_1276:
	s_ashr_i32 s19, s18, 31
	s_lshl_b64 s[20:21], s[18:19], 17
	s_add_u32 s20, s47, s20
	s_addc_u32 s21, s48, s21
	s_and_b64 s[22:23], s[4:5], exec
	s_cselect_b32 s19, s21, s29
	s_cselect_b32 s63, s20, s28
	s_ashr_i32 s17, s16, 31
	s_lshl_b64 s[22:23], s[16:17], 17
	s_add_u32 s22, s49, s22
	s_addc_u32 s23, s50, s23
	s_and_b64 s[30:31], s[4:5], exec
	s_cselect_b32 s17, s23, s27
	s_cselect_b32 s64, s22, s26
	s_mov_b32 s36, 0
	s_mov_b64 s[30:31], -1
	s_mov_b64 s[34:35], 0
	s_add_u32 s37, s28, s36
	s_addc_u32 s42, s29, 0
	s_add_u32 s40, s37, 0x100
	s_addc_u32 s41, s42, 0
	s_and_b64 s[38:39], s[34:35], exec
	s_cselect_b32 s39, s19, s41
	s_cselect_b32 s38, s63, s40
	s_add_u32 s36, s26, s36
	s_addc_u32 s40, s27, 0
	s_add_u32 s36, s36, 0x100
	s_addc_u32 s40, s40, 0
	s_and_b64 s[34:35], s[34:35], exec
	s_cselect_b32 s41, s17, s40
	s_cselect_b32 s40, s64, s36
	s_add_u32 s44, s37, 0x10080
	ds_read_b128 v[152:155], v147
	ds_read_b128 v[156:159], v147 offset:1024
	ds_read_b128 v[160:163], v147 offset:2048
	ds_read_b128 v[164:167], v147 offset:3072
	ds_read_b128 v[168:171], v148
	ds_read_b128 v[172:175], v148 offset:1024
	ds_read_b128 v[176:179], v148 offset:2048
	ds_read_b128 v[180:183], v148 offset:3072
	s_addc_u32 s45, s42, 0
	s_add_i32 s76, s61, s2
	s_add_i32 m0, s51, 0xc000
	s_add_i32 s79, s51, 0xe000
	s_add_i32 s73, s76, 0x2000
	s_add_u32 s42, s40, 0x10000
	s_addc_u32 s43, s41, 0
	s_add_i32 s75, s62, s2
	s_add_i32 s74, s75, 0x2000
	s_add_i32 s72, 0, 0x18000
	s_add_i32 s67, 0, 0x1c000
	s_add_u32 s36, s38, 0x10000
	s_addc_u32 s37, s39, 0
	s_add_i32 s66, s72, s2
	s_add_i32 s65, s66, 0x2000
	s_add_u32 s34, s40, 0x10080
	s_addc_u32 s35, s41, 0
	s_add_i32 s78, s67, s2
	s_add_i32 s77, s78, 0x2000
	v_lshl_add_u64 v[216:217], s[44:45], 0, v[128:129]
	ds_read_b128 v[184:187], v149
	ds_read_b128 v[188:191], v149 offset:1024
	ds_read_b128 v[192:195], v149 offset:2048
	ds_read_b128 v[196:199], v149 offset:3072
	ds_read_b128 v[200:203], v149 offset:4096
	ds_read_b128 v[204:207], v149 offset:5120
	ds_read_b128 v[208:211], v149 offset:6144
	ds_read_b128 v[212:215], v149 offset:7168
	global_load_lds_dwordx4 v[216:217], off
	v_lshl_add_u64 v[216:217], s[44:45], 0, v[132:133]
	s_mov_b32 m0, s79
	s_nop 0
	global_load_lds_dwordx4 v[216:217], off
	s_waitcnt vmcnt(8)
	s_waitcnt lgkmcnt(0)
	s_barrier
	s_setprio 1
	s_waitcnt lgkmcnt(0)
	v_mfma_f32_16x16x32_bf16 v[124:127], v[152:155], v[184:187], 0
	v_mfma_f32_16x16x32_bf16 v[120:123], v[160:163], v[184:187], 0
	v_mfma_f32_16x16x32_bf16 v[108:111], v[152:155], v[192:195], 0
	v_mfma_f32_16x16x32_bf16 v[104:107], v[160:163], v[192:195], 0
	v_mfma_f32_16x16x32_bf16 v[92:95], v[152:155], v[200:203], 0
	v_mfma_f32_16x16x32_bf16 v[88:91], v[160:163], v[200:203], 0
	v_mfma_f32_16x16x32_bf16 v[76:79], v[152:155], v[208:211], 0
	v_mfma_f32_16x16x32_bf16 v[72:75], v[160:163], v[208:211], 0
	v_mfma_f32_16x16x32_bf16 v[124:127], v[156:159], v[188:191], v[124:127]
	v_mfma_f32_16x16x32_bf16 v[120:123], v[164:167], v[188:191], v[120:123]
	v_mfma_f32_16x16x32_bf16 v[108:111], v[156:159], v[196:199], v[108:111]
	v_mfma_f32_16x16x32_bf16 v[104:107], v[164:167], v[196:199], v[104:107]
	v_mfma_f32_16x16x32_bf16 v[92:95], v[156:159], v[204:207], v[92:95]
	v_mfma_f32_16x16x32_bf16 v[88:91], v[164:167], v[204:207], v[88:91]
	v_mfma_f32_16x16x32_bf16 v[76:79], v[156:159], v[212:215], v[76:79]
	v_mfma_f32_16x16x32_bf16 v[72:75], v[164:167], v[212:215], v[72:75]
	s_setprio 0
	s_setprio 1
	v_mfma_f32_16x16x32_bf16 v[116:119], v[168:171], v[184:187], 0
	v_mfma_f32_16x16x32_bf16 v[112:115], v[176:179], v[184:187], 0
	v_mfma_f32_16x16x32_bf16 v[100:103], v[168:171], v[192:195], 0
	v_mfma_f32_16x16x32_bf16 v[96:99], v[176:179], v[192:195], 0
	v_mfma_f32_16x16x32_bf16 v[84:87], v[168:171], v[200:203], 0
	v_mfma_f32_16x16x32_bf16 v[80:83], v[176:179], v[200:203], 0
	v_mfma_f32_16x16x32_bf16 v[68:71], v[168:171], v[208:211], 0
	v_mfma_f32_16x16x32_bf16 v[64:67], v[176:179], v[208:211], 0
	v_mfma_f32_16x16x32_bf16 v[116:119], v[172:175], v[188:191], v[116:119]
	v_mfma_f32_16x16x32_bf16 v[112:115], v[180:183], v[188:191], v[112:115]
	v_mfma_f32_16x16x32_bf16 v[100:103], v[172:175], v[196:199], v[100:103]
	v_mfma_f32_16x16x32_bf16 v[96:99], v[180:183], v[196:199], v[96:99]
	v_mfma_f32_16x16x32_bf16 v[84:87], v[172:175], v[204:207], v[84:87]
	v_mfma_f32_16x16x32_bf16 v[80:83], v[180:183], v[204:207], v[80:83]
	v_mfma_f32_16x16x32_bf16 v[68:71], v[172:175], v[212:215], v[68:71]
	v_mfma_f32_16x16x32_bf16 v[64:67], v[180:183], v[212:215], v[64:67]
	s_setprio 0
	s_barrier
	s_mov_b32 m0, s76
	v_lshl_add_u64 v[216:217], s[40:41], 0, v[130:131]
	ds_read_b128 v[184:187], v149 offset:16384
	ds_read_b128 v[188:191], v149 offset:17408
	ds_read_b128 v[192:195], v149 offset:18432
	ds_read_b128 v[196:199], v149 offset:19456
	ds_read_b128 v[200:203], v149 offset:20480
	ds_read_b128 v[204:207], v149 offset:21504
	ds_read_b128 v[208:211], v149 offset:22528
	ds_read_b128 v[212:215], v149 offset:23552
	global_load_lds_dwordx4 v[216:217], off
	v_lshl_add_u64 v[218:219], s[40:41], 0, v[134:135]
	s_mov_b32 m0, s73
	v_lshl_add_u64 v[220:221], s[42:43], 0, v[130:131]
	global_load_lds_dwordx4 v[218:219], off
	s_mov_b32 m0, s75
	v_lshl_add_u64 v[222:223], s[38:39], 0, v[132:133]
	global_load_lds_dwordx4 v[220:221], off
	v_lshl_add_u64 v[220:221], s[42:43], 0, v[134:135]
	s_mov_b32 m0, s74
	s_nop 0
	global_load_lds_dwordx4 v[220:221], off
	v_lshl_add_u64 v[220:221], s[38:39], 0, v[128:129]
	s_mov_b32 m0, s51
	s_nop 0
	global_load_lds_dwordx4 v[220:221], off
	s_mov_b32 m0, s52
	s_nop 0
	global_load_lds_dwordx4 v[222:223], off
	s_waitcnt vmcnt(8)
	s_waitcnt lgkmcnt(0)
	s_barrier
; #define PG8_STAGE(bufoff, gbase, voff) do { _Pragma("unroll") for (int _i = 0; _i < 2; ++_i) \
;         __builtin_amdgcn_global_load_lds((const unsigned*)((const char*)(gbase) + (voff)[_i]), (LAS unsigned*)(lds + (bufoff) + ldsw + _i * 8192), 16, 0, 0); } while (0)
; #define PG8_LDA(dst, b, h) do { _Pragma("unroll") for (int m = 0; m < 4; ++m) _Pragma("unroll") for (int k = 0; k < 2; ++k) dst[m][k] = *(const LAS bf16x8*)(lds + PG8_SA(b, h) + aoff + m * 2048 + k * 1024); } while (0)
; #define PG8_LDB(dst, b, h) do { _Pragma("unroll") for (int n = 0; n < 2; ++n) _Pragma("unroll") for (int k = 0; k < 2; ++k) dst[n][k] = *(const LAS bf16x8*)(lds + PG8_SB(b, h) + boff + n * 2048 + k * 1024); } while (0)
; #define PG8_MMA(ai, bj, At, Bt) do { __builtin_amdgcn_s_setprio(1); _Pragma("unroll") for (int m = 0; m < 4; ++m) _Pragma("unroll") for (int n = 0; n < 2; ++n) _Pragma("unroll") for (int k = 0; k < 2; ++k) \
;         acc[ai][bj][m][n] = __builtin_amdgcn_mfma_f32_16x16x32_bf16(Bt[n][k], At[m][k], acc[ai][bj][m][n], 0, 0, 0); __builtin_amdgcn_s_setprio(0); } while (0)
; #define PG8_WAIT_V(n) asm volatile("s_waitcnt vmcnt(" #n ")" ::: "memory")
; #define PG8_WAIT_L(n) asm volatile("s_waitcnt lgkmcnt(" #n ")" ::: "memory")
; #define PG8_BAR __builtin_amdgcn_s_barrier()
; #define PG8_SCHED __builtin_amdgcn_sched_barrier(0)
; template <class Epi, class Sched>
; __device__ __forceinline__ void gemm_phase(LAS unsigned char* lds, const Gemm g, const Sched& S, const Epi& E, int wave_id) {
;     ...
;             PG8_WAIT_V(8); PG8_WAIT_L(0); PG8_BAR; PG8_MMA(1, 0, At, B0); PG8_MMA(1, 1, At, B1); PG8_BAR; PG8_SCHED;
;             PG8_LDB(B0, 1, 0); PG8_LDB(B1, 1, 1); PG8_SCHED; PG8_LDA(At, 1, 0); PG8_STAGE(PG8_SA(0, 1), a2 + hstepA, voffA);
;             PG8_WAIT_V(8); PG8_WAIT_L(0); PG8_BAR; PG8_MMA(0, 0, At, B0); PG8_MMA(0, 1, At, B1); PG8_BAR; PG8_SCHED;
;             PG8_LDA(At, 1, 1); PG8_STAGE(PG8_SB(1, 0), b3, voffB); PG8_STAGE(PG8_SB(1, 1), b3 + hstepB, voffB); PG8_STAGE(PG8_SA(1, 0), a3, voffA);
	s_setprio 1
	s_waitcnt lgkmcnt(0)
	v_mfma_f32_16x16x32_bf16 v[60:63], v[152:155], v[184:187], 0
	v_mfma_f32_16x16x32_bf16 v[56:59], v[160:163], v[184:187], 0
	v_mfma_f32_16x16x32_bf16 v[44:47], v[152:155], v[192:195], 0
	v_mfma_f32_16x16x32_bf16 v[40:43], v[160:163], v[192:195], 0
	v_mfma_f32_16x16x32_bf16 v[28:31], v[152:155], v[200:203], 0
	v_mfma_f32_16x16x32_bf16 v[24:27], v[160:163], v[200:203], 0
	v_mfma_f32_16x16x32_bf16 v[12:15], v[152:155], v[208:211], 0
	v_mfma_f32_16x16x32_bf16 v[8:11], v[160:163], v[208:211], 0
	v_mfma_f32_16x16x32_bf16 v[60:63], v[156:159], v[188:191], v[60:63]
	v_mfma_f32_16x16x32_bf16 v[56:59], v[164:167], v[188:191], v[56:59]
	v_mfma_f32_16x16x32_bf16 v[44:47], v[156:159], v[196:199], v[44:47]
	v_mfma_f32_16x16x32_bf16 v[40:43], v[164:167], v[196:199], v[40:43]
	v_mfma_f32_16x16x32_bf16 v[28:31], v[156:159], v[204:207], v[28:31]
	v_mfma_f32_16x16x32_bf16 v[24:27], v[164:167], v[204:207], v[24:27]
	v_mfma_f32_16x16x32_bf16 v[12:15], v[156:159], v[212:215], v[12:15]
	v_mfma_f32_16x16x32_bf16 v[8:11], v[164:167], v[212:215], v[8:11]
	s_setprio 0
	s_setprio 1
	v_mfma_f32_16x16x32_bf16 v[52:55], v[168:171], v[184:187], 0
	v_mfma_f32_16x16x32_bf16 v[48:51], v[176:179], v[184:187], 0
	v_mfma_f32_16x16x32_bf16 v[36:39], v[168:171], v[192:195], 0
	v_mfma_f32_16x16x32_bf16 v[32:35], v[176:179], v[192:195], 0
	v_mfma_f32_16x16x32_bf16 v[20:23], v[168:171], v[200:203], 0
	v_mfma_f32_16x16x32_bf16 v[16:19], v[176:179], v[200:203], 0
	v_mfma_f32_16x16x32_bf16 v[4:7], v[168:171], v[208:211], 0
	v_mfma_f32_16x16x32_bf16 v[0:3], v[176:179], v[208:211], 0
	v_mfma_f32_16x16x32_bf16 v[52:55], v[172:175], v[188:191], v[52:55]
	v_mfma_f32_16x16x32_bf16 v[48:51], v[180:183], v[188:191], v[48:51]
	v_mfma_f32_16x16x32_bf16 v[36:39], v[172:175], v[196:199], v[36:39]
	v_mfma_f32_16x16x32_bf16 v[32:35], v[180:183], v[196:199], v[32:35]
	v_mfma_f32_16x16x32_bf16 v[20:23], v[172:175], v[204:207], v[20:23]
	v_mfma_f32_16x16x32_bf16 v[16:19], v[180:183], v[204:207], v[16:19]
	v_mfma_f32_16x16x32_bf16 v[4:7], v[172:175], v[212:215], v[4:7]
	v_mfma_f32_16x16x32_bf16 v[0:3], v[180:183], v[212:215], v[0:3]
	s_setprio 0
	s_barrier
	v_add_u32_e32 v164, s72, v146
	v_add_u32_e32 v180, s67, v146
	ds_read_b128 v[152:155], v164
	ds_read_b128 v[156:159], v164 offset:1024
	ds_read_b128 v[160:163], v164 offset:2048
	ds_read_b128 v[164:167], v164 offset:3072
	ds_read_b128 v[168:171], v180
	ds_read_b128 v[172:175], v180 offset:1024
	ds_read_b128 v[176:179], v180 offset:2048
	ds_read_b128 v[180:183], v180 offset:3072
	s_mov_b32 m0, s53
	v_lshl_add_u64 v[224:225], s[36:37], 0, v[128:129]
	ds_read_b128 v[184:187], v149 offset:32768
	ds_read_b128 v[188:191], v149 offset:33792
	ds_read_b128 v[192:195], v149 offset:34816
	ds_read_b128 v[196:199], v149 offset:35840
	ds_read_b128 v[200:203], v149 offset:36864
	ds_read_b128 v[204:207], v149 offset:37888
	ds_read_b128 v[208:211], v149 offset:38912
	ds_read_b128 v[212:215], v149 offset:39936
	global_load_lds_dwordx4 v[224:225], off
	v_lshl_add_u64 v[224:225], s[36:37], 0, v[132:133]
	s_mov_b32 m0, s54
	s_nop 0
	global_load_lds_dwordx4 v[224:225], off
	s_waitcnt vmcnt(8)
	s_waitcnt lgkmcnt(0)
	s_barrier
	s_setprio 1
	s_waitcnt lgkmcnt(0)
	v_mfma_f32_16x16x32_bf16 v[124:127], v[152:155], v[184:187], v[124:127]
	v_mfma_f32_16x16x32_bf16 v[120:123], v[160:163], v[184:187], v[120:123]
	v_mfma_f32_16x16x32_bf16 v[108:111], v[152:155], v[192:195], v[108:111]
	v_mfma_f32_16x16x32_bf16 v[104:107], v[160:163], v[192:195], v[104:107]
	v_mfma_f32_16x16x32_bf16 v[92:95], v[152:155], v[200:203], v[92:95]
	v_mfma_f32_16x16x32_bf16 v[88:91], v[160:163], v[200:203], v[88:91]
	v_mfma_f32_16x16x32_bf16 v[76:79], v[152:155], v[208:211], v[76:79]
	v_mfma_f32_16x16x32_bf16 v[72:75], v[160:163], v[208:211], v[72:75]
	v_mfma_f32_16x16x32_bf16 v[124:127], v[156:159], v[188:191], v[124:127]
	v_mfma_f32_16x16x32_bf16 v[120:123], v[164:167], v[188:191], v[120:123]
	v_mfma_f32_16x16x32_bf16 v[108:111], v[156:159], v[196:199], v[108:111]
	v_mfma_f32_16x16x32_bf16 v[104:107], v[164:167], v[196:199], v[104:107]
	v_mfma_f32_16x16x32_bf16 v[92:95], v[156:159], v[204:207], v[92:95]
	v_mfma_f32_16x16x32_bf16 v[88:91], v[164:167], v[204:207], v[88:91]
	v_mfma_f32_16x16x32_bf16 v[76:79], v[156:159], v[212:215], v[76:79]
	v_mfma_f32_16x16x32_bf16 v[72:75], v[164:167], v[212:215], v[72:75]
	s_setprio 0
	s_setprio 1
	v_mfma_f32_16x16x32_bf16 v[116:119], v[168:171], v[184:187], v[116:119]
	v_mfma_f32_16x16x32_bf16 v[112:115], v[176:179], v[184:187], v[112:115]
	v_mfma_f32_16x16x32_bf16 v[100:103], v[168:171], v[192:195], v[100:103]
	v_mfma_f32_16x16x32_bf16 v[96:99], v[176:179], v[192:195], v[96:99]
	v_mfma_f32_16x16x32_bf16 v[84:87], v[168:171], v[200:203], v[84:87]
	v_mfma_f32_16x16x32_bf16 v[80:83], v[176:179], v[200:203], v[80:83]
	v_mfma_f32_16x16x32_bf16 v[68:71], v[168:171], v[208:211], v[68:71]
	v_mfma_f32_16x16x32_bf16 v[64:67], v[176:179], v[208:211], v[64:67]
	v_mfma_f32_16x16x32_bf16 v[116:119], v[172:175], v[188:191], v[116:119]
	v_mfma_f32_16x16x32_bf16 v[112:115], v[180:183], v[188:191], v[112:115]
	v_mfma_f32_16x16x32_bf16 v[100:103], v[172:175], v[196:199], v[100:103]
	v_mfma_f32_16x16x32_bf16 v[96:99], v[180:183], v[196:199], v[96:99]
	v_mfma_f32_16x16x32_bf16 v[84:87], v[172:175], v[204:207], v[84:87]
	v_mfma_f32_16x16x32_bf16 v[80:83], v[180:183], v[204:207], v[80:83]
	v_mfma_f32_16x16x32_bf16 v[68:71], v[172:175], v[212:215], v[68:71]
	v_mfma_f32_16x16x32_bf16 v[64:67], v[180:183], v[212:215], v[64:67]
	s_setprio 0
	s_barrier
; #define PG8_STAGE(bufoff, gbase, voff) do { _Pragma("unroll") for (int _i = 0; _i < 2; ++_i) \
;         __builtin_amdgcn_global_load_lds((const unsigned*)((const char*)(gbase) + (voff)[_i]), (LAS unsigned*)(lds + (bufoff) + ldsw + _i * 8192), 16, 0, 0); } while (0)
; #define PG8_LDA(dst, b, h) do { _Pragma("unroll") for (int m = 0; m < 4; ++m) _Pragma("unroll") for (int k = 0; k < 2; ++k) dst[m][k] = *(const LAS bf16x8*)(lds + PG8_SA(b, h) + aoff + m * 2048 + k * 1024); } while (0)
; #define PG8_MMA(ai, bj, At, Bt) do { __builtin_amdgcn_s_setprio(1); _Pragma("unroll") for (int m = 0; m < 4; ++m) _Pragma("unroll") for (int n = 0; n < 2; ++n) _Pragma("unroll") for (int k = 0; k < 2; ++k) \
;         acc[ai][bj][m][n] = __builtin_amdgcn_mfma_f32_16x16x32_bf16(Bt[n][k], At[m][k], acc[ai][bj][m][n], 0, 0, 0); __builtin_amdgcn_s_setprio(0); } while (0)
; #define PG8_WAIT_V(n) asm volatile("s_waitcnt vmcnt(" #n ")" ::: "memory")
; #define PG8_WAIT_L(n) asm volatile("s_waitcnt lgkmcnt(" #n ")" ::: "memory")
; #define PG8_BAR __builtin_amdgcn_s_barrier()
; #define PG8_SCHED __builtin_amdgcn_sched_barrier(0)
; template <class Epi, class Sched>
; __device__ __forceinline__ void gemm_phase(LAS unsigned char* lds, const Gemm g, const Sched& S, const Epi& E, int wave_id) {
;     ...
;             PG8_LDA(At, 1, 1); PG8_STAGE(PG8_SB(1, 0), b3, voffB); PG8_STAGE(PG8_SB(1, 1), b3 + hstepB, voffB); PG8_STAGE(PG8_SA(1, 0), a3, voffA);
;             PG8_WAIT_V(8); PG8_WAIT_L(0); PG8_BAR; PG8_MMA(1, 0, At, B0); PG8_MMA(1, 1, At, B1); PG8_BAR; PG8_SCHED;
;         }
	s_mov_b32 m0, s66
	v_lshl_add_u64 v[216:217], v[216:217], 0, s[12:13]
	ds_read_b128 v[184:187], v149 offset:49152
	ds_read_b128 v[188:191], v149 offset:50176
	ds_read_b128 v[192:195], v149 offset:51200
	ds_read_b128 v[196:199], v149 offset:52224
	ds_read_b128 v[200:203], v149 offset:53248
	ds_read_b128 v[204:207], v149 offset:54272
	ds_read_b128 v[208:211], v149 offset:55296
	ds_read_b128 v[212:215], v149 offset:56320
	global_load_lds_dwordx4 v[216:217], off
	v_lshl_add_u64 v[216:217], v[218:219], 0, s[12:13]
	s_mov_b32 m0, s65
	s_nop 0
	global_load_lds_dwordx4 v[216:217], off
	v_lshl_add_u64 v[216:217], s[34:35], 0, v[130:131]
	s_mov_b32 m0, s78
	s_nop 0
	global_load_lds_dwordx4 v[216:217], off
	v_lshl_add_u64 v[216:217], s[34:35], 0, v[134:135]
	s_mov_b32 m0, s77
	s_nop 0
	global_load_lds_dwordx4 v[216:217], off
	v_lshl_add_u64 v[216:217], v[220:221], 0, s[12:13]
	s_mov_b32 m0, s58
	s_nop 0
	global_load_lds_dwordx4 v[216:217], off
	v_lshl_add_u64 v[216:217], v[222:223], 0, s[12:13]
	s_mov_b32 m0, s59
	s_nop 0
	global_load_lds_dwordx4 v[216:217], off
	s_waitcnt vmcnt(8)
	s_waitcnt lgkmcnt(0)
	s_barrier
	s_setprio 1
	s_waitcnt lgkmcnt(0)
	v_mfma_f32_16x16x32_bf16 v[60:63], v[152:155], v[184:187], v[60:63]
	v_mfma_f32_16x16x32_bf16 v[56:59], v[160:163], v[184:187], v[56:59]
	v_mfma_f32_16x16x32_bf16 v[44:47], v[152:155], v[192:195], v[44:47]
	v_mfma_f32_16x16x32_bf16 v[40:43], v[160:163], v[192:195], v[40:43]
	v_mfma_f32_16x16x32_bf16 v[28:31], v[152:155], v[200:203], v[28:31]
	v_mfma_f32_16x16x32_bf16 v[24:27], v[160:163], v[200:203], v[24:27]
	v_mfma_f32_16x16x32_bf16 v[12:15], v[152:155], v[208:211], v[12:15]
	v_mfma_f32_16x16x32_bf16 v[8:11], v[160:163], v[208:211], v[8:11]
	v_mfma_f32_16x16x32_bf16 v[60:63], v[156:159], v[188:191], v[60:63]
	v_mfma_f32_16x16x32_bf16 v[56:59], v[164:167], v[188:191], v[56:59]
	v_mfma_f32_16x16x32_bf16 v[44:47], v[156:159], v[196:199], v[44:47]
	v_mfma_f32_16x16x32_bf16 v[40:43], v[164:167], v[196:199], v[40:43]
	v_mfma_f32_16x16x32_bf16 v[28:31], v[156:159], v[204:207], v[28:31]
	v_mfma_f32_16x16x32_bf16 v[24:27], v[164:167], v[204:207], v[24:27]
	v_mfma_f32_16x16x32_bf16 v[12:15], v[156:159], v[212:215], v[12:15]
	v_mfma_f32_16x16x32_bf16 v[8:11], v[164:167], v[212:215], v[8:11]
	s_setprio 0
	s_setprio 1
	v_mfma_f32_16x16x32_bf16 v[52:55], v[168:171], v[184:187], v[52:55]
	v_mfma_f32_16x16x32_bf16 v[48:51], v[176:179], v[184:187], v[48:51]
	v_mfma_f32_16x16x32_bf16 v[36:39], v[168:171], v[192:195], v[36:39]
	v_mfma_f32_16x16x32_bf16 v[32:35], v[176:179], v[192:195], v[32:35]
	v_mfma_f32_16x16x32_bf16 v[20:23], v[168:171], v[200:203], v[20:23]
	v_mfma_f32_16x16x32_bf16 v[16:19], v[176:179], v[200:203], v[16:19]
	v_mfma_f32_16x16x32_bf16 v[4:7], v[168:171], v[208:211], v[4:7]
	v_mfma_f32_16x16x32_bf16 v[0:3], v[176:179], v[208:211], v[0:3]
	v_mfma_f32_16x16x32_bf16 v[52:55], v[172:175], v[188:191], v[52:55]
	v_mfma_f32_16x16x32_bf16 v[48:51], v[180:183], v[188:191], v[48:51]
	v_mfma_f32_16x16x32_bf16 v[36:39], v[172:175], v[196:199], v[36:39]
	v_mfma_f32_16x16x32_bf16 v[32:35], v[180:183], v[196:199], v[32:35]
	v_mfma_f32_16x16x32_bf16 v[20:23], v[172:175], v[204:207], v[20:23]
	v_mfma_f32_16x16x32_bf16 v[16:19], v[180:183], v[204:207], v[16:19]
	v_mfma_f32_16x16x32_bf16 v[4:7], v[172:175], v[212:215], v[4:7]
	v_mfma_f32_16x16x32_bf16 v[0:3], v[180:183], v[212:215], v[0:3]
	s_setprio 0
	s_barrier
	s_movk_i32 s36, 0x100
	s_andn2_b64 vcc, exec, s[30:31]
	s_mov_b64 s[34:35], -1
	s_mov_b64 s[30:31], 0

;     __device__ bool next(int i, Unit& u) const { if (r0 + i >= r1) return false; return base.next(r0 + i, u); }
;     __device__ bool next(int i, Unit& u) const { const int L = i * G + c; if (L >= 256) return false; u.pm = L; u.pn = L >> 3; return true; }
; #define PG8_STAGE(bufoff, gbase, voff) do { _Pragma("unroll") for (int _i = 0; _i < 2; ++_i) \
;         __builtin_amdgcn_global_load_lds((const unsigned*)((const char*)(gbase) + (voff)[_i]), (LAS unsigned*)(lds + (bufoff) + ldsw + _i * 8192), 16, 0, 0); } while (0)
; #define PG8_LDA(dst, b, h) do { _Pragma("unroll") for (int m = 0; m < 4; ++m) _Pragma("unroll") for (int k = 0; k < 2; ++k) dst[m][k] = *(const LAS bf16x8*)(lds + PG8_SA(b, h) + aoff + m * 2048 + k * 1024); } while (0)
; #define PG8_LDB(dst, b, h) do { _Pragma("unroll") for (int n = 0; n < 2; ++n) _Pragma("unroll") for (int k = 0; k < 2; ++k) dst[n][k] = *(const LAS bf16x8*)(lds + PG8_SB(b, h) + boff + n * 2048 + k * 1024); } while (0)
; #define PG8_WAIT_V(n) asm volatile("s_waitcnt vmcnt(" #n ")" ::: "memory")
; #define PG8_WAIT_L(n) asm volatile("s_waitcnt lgkmcnt(" #n ")" ::: "memory")
; template <class Epi, class Sched>
; __device__ __forceinline__ void gemm_phase(LAS unsigned char* lds, const Gemm g, const Sched& S, const Epi& E, int wave_id) {
;     ...
;         const bool has_next = S.next(ui + 1, nxt);
;         const char* nA = has_next ? (const char*)g.A + (size_t)nxt.pm * tstepA : cA; const char* nB = has_next ? (const char*)g.Bt + (size_t)nxt.pn * tstepB : cB;
;         for (int t = 0; t < nt; t += 2) {
;             const bool last = (t == nt - 2);
;             const char* a1 = cA + (size_t)(t + 1) * kstep;
;             const char* a2 = last ? nA : cA + (size_t)(t + 2) * kstep; const char* b2 = last ? nB : cB + (size_t)(t + 2) * kstep;
;             const char* a3 = a2 + kstep; const char* b3 = b2 + kstep;
;             PG8_LDB(B0, 0, 0); PG8_LDB(B1, 0, 1); PG8_SCHED; PG8_LDA(At, 0, 0); PG8_STAGE(PG8_SA(1, 1), a1 + hstepA, voffA);
;             PG8_WAIT_V(8); PG8_WAIT_L(0); PG8_BAR; PG8_MMA(0, 0, At, B0); PG8_MMA(0, 1, At, B1); PG8_BAR; PG8_SCHED;
;             PG8_LDA(At, 0, 1); PG8_STAGE(PG8_SB(0, 0), b2, voffB); PG8_STAGE(PG8_SB(0, 1), b2 + hstepB, voffB); PG8_STAGE(PG8_SA(0, 0), a2, voffA);
;             PG8_WAIT_V(8); PG8_WAIT_L(0); PG8_BAR; PG8_MMA(1, 0, At, B0); PG8_MMA(1, 1, At, B1); PG8_BAR; PG8_SCHED;
.LBB0_1381:
	s_ashr_i32 s41, s40, 31
	s_lshl_b64 s[42:43], s[40:41], 19
	s_add_u32 s42, s16, s42
	s_addc_u32 s43, s17, s43
	s_and_b64 s[44:45], s[8:9], exec
	s_cselect_b32 s41, s43, s13
	s_cselect_b32 s50, s42, s12
	s_ashr_i32 s39, s38, 31
	s_lshl_b64 s[44:45], s[38:39], 19
	s_add_u32 s44, s3, s44
	s_addc_u32 s45, s33, s45
	s_and_b64 s[48:49], s[8:9], exec
	s_cselect_b32 s39, s45, s47
	s_cselect_b32 s51, s44, s46
	s_add_u32 s12, s12, 0x40080
	s_addc_u32 s13, s13, 0
	s_add_u32 s65, s46, 0x100
	s_addc_u32 s66, s47, 0
	s_mov_b32 s67, -2
	s_waitcnt vmcnt(0)
	ds_read_b128 v[8:11], v200
	ds_read_b128 v[12:15], v200 offset:1024
	ds_read_b128 v[16:19], v200 offset:2048
	ds_read_b128 v[20:23], v200 offset:3072
	ds_read_b128 v[144:147], v201
	ds_read_b128 v[148:151], v201 offset:1024
	ds_read_b128 v[176:179], v201 offset:2048
	ds_read_b128 v[180:183], v201 offset:3072
	s_add_u32 s46, s12, 0xfffc0080
	s_addc_u32 s47, s13, -1
	s_cmp_eq_u32 s67, 12
	s_cselect_b32 s49, s41, s47
	s_cselect_b32 s48, s50, s46
	s_cselect_b32 s47, s39, s66
	s_cselect_b32 s46, s51, s65
	v_lshl_add_u64 v[222:223], s[12:13], 0, v[168:169]
	s_add_i32 m0, s37, 0xc000
	ds_read_b128 v[184:187], v202
	ds_read_b128 v[188:191], v202 offset:1024
	ds_read_b128 v[192:195], v202 offset:2048
	ds_read_b128 v[196:199], v202 offset:3072
	ds_read_b128 v[206:209], v202 offset:4096
	ds_read_b128 v[210:213], v202 offset:5120
	ds_read_b128 v[214:217], v202 offset:6144
	ds_read_b128 v[218:221], v202 offset:7168
	global_load_lds_dwordx4 v[222:223], off
	v_lshl_add_u64 v[222:223], s[12:13], 0, v[170:171]
	s_add_i32 m0, s37, 0xe000
	s_nop 0
	global_load_lds_dwordx4 v[222:223], off
	s_waitcnt vmcnt(8)
	s_waitcnt lgkmcnt(0)
	s_barrier
	s_setprio 1
	s_waitcnt lgkmcnt(0)
	v_mfma_f32_16x16x32_bf16 v[140:143], v[8:11], v[184:187], 0
	v_mfma_f32_16x16x32_bf16 v[136:139], v[16:19], v[184:187], 0
	v_mfma_f32_16x16x32_bf16 v[124:127], v[8:11], v[192:195], 0
	v_mfma_f32_16x16x32_bf16 v[120:123], v[16:19], v[192:195], 0
	v_mfma_f32_16x16x32_bf16 v[108:111], v[8:11], v[206:209], 0
	v_mfma_f32_16x16x32_bf16 v[104:107], v[16:19], v[206:209], 0
	v_mfma_f32_16x16x32_bf16 v[92:95], v[8:11], v[214:217], 0
	v_mfma_f32_16x16x32_bf16 v[88:91], v[16:19], v[214:217], 0
	v_mfma_f32_16x16x32_bf16 v[140:143], v[12:15], v[188:191], v[140:143]
	v_mfma_f32_16x16x32_bf16 v[136:139], v[20:23], v[188:191], v[136:139]
	v_mfma_f32_16x16x32_bf16 v[124:127], v[12:15], v[196:199], v[124:127]
	v_mfma_f32_16x16x32_bf16 v[120:123], v[20:23], v[196:199], v[120:123]
	v_mfma_f32_16x16x32_bf16 v[108:111], v[12:15], v[210:213], v[108:111]
	v_mfma_f32_16x16x32_bf16 v[104:107], v[20:23], v[210:213], v[104:107]
	v_mfma_f32_16x16x32_bf16 v[92:95], v[12:15], v[218:221], v[92:95]
	v_mfma_f32_16x16x32_bf16 v[88:91], v[20:23], v[218:221], v[88:91]
	s_setprio 0
	s_setprio 1
	v_mfma_f32_16x16x32_bf16 v[132:135], v[144:147], v[184:187], 0
	v_mfma_f32_16x16x32_bf16 v[128:131], v[176:179], v[184:187], 0
	v_mfma_f32_16x16x32_bf16 v[116:119], v[144:147], v[192:195], 0
	v_mfma_f32_16x16x32_bf16 v[112:115], v[176:179], v[192:195], 0
	v_mfma_f32_16x16x32_bf16 v[100:103], v[144:147], v[206:209], 0
	v_mfma_f32_16x16x32_bf16 v[96:99], v[176:179], v[206:209], 0
	v_mfma_f32_16x16x32_bf16 v[84:87], v[144:147], v[214:217], 0
	v_mfma_f32_16x16x32_bf16 v[80:83], v[176:179], v[214:217], 0
	v_mfma_f32_16x16x32_bf16 v[132:135], v[148:151], v[188:191], v[132:135]
	v_mfma_f32_16x16x32_bf16 v[128:131], v[180:183], v[188:191], v[128:131]
	v_mfma_f32_16x16x32_bf16 v[116:119], v[148:151], v[196:199], v[116:119]
	v_mfma_f32_16x16x32_bf16 v[112:115], v[180:183], v[196:199], v[112:115]
	v_mfma_f32_16x16x32_bf16 v[100:103], v[148:151], v[210:213], v[100:103]
	v_mfma_f32_16x16x32_bf16 v[96:99], v[180:183], v[210:213], v[96:99]
	v_mfma_f32_16x16x32_bf16 v[84:87], v[148:151], v[218:221], v[84:87]
	v_mfma_f32_16x16x32_bf16 v[80:83], v[180:183], v[218:221], v[80:83]
	s_setprio 0
	s_barrier
	s_add_i32 s72, s61, s35
	v_lshl_add_u64 v[222:223], s[46:47], 0, v[154:155]
	s_mov_b32 m0, s72
	ds_read_b128 v[184:187], v202 offset:16384
	ds_read_b128 v[188:191], v202 offset:17408
	ds_read_b128 v[192:195], v202 offset:18432
	ds_read_b128 v[196:199], v202 offset:19456
	ds_read_b128 v[206:209], v202 offset:20480
	ds_read_b128 v[210:213], v202 offset:21504
	ds_read_b128 v[214:217], v202 offset:22528
	ds_read_b128 v[218:221], v202 offset:23552
	global_load_lds_dwordx4 v[222:223], off
	s_add_i32 m0, s72, 0x2000
	s_add_u32 s72, s46, 0x40000
	v_lshl_add_u64 v[224:225], s[46:47], 0, v[158:159]
	s_addc_u32 s73, s47, 0
	s_add_i32 s74, s62, s35
	global_load_lds_dwordx4 v[224:225], off
	v_lshl_add_u64 v[226:227], s[72:73], 0, v[154:155]
	s_mov_b32 m0, s74
	v_lshl_add_u64 v[228:229], s[48:49], 0, v[156:157]
	global_load_lds_dwordx4 v[226:227], off
	v_lshl_add_u64 v[226:227], s[72:73], 0, v[158:159]
	s_add_i32 m0, s74, 0x2000
	s_nop 0
	global_load_lds_dwordx4 v[226:227], off
	v_lshl_add_u64 v[226:227], s[48:49], 0, v[152:153]
	s_mov_b32 m0, s37
	s_nop 0
	global_load_lds_dwordx4 v[226:227], off
	s_mov_b32 m0, s52
	s_nop 0
	global_load_lds_dwordx4 v[228:229], off
	s_waitcnt vmcnt(8)
	s_waitcnt lgkmcnt(0)
	s_barrier
; #define PG8_STAGE(bufoff, gbase, voff) do { _Pragma("unroll") for (int _i = 0; _i < 2; ++_i) \
;         __builtin_amdgcn_global_load_lds((const unsigned*)((const char*)(gbase) + (voff)[_i]), (LAS unsigned*)(lds + (bufoff) + ldsw + _i * 8192), 16, 0, 0); } while (0)
; #define PG8_LDA(dst, b, h) do { _Pragma("unroll") for (int m = 0; m < 4; ++m) _Pragma("unroll") for (int k = 0; k < 2; ++k) dst[m][k] = *(const LAS bf16x8*)(lds + PG8_SA(b, h) + aoff + m * 2048 + k * 1024); } while (0)
; #define PG8_LDB(dst, b, h) do { _Pragma("unroll") for (int n = 0; n < 2; ++n) _Pragma("unroll") for (int k = 0; k < 2; ++k) dst[n][k] = *(const LAS bf16x8*)(lds + PG8_SB(b, h) + boff + n * 2048 + k * 1024); } while (0)
; #define PG8_MMA(ai, bj, At, Bt) do { __builtin_amdgcn_s_setprio(1); _Pragma("unroll") for (int m = 0; m < 4; ++m) _Pragma("unroll") for (int n = 0; n < 2; ++n) _Pragma("unroll") for (int k = 0; k < 2; ++k) \
;         acc[ai][bj][m][n] = __builtin_amdgcn_mfma_f32_16x16x32_bf16(Bt[n][k], At[m][k], acc[ai][bj][m][n], 0, 0, 0); __builtin_amdgcn_s_setprio(0); } while (0)
; #define PG8_WAIT_V(n) asm volatile("s_waitcnt vmcnt(" #n ")" ::: "memory")
; #define PG8_WAIT_L(n) asm volatile("s_waitcnt lgkmcnt(" #n ")" ::: "memory")
; #define PG8_BAR __builtin_amdgcn_s_barrier()
; #define PG8_SCHED __builtin_amdgcn_sched_barrier(0)
; template <class Epi, class Sched>
; __device__ __forceinline__ void gemm_phase(LAS unsigned char* lds, const Gemm g, const Sched& S, const Epi& E, int wave_id) {
;     ...
;             PG8_WAIT_V(8); PG8_WAIT_L(0); PG8_BAR; PG8_MMA(1, 0, At, B0); PG8_MMA(1, 1, At, B1); PG8_BAR; PG8_SCHED;
;             PG8_LDB(B0, 1, 0); PG8_LDB(B1, 1, 1); PG8_SCHED; PG8_LDA(At, 1, 0); PG8_STAGE(PG8_SA(0, 1), a2 + hstepA, voffA);
;             PG8_WAIT_V(8); PG8_WAIT_L(0); PG8_BAR; PG8_MMA(0, 0, At, B0); PG8_MMA(0, 1, At, B1); PG8_BAR; PG8_SCHED;
;             PG8_LDA(At, 1, 1); PG8_STAGE(PG8_SB(1, 0), b3, voffB); PG8_STAGE(PG8_SB(1, 1), b3 + hstepB, voffB); PG8_STAGE(PG8_SA(1, 0), a3, voffA);
	s_setprio 1
	s_waitcnt lgkmcnt(0)
	v_mfma_f32_16x16x32_bf16 v[76:79], v[8:11], v[184:187], 0
	v_mfma_f32_16x16x32_bf16 v[72:75], v[16:19], v[184:187], 0
	v_mfma_f32_16x16x32_bf16 v[60:63], v[8:11], v[192:195], 0
	v_mfma_f32_16x16x32_bf16 v[56:59], v[16:19], v[192:195], 0
	v_mfma_f32_16x16x32_bf16 v[44:47], v[8:11], v[206:209], 0
	v_mfma_f32_16x16x32_bf16 v[40:43], v[16:19], v[206:209], 0
	v_mfma_f32_16x16x32_bf16 v[8:11], v[8:11], v[214:217], 0
	v_mfma_f32_16x16x32_bf16 v[76:79], v[12:15], v[188:191], v[76:79]
	v_mfma_f32_16x16x32_bf16 v[72:75], v[20:23], v[188:191], v[72:75]
	v_mfma_f32_16x16x32_bf16 v[60:63], v[12:15], v[196:199], v[60:63]
	v_mfma_f32_16x16x32_bf16 v[56:59], v[20:23], v[196:199], v[56:59]
	v_mfma_f32_16x16x32_bf16 v[44:47], v[12:15], v[210:213], v[44:47]
	v_mfma_f32_16x16x32_bf16 v[40:43], v[20:23], v[210:213], v[40:43]
	v_mfma_f32_16x16x32_bf16 v[8:11], v[12:15], v[218:221], v[8:11]
	v_mfma_f32_16x16x32_bf16 v[12:15], v[16:19], v[214:217], 0
	v_mfma_f32_16x16x32_bf16 v[12:15], v[20:23], v[218:221], v[12:15]
	s_setprio 0
	s_setprio 1
	v_mfma_f32_16x16x32_bf16 v[24:27], v[144:147], v[192:195], 0
	v_mfma_f32_16x16x32_bf16 v[52:55], v[148:151], v[196:199], v[24:27]
	v_mfma_f32_16x16x32_bf16 v[24:27], v[176:179], v[192:195], 0
	v_mfma_f32_16x16x32_bf16 v[48:51], v[180:183], v[196:199], v[24:27]
	v_mfma_f32_16x16x32_bf16 v[24:27], v[144:147], v[206:209], 0
	v_mfma_f32_16x16x32_bf16 v[36:39], v[148:151], v[210:213], v[24:27]
	v_mfma_f32_16x16x32_bf16 v[24:27], v[176:179], v[206:209], 0
	v_mfma_f32_16x16x32_bf16 v[4:7], v[144:147], v[214:217], 0
	v_mfma_f32_16x16x32_bf16 v[0:3], v[176:179], v[214:217], 0
	v_mfma_f32_16x16x32_bf16 v[16:19], v[144:147], v[184:187], 0
	v_mfma_f32_16x16x32_bf16 v[20:23], v[176:179], v[184:187], 0
	v_mfma_f32_16x16x32_bf16 v[32:35], v[180:183], v[210:213], v[24:27]
	v_mfma_f32_16x16x32_bf16 v[4:7], v[148:151], v[218:221], v[4:7]
	v_mfma_f32_16x16x32_bf16 v[0:3], v[180:183], v[218:221], v[0:3]
	v_mfma_f32_16x16x32_bf16 v[16:19], v[148:151], v[188:191], v[16:19]
	v_mfma_f32_16x16x32_bf16 v[20:23], v[180:183], v[188:191], v[20:23]
	s_setprio 0
	s_barrier
	s_add_i32 s72, 0, 0x18000
	s_add_i32 s73, 0, 0x1c000
	v_add_u32_e32 v68, s72, v165
	v_add_u32_e32 v180, s73, v165
	ds_read_b128 v[24:27], v68
	ds_read_b128 v[28:31], v68 offset:1024
	ds_read_b128 v[64:67], v68 offset:2048
	ds_read_b128 v[68:71], v68 offset:3072
	ds_read_b128 v[144:147], v180
	ds_read_b128 v[148:151], v180 offset:1024
	ds_read_b128 v[176:179], v180 offset:2048
	ds_read_b128 v[180:183], v180 offset:3072
	s_add_u32 s48, s48, 0x40000
	s_addc_u32 s49, s49, 0
	s_mov_b32 m0, s53
	v_lshl_add_u64 v[230:231], s[48:49], 0, v[152:153]
	ds_read_b128 v[184:187], v202 offset:32768
	ds_read_b128 v[188:191], v202 offset:33792
	ds_read_b128 v[192:195], v202 offset:34816
	ds_read_b128 v[196:199], v202 offset:35840
	ds_read_b128 v[206:209], v202 offset:36864
	ds_read_b128 v[210:213], v202 offset:37888
	ds_read_b128 v[214:217], v202 offset:38912
	ds_read_b128 v[218:221], v202 offset:39936
	global_load_lds_dwordx4 v[230:231], off
	v_lshl_add_u64 v[230:231], s[48:49], 0, v[156:157]
	s_mov_b32 m0, s54
	s_nop 0
	global_load_lds_dwordx4 v[230:231], off
	s_waitcnt vmcnt(8)
	s_waitcnt lgkmcnt(0)
	s_barrier
	s_setprio 1
	s_waitcnt lgkmcnt(0)
	v_mfma_f32_16x16x32_bf16 v[140:143], v[24:27], v[184:187], v[140:143]
	v_mfma_f32_16x16x32_bf16 v[136:139], v[64:67], v[184:187], v[136:139]
	v_mfma_f32_16x16x32_bf16 v[124:127], v[24:27], v[192:195], v[124:127]
	v_mfma_f32_16x16x32_bf16 v[120:123], v[64:67], v[192:195], v[120:123]
	v_mfma_f32_16x16x32_bf16 v[108:111], v[24:27], v[206:209], v[108:111]
	v_mfma_f32_16x16x32_bf16 v[104:107], v[64:67], v[206:209], v[104:107]
	v_mfma_f32_16x16x32_bf16 v[92:95], v[24:27], v[214:217], v[92:95]
	v_mfma_f32_16x16x32_bf16 v[88:91], v[64:67], v[214:217], v[88:91]
	v_mfma_f32_16x16x32_bf16 v[140:143], v[28:31], v[188:191], v[140:143]
	v_mfma_f32_16x16x32_bf16 v[136:139], v[68:71], v[188:191], v[136:139]
	v_mfma_f32_16x16x32_bf16 v[124:127], v[28:31], v[196:199], v[124:127]
	v_mfma_f32_16x16x32_bf16 v[120:123], v[68:71], v[196:199], v[120:123]
	v_mfma_f32_16x16x32_bf16 v[108:111], v[28:31], v[210:213], v[108:111]
	v_mfma_f32_16x16x32_bf16 v[104:107], v[68:71], v[210:213], v[104:107]
	v_mfma_f32_16x16x32_bf16 v[92:95], v[28:31], v[218:221], v[92:95]
	v_mfma_f32_16x16x32_bf16 v[88:91], v[68:71], v[218:221], v[88:91]
	s_setprio 0
	s_setprio 1
	v_mfma_f32_16x16x32_bf16 v[132:135], v[144:147], v[184:187], v[132:135]
	v_mfma_f32_16x16x32_bf16 v[128:131], v[176:179], v[184:187], v[128:131]
	v_mfma_f32_16x16x32_bf16 v[116:119], v[144:147], v[192:195], v[116:119]
	v_mfma_f32_16x16x32_bf16 v[112:115], v[176:179], v[192:195], v[112:115]
	v_mfma_f32_16x16x32_bf16 v[100:103], v[144:147], v[206:209], v[100:103]
	v_mfma_f32_16x16x32_bf16 v[96:99], v[176:179], v[206:209], v[96:99]
	v_mfma_f32_16x16x32_bf16 v[84:87], v[144:147], v[214:217], v[84:87]
	v_mfma_f32_16x16x32_bf16 v[80:83], v[176:179], v[214:217], v[80:83]
	v_mfma_f32_16x16x32_bf16 v[132:135], v[148:151], v[188:191], v[132:135]
	v_mfma_f32_16x16x32_bf16 v[128:131], v[180:183], v[188:191], v[128:131]
	v_mfma_f32_16x16x32_bf16 v[116:119], v[148:151], v[196:199], v[116:119]
	v_mfma_f32_16x16x32_bf16 v[112:115], v[180:183], v[196:199], v[112:115]
	v_mfma_f32_16x16x32_bf16 v[100:103], v[148:151], v[210:213], v[100:103]
	v_mfma_f32_16x16x32_bf16 v[96:99], v[180:183], v[210:213], v[96:99]
	v_mfma_f32_16x16x32_bf16 v[84:87], v[148:151], v[218:221], v[84:87]
	v_mfma_f32_16x16x32_bf16 v[80:83], v[180:183], v[218:221], v[80:83]
	s_setprio 0
	s_barrier
; #define PG8_STAGE(bufoff, gbase, voff) do { _Pragma("unroll") for (int _i = 0; _i < 2; ++_i) \
;         __builtin_amdgcn_global_load_lds((const unsigned*)((const char*)(gbase) + (voff)[_i]), (LAS unsigned*)(lds + (bufoff) + ldsw + _i * 8192), 16, 0, 0); } while (0)
; #define PG8_LDA(dst, b, h) do { _Pragma("unroll") for (int m = 0; m < 4; ++m) _Pragma("unroll") for (int k = 0; k < 2; ++k) dst[m][k] = *(const LAS bf16x8*)(lds + PG8_SA(b, h) + aoff + m * 2048 + k * 1024); } while (0)
; #define PG8_MMA(ai, bj, At, Bt) do { __builtin_amdgcn_s_setprio(1); _Pragma("unroll") for (int m = 0; m < 4; ++m) _Pragma("unroll") for (int n = 0; n < 2; ++n) _Pragma("unroll") for (int k = 0; k < 2; ++k) \
;         acc[ai][bj][m][n] = __builtin_amdgcn_mfma_f32_16x16x32_bf16(Bt[n][k], At[m][k], acc[ai][bj][m][n], 0, 0, 0); __builtin_amdgcn_s_setprio(0); } while (0)
; #define PG8_WAIT_V(n) asm volatile("s_waitcnt vmcnt(" #n ")" ::: "memory")
; #define PG8_WAIT_L(n) asm volatile("s_waitcnt lgkmcnt(" #n ")" ::: "memory")
; #define PG8_BAR __builtin_amdgcn_s_barrier()
; #define PG8_SCHED __builtin_amdgcn_sched_barrier(0)
; template <class Epi, class Sched>
; __device__ __forceinline__ void gemm_phase(LAS unsigned char* lds, const Gemm g, const Sched& S, const Epi& E, int wave_id) {
;     ...
;             PG8_LDA(At, 1, 1); PG8_STAGE(PG8_SB(1, 0), b3, voffB); PG8_STAGE(PG8_SB(1, 1), b3 + hstepB, voffB); PG8_STAGE(PG8_SA(1, 0), a3, voffA);
;             PG8_WAIT_V(8); PG8_WAIT_L(0); PG8_BAR; PG8_MMA(1, 0, At, B0); PG8_MMA(1, 1, At, B1); PG8_BAR; PG8_SCHED;
	s_add_i32 s48, s72, s35
	v_lshl_add_u64 v[222:223], v[222:223], 0, s[22:23]
	s_mov_b32 m0, s48
	ds_read_b128 v[184:187], v202 offset:49152
	ds_read_b128 v[188:191], v202 offset:50176
	ds_read_b128 v[192:195], v202 offset:51200
	ds_read_b128 v[196:199], v202 offset:52224
	ds_read_b128 v[206:209], v202 offset:53248
	ds_read_b128 v[210:213], v202 offset:54272
	ds_read_b128 v[214:217], v202 offset:55296
	ds_read_b128 v[218:221], v202 offset:56320
	global_load_lds_dwordx4 v[222:223], off
	s_add_i32 m0, s48, 0x2000
	s_add_u32 s46, s46, 0x40080
	v_lshl_add_u64 v[222:223], v[224:225], 0, s[22:23]
	s_addc_u32 s47, s47, 0
	s_add_i32 s48, s73, s35
	global_load_lds_dwordx4 v[222:223], off
	v_lshl_add_u64 v[222:223], s[46:47], 0, v[154:155]
	s_mov_b32 m0, s48
	s_nop 0
	global_load_lds_dwordx4 v[222:223], off
	v_lshl_add_u64 v[222:223], s[46:47], 0, v[158:159]
	s_add_i32 m0, s48, 0x2000
	s_nop 0
	global_load_lds_dwordx4 v[222:223], off
	v_lshl_add_u64 v[222:223], v[226:227], 0, s[22:23]
	s_mov_b32 m0, s55
	s_nop 0
	global_load_lds_dwordx4 v[222:223], off
	v_lshl_add_u64 v[222:223], v[228:229], 0, s[22:23]
	s_mov_b32 m0, s56
	s_nop 0
	global_load_lds_dwordx4 v[222:223], off
	s_waitcnt vmcnt(8)
	s_waitcnt lgkmcnt(0)
	s_barrier
	s_setprio 1
	s_waitcnt lgkmcnt(0)
	v_mfma_f32_16x16x32_bf16 v[76:79], v[24:27], v[184:187], v[76:79]
	v_mfma_f32_16x16x32_bf16 v[60:63], v[24:27], v[192:195], v[60:63]
	v_mfma_f32_16x16x32_bf16 v[44:47], v[24:27], v[206:209], v[44:47]
	v_mfma_f32_16x16x32_bf16 v[8:11], v[24:27], v[214:217], v[8:11]
	v_mfma_f32_16x16x32_bf16 v[76:79], v[28:31], v[188:191], v[76:79]
	v_mfma_f32_16x16x32_bf16 v[72:75], v[64:67], v[184:187], v[72:75]
	v_mfma_f32_16x16x32_bf16 v[60:63], v[28:31], v[196:199], v[60:63]
	v_mfma_f32_16x16x32_bf16 v[56:59], v[64:67], v[192:195], v[56:59]
	v_mfma_f32_16x16x32_bf16 v[44:47], v[28:31], v[210:213], v[44:47]
	v_mfma_f32_16x16x32_bf16 v[40:43], v[64:67], v[206:209], v[40:43]
	v_mfma_f32_16x16x32_bf16 v[28:31], v[28:31], v[218:221], v[8:11]
	v_mfma_f32_16x16x32_bf16 v[8:11], v[64:67], v[214:217], v[12:15]
	v_mfma_f32_16x16x32_bf16 v[72:75], v[68:71], v[188:191], v[72:75]
	v_mfma_f32_16x16x32_bf16 v[56:59], v[68:71], v[196:199], v[56:59]
	v_mfma_f32_16x16x32_bf16 v[40:43], v[68:71], v[210:213], v[40:43]
	v_mfma_f32_16x16x32_bf16 v[24:27], v[68:71], v[218:221], v[8:11]
	s_setprio 0
	s_setprio 1
	v_mfma_f32_16x16x32_bf16 v[8:11], v[144:147], v[184:187], v[16:19]
	v_mfma_f32_16x16x32_bf16 v[68:71], v[148:151], v[188:191], v[8:11]
	v_mfma_f32_16x16x32_bf16 v[8:11], v[176:179], v[184:187], v[20:23]
	v_mfma_f32_16x16x32_bf16 v[64:67], v[180:183], v[188:191], v[8:11]
	v_mfma_f32_16x16x32_bf16 v[8:11], v[144:147], v[192:195], v[52:55]
	v_mfma_f32_16x16x32_bf16 v[52:55], v[148:151], v[196:199], v[8:11]
	v_mfma_f32_16x16x32_bf16 v[8:11], v[176:179], v[192:195], v[48:51]
	v_mfma_f32_16x16x32_bf16 v[48:51], v[180:183], v[196:199], v[8:11]
	v_mfma_f32_16x16x32_bf16 v[8:11], v[144:147], v[206:209], v[36:39]
	v_mfma_f32_16x16x32_bf16 v[36:39], v[148:151], v[210:213], v[8:11]
	v_mfma_f32_16x16x32_bf16 v[8:11], v[176:179], v[206:209], v[32:35]
	v_mfma_f32_16x16x32_bf16 v[4:7], v[144:147], v[214:217], v[4:7]
	v_mfma_f32_16x16x32_bf16 v[0:3], v[176:179], v[214:217], v[0:3]
	v_mfma_f32_16x16x32_bf16 v[32:35], v[180:183], v[210:213], v[8:11]
	v_mfma_f32_16x16x32_bf16 v[4:7], v[148:151], v[218:221], v[4:7]
	v_mfma_f32_16x16x32_bf16 v[0:3], v[180:183], v[218:221], v[0:3]
	s_setprio 0
	s_barrier
	s_add_i32 s67, s67, 2
	s_add_u32 s12, s12, 0x100
	s_addc_u32 s13, s13, 0
	s_add_u32 s65, s65, 0x100
	s_addc_u32 s66, s66, 0
	s_cmp_gt_u32 s67, 13
